# GEMM epilogue stores plain instead of write-through sc1 (grid barrier wbl2 still publishes)
# speedup vs baseline: 1.0290x; 1.0100x over previous
; __device__ __forceinline__ float rstd_of(u64 s) { return rsqrtf((float)s * SS_INV + EPS); }
; __device__ __forceinline__ unsigned cvt_pk_bf16(float lo, float hi) { unsigned r; asm("v_cvt_pk_bf16_f32 %0, %1, %2" : "=v"(r) : "v"(lo), "v"(hi)); return r; }
; #define WT_STORE16(ptr, val) __builtin_amdgcn_raw_buffer_store_b128((val), wsr, (int)((const char*)(ptr) - (const char*)ws), 0, 16)
; template <int MODE>
; __device__ __forceinline__ void gemm_epilogue(const Params& p, int l, const f32x4 (&acc)[2][2][4][2], const Unit& u, int wr, int wc, int fr, int fq, const LAS float* rl, int pm0) {
;     ...
;                 for (int e = 0; e < 4; ++e) { s0[e] = (u.pm == pm0) ? rl[128 * bj + 32 * wc + 8 * fq + e] : rstd_of(ss[tok0 + e]); s1[e] = (u.pm == pm0) ? rl[128 * bj + 32 * wc + 8 * fq + 4 + e] : rstd_of(ss[tok0 + 4 + e]); }
; #pragma unroll
;                 for (int ai = 0; ai < 2; ++ai)
; #pragma unroll
;                     for (int m = 0; m < 4; ++m) {
;                         const int zr = 128 * ai + 64 * wr + 16 * m + fr;
;                         const f32x4 v0 = acc[ai][bj][m][0] * s0, v1 = acc[ai][bj][m][1] * s1;
;                         u32x4 w; w.x = cvt_pk_bf16(v0[0], v0[1]); w.y = cvt_pk_bf16(v0[2], v0[3]); w.z = cvt_pk_bf16(v1[0], v1[1]); w.w = cvt_pk_bf16(v1[2], v1[3]);
;                         WT_STORE16(ob + (size_t)zr * T + tok0, w);
;                     }
.LBB0_174:
	s_waitcnt lgkmcnt(0)
	v_pk_mul_f32 v[62:63], v[62:63], v[66:67]
	v_pk_mul_f32 v[76:77], v[60:61], v[72:73]
	v_pk_mul_f32 v[60:61], v[58:59], v[68:69]
	v_cvt_pk_bf16_f32 v58, v62, v63
	v_lshl_add_u32 v62, v130, 1, s2
	v_add_u32_e32 v62, 0x100, v62
	s_add_u32 s15, s58, s15
	v_pk_mul_f32 v[64:65], v[64:65], v[70:71]
	v_add_u32_e32 v63, v62, v154
	v_cvt_pk_bf16_f32 v59, v64, v65
	v_pk_mul_f32 v[54:55], v[54:55], v[66:67]
	s_addc_u32 s21, s59, 0
	v_cvt_pk_bf16_f32 v60, v60, v61
	v_cvt_pk_bf16_f32 v61, v76, v77
	buffer_store_dwordx4 v[58:61], v63, s[60:63], 0 offen
	v_pk_mul_f32 v[56:57], v[56:57], v[70:71]
	v_pk_mul_f32 v[46:47], v[46:47], v[66:67]
	v_pk_mul_f32 v[58:59], v[52:53], v[72:73]
	v_pk_mul_f32 v[52:53], v[50:51], v[68:69]
	v_cvt_pk_bf16_f32 v50, v54, v55
	v_cvt_pk_bf16_f32 v51, v56, v57
	v_add_u32_e32 v54, v62, v156
	s_add_u32 s20, s15, s22
	v_cvt_pk_bf16_f32 v52, v52, v53
	v_cvt_pk_bf16_f32 v53, v58, v59
	buffer_store_dwordx4 v[50:53], v54, s[60:63], 0 offen
	v_pk_mul_f32 v[48:49], v[48:49], v[70:71]
	v_pk_mul_f32 v[38:39], v[38:39], v[66:67]
	v_pk_mul_f32 v[50:51], v[44:45], v[72:73]
	v_pk_mul_f32 v[44:45], v[42:43], v[68:69]
	v_cvt_pk_bf16_f32 v42, v46, v47
	v_cvt_pk_bf16_f32 v43, v48, v49
	v_add_u32_e32 v46, v62, v158
	s_addc_u32 s21, s21, s17
	v_cvt_pk_bf16_f32 v44, v44, v45
	v_cvt_pk_bf16_f32 v45, v50, v51
	buffer_store_dwordx4 v[42:45], v46, s[60:63], 0 offen
	v_pk_mul_f32 v[40:41], v[40:41], v[70:71]
	v_pk_mul_f32 v[30:31], v[30:31], v[66:67]
	v_pk_mul_f32 v[42:43], v[36:37], v[72:73]
	v_pk_mul_f32 v[36:37], v[34:35], v[68:69]
	v_cvt_pk_bf16_f32 v34, v38, v39
	v_cvt_pk_bf16_f32 v35, v40, v41
	v_add_u32_e32 v38, v62, v160
	v_lshl_add_u64 v[74:75], v[130:131], 1, s[20:21]
	v_cvt_pk_bf16_f32 v36, v36, v37
	v_cvt_pk_bf16_f32 v37, v42, v43
	buffer_store_dwordx4 v[34:37], v38, s[60:63], 0 offen
	v_pk_mul_f32 v[32:33], v[32:33], v[70:71]
	v_pk_mul_f32 v[22:23], v[22:23], v[66:67]
	v_pk_mul_f32 v[34:35], v[28:29], v[72:73]
	v_pk_mul_f32 v[28:29], v[26:27], v[68:69]
	v_cvt_pk_bf16_f32 v26, v30, v31
	v_cvt_pk_bf16_f32 v27, v32, v33
	v_add_u32_e32 v30, v62, v162
	v_pk_mul_f32 v[2:3], v[2:3], v[68:69]
	v_cvt_pk_bf16_f32 v28, v28, v29
	v_cvt_pk_bf16_f32 v29, v34, v35
	buffer_store_dwordx4 v[26:29], v30, s[60:63], 0 offen
	v_pk_mul_f32 v[24:25], v[24:25], v[70:71]
	v_pk_mul_f32 v[14:15], v[14:15], v[66:67]
	v_pk_mul_f32 v[26:27], v[20:21], v[72:73]
	v_pk_mul_f32 v[20:21], v[18:19], v[68:69]
	v_cvt_pk_bf16_f32 v18, v22, v23
	v_cvt_pk_bf16_f32 v19, v24, v25
	v_add_u32_e32 v22, v62, v164
	v_cvt_pk_bf16_f32 v132, v2, v3
	v_lshl_add_u64 v[2:3], v[74:75], 0, v[168:169]
	v_cvt_pk_bf16_f32 v20, v20, v21
	v_cvt_pk_bf16_f32 v21, v26, v27
	buffer_store_dwordx4 v[18:21], v22, s[60:63], 0 offen
	v_lshl_add_u64 v[174:175], v[2:3], 0, s[44:45]
	v_pk_mul_f32 v[16:17], v[16:17], v[70:71]
	v_pk_mul_f32 v[18:19], v[12:13], v[72:73]
	v_pk_mul_f32 v[12:13], v[10:11], v[68:69]
	v_cvt_pk_bf16_f32 v10, v14, v15
	v_add_u32_e32 v14, v62, v166
	v_cvt_pk_bf16_f32 v11, v16, v17
	v_cvt_pk_bf16_f32 v12, v12, v13
	v_cvt_pk_bf16_f32 v13, v18, v19
	buffer_store_dwordx4 v[10:13], v14, s[60:63], 0 offen
	v_pk_mul_f32 v[8:9], v[8:9], v[70:71]
	v_pk_mul_f32 v[6:7], v[6:7], v[66:67]
	v_pk_mul_f32 v[4:5], v[4:5], v[72:73]
	v_cvt_pk_bf16_f32 v130, v6, v7
	v_cvt_pk_bf16_f32 v131, v8, v9
	s_nop 0
	v_cvt_pk_bf16_f32 v133, v4, v5
.LBB0_175:
	v_subrev_u32_e32 v2, s58, v174
	s_and_b64 vcc, exec, s[38:39]
	s_mov_b32 s96, s14
	s_mov_b32 s2, s16
	s_mov_b64 s[40:41], s[0:1]
	s_mov_b64 s[20:21], s[18:19]
	buffer_store_dwordx4 v[130:133], v2, s[60:63], 0 offen
	s_cbranch_vccnz .LBB0_301

; __device__ __forceinline__ float rstd_of(u64 s) { return rsqrtf((float)s * SS_INV + EPS); }
; __device__ __forceinline__ unsigned cvt_pk_bf16(float lo, float hi) { unsigned r; asm("v_cvt_pk_bf16_f32 %0, %1, %2" : "=v"(r) : "v"(lo), "v"(hi)); return r; }
; #define WT_STORE16(ptr, val) __builtin_amdgcn_raw_buffer_store_b128((val), wsr, (int)((const char*)(ptr) - (const char*)ws), 0, 16)
; template <int MODE>
; __device__ __forceinline__ void gemm_epilogue(const Params& p, int l, const f32x4 (&acc)[2][2][4][2], const Unit& u, int wr, int wc, int fr, int fq, const LAS float* rl, int pm0) {
;     ...
; #pragma unroll
;             for (int ai = 0; ai < 2; ++ai)
; #pragma unroll
;                 for (int m = 0; m < 4; ++m) {
;                     const int tok = u.pm * 256 + 128 * ai + 64 * wr + 16 * m + fr;
;                     const float rs = (u.pm == pm0) ? rl[128 * ai + 64 * wr + 16 * m + fr] : rstd_of(ss[tok]);
; #pragma unroll
;                     for (int bj = 0; bj < 2; ++bj) {
;                         const f32x4 v0 = acc[ai][bj][m][0] * rs, v1 = acc[ai][bj][m][1] * rs;
;                         u32x4 w; w.x = cvt_pk_bf16(v0[0], v0[1]); w.y = cvt_pk_bf16(v0[2], v0[3]); w.z = cvt_pk_bf16(v1[0], v1[1]); w.w = cvt_pk_bf16(v1[2], v1[3]);
;                         WT_STORE16(ob + (size_t)tok * ld + 128 * bj + 32 * wc + 8 * fq, w);
;                     }
;                 }
.LBB0_208:
	s_add_u32 s20, s20, s11
	s_addc_u32 s21, s21, 0
	v_lshl_add_u64 v[132:133], s[20:21], 0, v[0:1]
	v_mul_lo_u32 v142, v130, s78
	v_lshl_add_u32 v142, v142, 1, v132
	s_waitcnt lgkmcnt(0)
	v_pk_mul_f32 v[176:177], v[126:127], v[174:175] op_sel_hi:[1,0]
	v_pk_mul_f32 v[178:179], v[128:129], v[174:175] op_sel_hi:[1,0]
	v_cvt_pk_bf16_f32 v176, v176, v177
	v_subrev_u32_e32 v142, s58, v142
	v_cvt_pk_bf16_f32 v177, v178, v179
	v_pk_mul_f32 v[184:185], v[124:125], v[174:175] op_sel_hi:[1,0]
	v_pk_mul_f32 v[186:187], v[122:123], v[174:175] op_sel_hi:[1,0]
	v_cvt_pk_bf16_f32 v179, v184, v185
	v_pk_mul_f32 v[184:185], v[60:61], v[174:175] op_sel_hi:[1,0]
	v_cvt_pk_bf16_f32 v178, v186, v187
	buffer_store_dwordx4 v[176:179], v142, s[60:63], 0 offen
	v_pk_mul_f32 v[186:187], v[58:59], v[174:175] op_sel_hi:[1,0]
	s_andn2_b64 vcc, exec, s[22:23]
	v_pk_mul_f32 v[176:177], v[64:65], v[174:175] op_sel_hi:[1,0]
	v_pk_mul_f32 v[178:179], v[62:63], v[174:175] op_sel_hi:[1,0]
	v_cvt_pk_bf16_f32 v175, v176, v177
	v_cvt_pk_bf16_f32 v176, v186, v187
	v_cvt_pk_bf16_f32 v177, v184, v185
	s_mov_b64 s[20:21], -1
	v_cvt_pk_bf16_f32 v174, v178, v179
	buffer_store_dwordx4 v[174:177], v142, s[60:63], 0 offen offset:256
	v_cndmask_b32_e64 v142, 0, 1, s[22:23]
	v_cmp_ne_u32_e64 s[40:41], 1, v142
	v_or_b32_e32 v176, 16, v130
	s_cbranch_vccnz .LBB0_210
	v_lshl_add_u64 v[174:175], v[130:131], 3, s[12:13]
	global_load_dwordx2 v[174:175], v[174:175], off offset:128
	s_mov_b64 s[20:21], 0
	s_waitcnt vmcnt(0)
	v_ffbh_u32_e32 v142, v175
	v_min_u32_e32 v142, 32, v142
	v_lshlrev_b64 v[174:175], v142, v[174:175]
	v_min_u32_e32 v143, 1, v174
	v_or_b32_e32 v143, v175, v143
	v_cvt_f32_u32_e32 v143, v143
	v_sub_u32_e32 v142, 32, v142
	v_ldexp_f32 v142, v143, v142
	v_fmamk_f32 v142, v142, 0x30000000, v203
	v_mul_f32_e32 v143, 0x4b800000, v142
	v_cmp_gt_f32_e32 vcc, s89, v142
	s_nop 1
	v_cndmask_b32_e32 v142, v142, v143, vcc
	v_rsq_f32_e32 v142, v142
	s_nop 0
	v_mul_f32_e32 v143, 0x45800000, v142
	v_cndmask_b32_e32 v174, v142, v143, vcc

; __device__ __forceinline__ float rstd_of(u64 s) { return rsqrtf((float)s * SS_INV + EPS); }
; __device__ __forceinline__ unsigned cvt_pk_bf16(float lo, float hi) { unsigned r; asm("v_cvt_pk_bf16_f32 %0, %1, %2" : "=v"(r) : "v"(lo), "v"(hi)); return r; }
; #define WT_STORE16(ptr, val) __builtin_amdgcn_raw_buffer_store_b128((val), wsr, (int)((const char*)(ptr) - (const char*)ws), 0, 16)
; template <int MODE>
; __device__ __forceinline__ void gemm_epilogue(const Params& p, int l, const f32x4 (&acc)[2][2][4][2], const Unit& u, int wr, int wc, int fr, int fq, const LAS float* rl, int pm0) {
;     ...
; #pragma unroll
;             for (int ai = 0; ai < 2; ++ai)
; #pragma unroll
;                 for (int m = 0; m < 4; ++m) {
;                     const int tok = u.pm * 256 + 128 * ai + 64 * wr + 16 * m + fr;
;                     const float rs = (u.pm == pm0) ? rl[128 * ai + 64 * wr + 16 * m + fr] : rstd_of(ss[tok]);
; #pragma unroll
;                     for (int bj = 0; bj < 2; ++bj) {
;                         const f32x4 v0 = acc[ai][bj][m][0] * rs, v1 = acc[ai][bj][m][1] * rs;
;                         u32x4 w; w.x = cvt_pk_bf16(v0[0], v0[1]); w.y = cvt_pk_bf16(v0[2], v0[3]); w.z = cvt_pk_bf16(v1[0], v1[1]); w.w = cvt_pk_bf16(v1[2], v1[3]);
;                         WT_STORE16(ob + (size_t)tok * ld + 128 * bj + 32 * wc + 8 * fq, w);
;                     }
;                 }
.LBB0_212:
	v_mul_lo_u32 v142, v176, s78
	v_lshl_add_u32 v142, v142, 1, v132
	s_waitcnt lgkmcnt(0)
	v_pk_mul_f32 v[176:177], v[118:119], v[174:175] op_sel_hi:[1,0]
	v_pk_mul_f32 v[178:179], v[120:121], v[174:175] op_sel_hi:[1,0]
	v_cvt_pk_bf16_f32 v176, v176, v177
	v_subrev_u32_e32 v142, s58, v142
	v_cvt_pk_bf16_f32 v177, v178, v179
	v_pk_mul_f32 v[184:185], v[116:117], v[174:175] op_sel_hi:[1,0]
	v_pk_mul_f32 v[186:187], v[114:115], v[174:175] op_sel_hi:[1,0]
	v_cvt_pk_bf16_f32 v179, v184, v185
	v_pk_mul_f32 v[184:185], v[52:53], v[174:175] op_sel_hi:[1,0]
	v_cvt_pk_bf16_f32 v178, v186, v187
	buffer_store_dwordx4 v[176:179], v142, s[60:63], 0 offen
	v_pk_mul_f32 v[186:187], v[50:51], v[174:175] op_sel_hi:[1,0]
	s_and_b64 vcc, exec, s[40:41]
	v_pk_mul_f32 v[176:177], v[56:57], v[174:175] op_sel_hi:[1,0]
	v_pk_mul_f32 v[178:179], v[54:55], v[174:175] op_sel_hi:[1,0]
	v_cvt_pk_bf16_f32 v175, v176, v177
	v_cvt_pk_bf16_f32 v176, v186, v187
	v_cvt_pk_bf16_f32 v177, v184, v185
	s_mov_b64 s[20:21], -1
	v_cvt_pk_bf16_f32 v174, v178, v179
	buffer_store_dwordx4 v[174:177], v142, s[60:63], 0 offen offset:256
	s_nop 1
	v_or_b32_e32 v176, 32, v130
	s_cbranch_vccnz .LBB0_214
	v_lshl_add_u64 v[174:175], v[130:131], 3, s[12:13]
	global_load_dwordx2 v[174:175], v[174:175], off offset:256
	s_mov_b64 s[20:21], 0
	s_waitcnt vmcnt(0)
	v_ffbh_u32_e32 v142, v175
	v_min_u32_e32 v142, 32, v142
	v_lshlrev_b64 v[174:175], v142, v[174:175]
	v_min_u32_e32 v143, 1, v174
	v_or_b32_e32 v143, v175, v143
	v_cvt_f32_u32_e32 v143, v143
	v_sub_u32_e32 v142, 32, v142
	v_ldexp_f32 v142, v143, v142
	v_fmamk_f32 v142, v142, 0x30000000, v203
	v_mul_f32_e32 v143, 0x4b800000, v142
	v_cmp_gt_f32_e32 vcc, s89, v142
	s_nop 1
	v_cndmask_b32_e32 v142, v142, v143, vcc
	v_rsq_f32_e32 v142, v142
	s_nop 0
	v_mul_f32_e32 v143, 0x45800000, v142
	v_cndmask_b32_e32 v174, v142, v143, vcc

; __device__ __forceinline__ float rstd_of(u64 s) { return rsqrtf((float)s * SS_INV + EPS); }
; __device__ __forceinline__ unsigned cvt_pk_bf16(float lo, float hi) { unsigned r; asm("v_cvt_pk_bf16_f32 %0, %1, %2" : "=v"(r) : "v"(lo), "v"(hi)); return r; }
; #define WT_STORE16(ptr, val) __builtin_amdgcn_raw_buffer_store_b128((val), wsr, (int)((const char*)(ptr) - (const char*)ws), 0, 16)
; template <int MODE>
; __device__ __forceinline__ void gemm_epilogue(const Params& p, int l, const f32x4 (&acc)[2][2][4][2], const Unit& u, int wr, int wc, int fr, int fq, const LAS float* rl, int pm0) {
;     ...
; #pragma unroll
;             for (int ai = 0; ai < 2; ++ai)
; #pragma unroll
;                 for (int m = 0; m < 4; ++m) {
;                     const int tok = u.pm * 256 + 128 * ai + 64 * wr + 16 * m + fr;
;                     const float rs = (u.pm == pm0) ? rl[128 * ai + 64 * wr + 16 * m + fr] : rstd_of(ss[tok]);
; #pragma unroll
;                     for (int bj = 0; bj < 2; ++bj) {
;                         const f32x4 v0 = acc[ai][bj][m][0] * rs, v1 = acc[ai][bj][m][1] * rs;
;                         u32x4 w; w.x = cvt_pk_bf16(v0[0], v0[1]); w.y = cvt_pk_bf16(v0[2], v0[3]); w.z = cvt_pk_bf16(v1[0], v1[1]); w.w = cvt_pk_bf16(v1[2], v1[3]);
;                         WT_STORE16(ob + (size_t)tok * ld + 128 * bj + 32 * wc + 8 * fq, w);
;                     }
;                 }
.LBB0_216:
	v_mul_lo_u32 v142, v176, s78
	v_lshl_add_u32 v142, v142, 1, v132
	s_waitcnt lgkmcnt(0)
	v_pk_mul_f32 v[176:177], v[110:111], v[174:175] op_sel_hi:[1,0]
	v_pk_mul_f32 v[178:179], v[112:113], v[174:175] op_sel_hi:[1,0]
	v_cvt_pk_bf16_f32 v176, v176, v177
	v_subrev_u32_e32 v142, s58, v142
	v_cvt_pk_bf16_f32 v177, v178, v179
	v_pk_mul_f32 v[184:185], v[108:109], v[174:175] op_sel_hi:[1,0]
	v_pk_mul_f32 v[186:187], v[106:107], v[174:175] op_sel_hi:[1,0]
	v_cvt_pk_bf16_f32 v179, v184, v185
	v_pk_mul_f32 v[184:185], v[44:45], v[174:175] op_sel_hi:[1,0]
	v_cvt_pk_bf16_f32 v178, v186, v187
	buffer_store_dwordx4 v[176:179], v142, s[60:63], 0 offen
	v_pk_mul_f32 v[186:187], v[42:43], v[174:175] op_sel_hi:[1,0]
	s_and_b64 vcc, exec, s[40:41]
	v_pk_mul_f32 v[176:177], v[48:49], v[174:175] op_sel_hi:[1,0]
	v_pk_mul_f32 v[178:179], v[46:47], v[174:175] op_sel_hi:[1,0]
	v_cvt_pk_bf16_f32 v175, v176, v177
	v_cvt_pk_bf16_f32 v176, v186, v187
	v_cvt_pk_bf16_f32 v177, v184, v185
	s_mov_b64 s[20:21], -1
	v_cvt_pk_bf16_f32 v174, v178, v179
	buffer_store_dwordx4 v[174:177], v142, s[60:63], 0 offen offset:256
	s_nop 1
	v_or_b32_e32 v176, 48, v130
	s_cbranch_vccnz .LBB0_218
	v_lshl_add_u64 v[174:175], v[130:131], 3, s[12:13]
	global_load_dwordx2 v[174:175], v[174:175], off offset:384
	s_mov_b64 s[20:21], 0
	s_waitcnt vmcnt(0)
	v_ffbh_u32_e32 v142, v175
	v_min_u32_e32 v142, 32, v142
	v_lshlrev_b64 v[174:175], v142, v[174:175]
	v_min_u32_e32 v143, 1, v174
	v_or_b32_e32 v143, v175, v143
	v_cvt_f32_u32_e32 v143, v143
	v_sub_u32_e32 v142, 32, v142
	v_ldexp_f32 v142, v143, v142
	v_fmamk_f32 v142, v142, 0x30000000, v203
	v_mul_f32_e32 v143, 0x4b800000, v142
	v_cmp_gt_f32_e32 vcc, s89, v142
	s_nop 1
	v_cndmask_b32_e32 v142, v142, v143, vcc
	v_rsq_f32_e32 v142, v142
	s_nop 0
	v_mul_f32_e32 v143, 0x45800000, v142
	v_cndmask_b32_e32 v174, v142, v143, vcc

; __device__ __forceinline__ float rstd_of(u64 s) { return rsqrtf((float)s * SS_INV + EPS); }
; __device__ __forceinline__ unsigned cvt_pk_bf16(float lo, float hi) { unsigned r; asm("v_cvt_pk_bf16_f32 %0, %1, %2" : "=v"(r) : "v"(lo), "v"(hi)); return r; }
; #define WT_STORE16(ptr, val) __builtin_amdgcn_raw_buffer_store_b128((val), wsr, (int)((const char*)(ptr) - (const char*)ws), 0, 16)
; template <int MODE>
; __device__ __forceinline__ void gemm_epilogue(const Params& p, int l, const f32x4 (&acc)[2][2][4][2], const Unit& u, int wr, int wc, int fr, int fq, const LAS float* rl, int pm0) {
;     ...
; #pragma unroll
;             for (int ai = 0; ai < 2; ++ai)
; #pragma unroll
;                 for (int m = 0; m < 4; ++m) {
;                     const int tok = u.pm * 256 + 128 * ai + 64 * wr + 16 * m + fr;
;                     const float rs = (u.pm == pm0) ? rl[128 * ai + 64 * wr + 16 * m + fr] : rstd_of(ss[tok]);
; #pragma unroll
;                     for (int bj = 0; bj < 2; ++bj) {
;                         const f32x4 v0 = acc[ai][bj][m][0] * rs, v1 = acc[ai][bj][m][1] * rs;
;                         u32x4 w; w.x = cvt_pk_bf16(v0[0], v0[1]); w.y = cvt_pk_bf16(v0[2], v0[3]); w.z = cvt_pk_bf16(v1[0], v1[1]); w.w = cvt_pk_bf16(v1[2], v1[3]);
;                         WT_STORE16(ob + (size_t)tok * ld + 128 * bj + 32 * wc + 8 * fq, w);
;                     }
;                 }
.LBB0_220:
	v_mul_lo_u32 v142, v176, s78
	v_lshl_add_u32 v142, v142, 1, v132
	s_waitcnt lgkmcnt(0)
	v_pk_mul_f32 v[176:177], v[102:103], v[174:175] op_sel_hi:[1,0]
	v_pk_mul_f32 v[178:179], v[104:105], v[174:175] op_sel_hi:[1,0]
	v_cvt_pk_bf16_f32 v176, v176, v177
	v_subrev_u32_e32 v142, s58, v142
	v_cvt_pk_bf16_f32 v177, v178, v179
	v_pk_mul_f32 v[184:185], v[100:101], v[174:175] op_sel_hi:[1,0]
	v_pk_mul_f32 v[186:187], v[98:99], v[174:175] op_sel_hi:[1,0]
	v_cvt_pk_bf16_f32 v179, v184, v185
	v_pk_mul_f32 v[184:185], v[36:37], v[174:175] op_sel_hi:[1,0]
	v_cvt_pk_bf16_f32 v178, v186, v187
	buffer_store_dwordx4 v[176:179], v142, s[60:63], 0 offen
	v_pk_mul_f32 v[186:187], v[34:35], v[174:175] op_sel_hi:[1,0]
	s_and_b64 vcc, exec, s[40:41]
	v_pk_mul_f32 v[176:177], v[40:41], v[174:175] op_sel_hi:[1,0]
	v_pk_mul_f32 v[178:179], v[38:39], v[174:175] op_sel_hi:[1,0]
	v_cvt_pk_bf16_f32 v175, v176, v177
	v_cvt_pk_bf16_f32 v176, v186, v187
	v_cvt_pk_bf16_f32 v177, v184, v185
	s_mov_b64 s[20:21], -1
	v_cvt_pk_bf16_f32 v174, v178, v179
	buffer_store_dwordx4 v[174:177], v142, s[60:63], 0 offen offset:256
	s_nop 1
	v_add_u32_e32 v176, 0x80, v130
	s_cbranch_vccnz .LBB0_222
	v_lshl_add_u64 v[174:175], v[130:131], 3, s[12:13]
	global_load_dwordx2 v[174:175], v[174:175], off offset:1024
	s_mov_b64 s[20:21], 0
	s_waitcnt vmcnt(0)
	v_ffbh_u32_e32 v142, v175
	v_min_u32_e32 v142, 32, v142
	v_lshlrev_b64 v[174:175], v142, v[174:175]
	v_min_u32_e32 v143, 1, v174
	v_or_b32_e32 v143, v175, v143
	v_cvt_f32_u32_e32 v143, v143
	v_sub_u32_e32 v142, 32, v142
	v_ldexp_f32 v142, v143, v142
	v_fmamk_f32 v142, v142, 0x30000000, v203
	v_mul_f32_e32 v143, 0x4b800000, v142
	v_cmp_gt_f32_e32 vcc, s89, v142
	s_nop 1
	v_cndmask_b32_e32 v142, v142, v143, vcc
	v_rsq_f32_e32 v142, v142
	s_nop 0
	v_mul_f32_e32 v143, 0x45800000, v142
	v_cndmask_b32_e32 v174, v142, v143, vcc

; __device__ __forceinline__ float rstd_of(u64 s) { return rsqrtf((float)s * SS_INV + EPS); }
; __device__ __forceinline__ unsigned cvt_pk_bf16(float lo, float hi) { unsigned r; asm("v_cvt_pk_bf16_f32 %0, %1, %2" : "=v"(r) : "v"(lo), "v"(hi)); return r; }
; #define WT_STORE16(ptr, val) __builtin_amdgcn_raw_buffer_store_b128((val), wsr, (int)((const char*)(ptr) - (const char*)ws), 0, 16)
; template <int MODE>
; __device__ __forceinline__ void gemm_epilogue(const Params& p, int l, const f32x4 (&acc)[2][2][4][2], const Unit& u, int wr, int wc, int fr, int fq, const LAS float* rl, int pm0) {
;     ...
; #pragma unroll
;             for (int ai = 0; ai < 2; ++ai)
; #pragma unroll
;                 for (int m = 0; m < 4; ++m) {
;                     const int tok = u.pm * 256 + 128 * ai + 64 * wr + 16 * m + fr;
;                     const float rs = (u.pm == pm0) ? rl[128 * ai + 64 * wr + 16 * m + fr] : rstd_of(ss[tok]);
; #pragma unroll
;                     for (int bj = 0; bj < 2; ++bj) {
;                         const f32x4 v0 = acc[ai][bj][m][0] * rs, v1 = acc[ai][bj][m][1] * rs;
;                         u32x4 w; w.x = cvt_pk_bf16(v0[0], v0[1]); w.y = cvt_pk_bf16(v0[2], v0[3]); w.z = cvt_pk_bf16(v1[0], v1[1]); w.w = cvt_pk_bf16(v1[2], v1[3]);
;                         WT_STORE16(ob + (size_t)tok * ld + 128 * bj + 32 * wc + 8 * fq, w);
;                     }
;                 }
.LBB0_224:
	v_mul_lo_u32 v142, v176, s78
	v_lshl_add_u32 v142, v142, 1, v132
	s_waitcnt lgkmcnt(0)
	v_pk_mul_f32 v[176:177], v[94:95], v[174:175] op_sel_hi:[1,0]
	v_pk_mul_f32 v[178:179], v[96:97], v[174:175] op_sel_hi:[1,0]
	v_cvt_pk_bf16_f32 v176, v176, v177
	v_subrev_u32_e32 v142, s58, v142
	v_cvt_pk_bf16_f32 v177, v178, v179
	v_pk_mul_f32 v[184:185], v[92:93], v[174:175] op_sel_hi:[1,0]
	v_pk_mul_f32 v[186:187], v[90:91], v[174:175] op_sel_hi:[1,0]
	v_cvt_pk_bf16_f32 v179, v184, v185
	v_pk_mul_f32 v[184:185], v[28:29], v[174:175] op_sel_hi:[1,0]
	v_cvt_pk_bf16_f32 v178, v186, v187
	buffer_store_dwordx4 v[176:179], v142, s[60:63], 0 offen
	v_pk_mul_f32 v[186:187], v[26:27], v[174:175] op_sel_hi:[1,0]
	s_and_b64 vcc, exec, s[40:41]
	v_pk_mul_f32 v[176:177], v[32:33], v[174:175] op_sel_hi:[1,0]
	v_pk_mul_f32 v[178:179], v[30:31], v[174:175] op_sel_hi:[1,0]
	v_cvt_pk_bf16_f32 v175, v176, v177
	v_cvt_pk_bf16_f32 v176, v186, v187
	v_cvt_pk_bf16_f32 v177, v184, v185
	s_mov_b64 s[20:21], -1
	v_cvt_pk_bf16_f32 v174, v178, v179
	buffer_store_dwordx4 v[174:177], v142, s[60:63], 0 offen offset:256
	s_nop 1
	v_add_u32_e32 v176, 0x90, v130
	s_cbranch_vccnz .LBB0_226
	v_lshl_add_u64 v[174:175], v[130:131], 3, s[12:13]
	global_load_dwordx2 v[174:175], v[174:175], off offset:1152
	s_mov_b64 s[20:21], 0
	s_waitcnt vmcnt(0)
	v_ffbh_u32_e32 v142, v175
	v_min_u32_e32 v142, 32, v142
	v_lshlrev_b64 v[174:175], v142, v[174:175]
	v_min_u32_e32 v143, 1, v174
	v_or_b32_e32 v143, v175, v143
	v_cvt_f32_u32_e32 v143, v143
	v_sub_u32_e32 v142, 32, v142
	v_ldexp_f32 v142, v143, v142
	v_fmamk_f32 v142, v142, 0x30000000, v203
	v_mul_f32_e32 v143, 0x4b800000, v142
	v_cmp_gt_f32_e32 vcc, s89, v142
	s_nop 1
	v_cndmask_b32_e32 v142, v142, v143, vcc
	v_rsq_f32_e32 v142, v142
	s_nop 0
	v_mul_f32_e32 v143, 0x45800000, v142
	v_cndmask_b32_e32 v174, v142, v143, vcc

; __device__ __forceinline__ float rstd_of(u64 s) { return rsqrtf((float)s * SS_INV + EPS); }
; __device__ __forceinline__ unsigned cvt_pk_bf16(float lo, float hi) { unsigned r; asm("v_cvt_pk_bf16_f32 %0, %1, %2" : "=v"(r) : "v"(lo), "v"(hi)); return r; }
; #define WT_STORE16(ptr, val) __builtin_amdgcn_raw_buffer_store_b128((val), wsr, (int)((const char*)(ptr) - (const char*)ws), 0, 16)
; template <int MODE>
; __device__ __forceinline__ void gemm_epilogue(const Params& p, int l, const f32x4 (&acc)[2][2][4][2], const Unit& u, int wr, int wc, int fr, int fq, const LAS float* rl, int pm0) {
;     ...
; #pragma unroll
;             for (int ai = 0; ai < 2; ++ai)
; #pragma unroll
;                 for (int m = 0; m < 4; ++m) {
;                     const int tok = u.pm * 256 + 128 * ai + 64 * wr + 16 * m + fr;
;                     const float rs = (u.pm == pm0) ? rl[128 * ai + 64 * wr + 16 * m + fr] : rstd_of(ss[tok]);
; #pragma unroll
;                     for (int bj = 0; bj < 2; ++bj) {
;                         const f32x4 v0 = acc[ai][bj][m][0] * rs, v1 = acc[ai][bj][m][1] * rs;
;                         u32x4 w; w.x = cvt_pk_bf16(v0[0], v0[1]); w.y = cvt_pk_bf16(v0[2], v0[3]); w.z = cvt_pk_bf16(v1[0], v1[1]); w.w = cvt_pk_bf16(v1[2], v1[3]);
;                         WT_STORE16(ob + (size_t)tok * ld + 128 * bj + 32 * wc + 8 * fq, w);
;                     }
;                 }
.LBB0_228:
	v_mul_lo_u32 v142, v176, s78
	v_lshl_add_u32 v142, v142, 1, v132
	s_waitcnt lgkmcnt(0)
	v_pk_mul_f32 v[176:177], v[86:87], v[174:175] op_sel_hi:[1,0]
	v_pk_mul_f32 v[178:179], v[88:89], v[174:175] op_sel_hi:[1,0]
	v_cvt_pk_bf16_f32 v176, v176, v177
	v_subrev_u32_e32 v142, s58, v142
	v_cvt_pk_bf16_f32 v177, v178, v179
	v_pk_mul_f32 v[184:185], v[84:85], v[174:175] op_sel_hi:[1,0]
	v_pk_mul_f32 v[186:187], v[82:83], v[174:175] op_sel_hi:[1,0]
	v_cvt_pk_bf16_f32 v179, v184, v185
	v_pk_mul_f32 v[184:185], v[20:21], v[174:175] op_sel_hi:[1,0]
	v_cvt_pk_bf16_f32 v178, v186, v187
	buffer_store_dwordx4 v[176:179], v142, s[60:63], 0 offen
	v_pk_mul_f32 v[186:187], v[18:19], v[174:175] op_sel_hi:[1,0]
	s_and_b64 vcc, exec, s[40:41]
	v_pk_mul_f32 v[176:177], v[24:25], v[174:175] op_sel_hi:[1,0]
	v_pk_mul_f32 v[178:179], v[22:23], v[174:175] op_sel_hi:[1,0]
	v_cvt_pk_bf16_f32 v175, v176, v177
	v_cvt_pk_bf16_f32 v176, v186, v187
	v_cvt_pk_bf16_f32 v177, v184, v185
	s_mov_b64 s[20:21], -1
	v_cvt_pk_bf16_f32 v174, v178, v179
	buffer_store_dwordx4 v[174:177], v142, s[60:63], 0 offen offset:256
	s_nop 1
	v_add_u32_e32 v176, 0xa0, v130
	s_cbranch_vccnz .LBB0_230
	v_lshl_add_u64 v[174:175], v[130:131], 3, s[12:13]
	global_load_dwordx2 v[174:175], v[174:175], off offset:1280
	s_mov_b64 s[20:21], 0
	s_waitcnt vmcnt(0)
	v_ffbh_u32_e32 v142, v175
	v_min_u32_e32 v142, 32, v142
	v_lshlrev_b64 v[174:175], v142, v[174:175]
	v_min_u32_e32 v143, 1, v174
	v_or_b32_e32 v143, v175, v143
	v_cvt_f32_u32_e32 v143, v143
	v_sub_u32_e32 v142, 32, v142
	v_ldexp_f32 v142, v143, v142
	v_fmamk_f32 v142, v142, 0x30000000, v203
	v_mul_f32_e32 v143, 0x4b800000, v142
	v_cmp_gt_f32_e32 vcc, s89, v142
	s_nop 1
	v_cndmask_b32_e32 v142, v142, v143, vcc
	v_rsq_f32_e32 v142, v142
	s_nop 0
	v_mul_f32_e32 v143, 0x45800000, v142
	v_cndmask_b32_e32 v174, v142, v143, vcc

; __device__ __forceinline__ float rstd_of(u64 s) { return rsqrtf((float)s * SS_INV + EPS); }
; __device__ __forceinline__ unsigned cvt_pk_bf16(float lo, float hi) { unsigned r; asm("v_cvt_pk_bf16_f32 %0, %1, %2" : "=v"(r) : "v"(lo), "v"(hi)); return r; }
; #define WT_STORE16(ptr, val) __builtin_amdgcn_raw_buffer_store_b128((val), wsr, (int)((const char*)(ptr) - (const char*)ws), 0, 16)
; template <int MODE>
; __device__ __forceinline__ void gemm_epilogue(const Params& p, int l, const f32x4 (&acc)[2][2][4][2], const Unit& u, int wr, int wc, int fr, int fq, const LAS float* rl, int pm0) {
;     ...
; #pragma unroll
;             for (int ai = 0; ai < 2; ++ai)
; #pragma unroll
;                 for (int m = 0; m < 4; ++m) {
;                     const int tok = u.pm * 256 + 128 * ai + 64 * wr + 16 * m + fr;
;                     const float rs = (u.pm == pm0) ? rl[128 * ai + 64 * wr + 16 * m + fr] : rstd_of(ss[tok]);
; #pragma unroll
;                     for (int bj = 0; bj < 2; ++bj) {
;                         const f32x4 v0 = acc[ai][bj][m][0] * rs, v1 = acc[ai][bj][m][1] * rs;
;                         u32x4 w; w.x = cvt_pk_bf16(v0[0], v0[1]); w.y = cvt_pk_bf16(v0[2], v0[3]); w.z = cvt_pk_bf16(v1[0], v1[1]); w.w = cvt_pk_bf16(v1[2], v1[3]);
;                         WT_STORE16(ob + (size_t)tok * ld + 128 * bj + 32 * wc + 8 * fq, w);
;                     }
;                 }
.LBB0_232:
	v_mul_lo_u32 v142, v176, s78
	v_lshl_add_u32 v142, v142, 1, v132
	s_waitcnt lgkmcnt(0)
	v_pk_mul_f32 v[176:177], v[78:79], v[174:175] op_sel_hi:[1,0]
	v_pk_mul_f32 v[178:179], v[80:81], v[174:175] op_sel_hi:[1,0]
	v_cvt_pk_bf16_f32 v176, v176, v177
	v_subrev_u32_e32 v142, s58, v142
	v_cvt_pk_bf16_f32 v177, v178, v179
	v_pk_mul_f32 v[184:185], v[76:77], v[174:175] op_sel_hi:[1,0]
	v_pk_mul_f32 v[186:187], v[74:75], v[174:175] op_sel_hi:[1,0]
	v_cvt_pk_bf16_f32 v179, v184, v185
	v_pk_mul_f32 v[184:185], v[12:13], v[174:175] op_sel_hi:[1,0]
	v_cvt_pk_bf16_f32 v178, v186, v187
	buffer_store_dwordx4 v[176:179], v142, s[60:63], 0 offen
	v_pk_mul_f32 v[186:187], v[10:11], v[174:175] op_sel_hi:[1,0]
	s_mov_b64 s[20:21], -1
	v_pk_mul_f32 v[176:177], v[16:17], v[174:175] op_sel_hi:[1,0]
	v_pk_mul_f32 v[178:179], v[14:15], v[174:175] op_sel_hi:[1,0]
	v_cvt_pk_bf16_f32 v175, v176, v177
	v_cvt_pk_bf16_f32 v176, v186, v187
	v_cvt_pk_bf16_f32 v177, v184, v185
	s_and_b64 vcc, exec, s[40:41]
	v_cvt_pk_bf16_f32 v174, v178, v179
	buffer_store_dwordx4 v[174:177], v142, s[60:63], 0 offen offset:256
	s_nop 1
	v_add_u32_e32 v176, 0xb0, v130
	v_ashrrev_i32_e32 v155, 31, v176
	s_cbranch_vccnz .LBB0_234
	v_lshl_add_u64 v[130:131], v[130:131], 3, s[12:13]
	global_load_dwordx2 v[130:131], v[130:131], off offset:1408
	s_mov_b64 s[20:21], 0
	s_waitcnt vmcnt(0)
	v_ffbh_u32_e32 v142, v131
	v_min_u32_e32 v142, 32, v142
	v_lshlrev_b64 v[130:131], v142, v[130:131]
	v_min_u32_e32 v130, 1, v130
	v_or_b32_e32 v130, v131, v130
	v_cvt_f32_u32_e32 v130, v130
	v_sub_u32_e32 v131, 32, v142
	v_ldexp_f32 v130, v130, v131
	v_fmamk_f32 v130, v130, 0x30000000, v203
	v_mul_f32_e32 v131, 0x4b800000, v130
	v_cmp_gt_f32_e32 vcc, s89, v130
	s_nop 1
	v_cndmask_b32_e32 v130, v130, v131, vcc
	v_rsq_f32_e32 v130, v130
	s_nop 0
	v_mul_f32_e32 v131, 0x45800000, v130
	v_cndmask_b32_e32 v174, v130, v131, vcc

; __device__ __forceinline__ float rstd_of(u64 s) { return rsqrtf((float)s * SS_INV + EPS); }
; __device__ __forceinline__ unsigned cvt_pk_bf16(float lo, float hi) { unsigned r; asm("v_cvt_pk_bf16_f32 %0, %1, %2" : "=v"(r) : "v"(lo), "v"(hi)); return r; }
; #define WT_STORE16(ptr, val) __builtin_amdgcn_raw_buffer_store_b128((val), wsr, (int)((const char*)(ptr) - (const char*)ws), 0, 16)
; template <int MODE>
; __device__ __forceinline__ void gemm_epilogue(const Params& p, int l, const f32x4 (&acc)[2][2][4][2], const Unit& u, int wr, int wc, int fr, int fq, const LAS float* rl, int pm0) {
;     ...
; #pragma unroll
;             for (int ai = 0; ai < 2; ++ai)
; #pragma unroll
;                 for (int m = 0; m < 4; ++m) {
;                     const int tok = u.pm * 256 + 128 * ai + 64 * wr + 16 * m + fr;
;                     const float rs = (u.pm == pm0) ? rl[128 * ai + 64 * wr + 16 * m + fr] : rstd_of(ss[tok]);
; #pragma unroll
;                     for (int bj = 0; bj < 2; ++bj) {
;                         const f32x4 v0 = acc[ai][bj][m][0] * rs, v1 = acc[ai][bj][m][1] * rs;
;                         u32x4 w; w.x = cvt_pk_bf16(v0[0], v0[1]); w.y = cvt_pk_bf16(v0[2], v0[3]); w.z = cvt_pk_bf16(v1[0], v1[1]); w.w = cvt_pk_bf16(v1[2], v1[3]);
;                         WT_STORE16(ob + (size_t)tok * ld + 128 * bj + 32 * wc + 8 * fq, w);
;                     }
;                 }
.LBB0_236:
	v_mul_lo_u32 v142, v155, s78
	v_mul_lo_u32 v143, v176, s79
	v_mad_u64_u32 v[130:131], s[20:21], v176, s78, 0
	v_add3_u32 v131, v131, v143, v142
	v_lshl_add_u64 v[176:177], v[130:131], 1, v[132:133]
	s_waitcnt lgkmcnt(0)
	v_pk_mul_f32 v[132:133], v[72:73], v[174:175] op_sel_hi:[1,0]
	v_pk_mul_f32 v[130:131], v[70:71], v[174:175] op_sel_hi:[1,0]
	v_pk_mul_f32 v[178:179], v[68:69], v[174:175] op_sel_hi:[1,0]
	v_pk_mul_f32 v[184:185], v[66:67], v[174:175] op_sel_hi:[1,0]
	v_cvt_pk_bf16_f32 v130, v130, v131
	v_cvt_pk_bf16_f32 v131, v132, v133
	v_cvt_pk_bf16_f32 v133, v178, v179
	v_subrev_u32_e32 v142, s58, v176
	v_cvt_pk_bf16_f32 v132, v184, v185
	buffer_store_dwordx4 v[130:133], v142, s[60:63], 0 offen
	v_pk_mul_f32 v[178:179], v[4:5], v[174:175] op_sel_hi:[1,0]
	s_nop 0
	v_pk_mul_f32 v[132:133], v[8:9], v[174:175] op_sel_hi:[1,0]
	v_pk_mul_f32 v[130:131], v[6:7], v[174:175] op_sel_hi:[1,0]
	v_pk_mul_f32 v[174:175], v[2:3], v[174:175] op_sel_hi:[1,0]
	v_cvt_pk_bf16_f32 v130, v130, v131
	v_cvt_pk_bf16_f32 v131, v132, v133
	v_cvt_pk_bf16_f32 v133, v178, v179
	s_nop 0
	v_cvt_pk_bf16_f32 v132, v174, v175
	v_lshl_add_u64 v[174:175], v[176:177], 0, s[44:45]
	s_branch .LBB0_175

; __device__ __forceinline__ float rstd_of(u64 s) { return rsqrtf((float)s * SS_INV + EPS); }
; __device__ __forceinline__ unsigned cvt_pk_bf16(float lo, float hi) { unsigned r; asm("v_cvt_pk_bf16_f32 %0, %1, %2" : "=v"(r) : "v"(lo), "v"(hi)); return r; }
; #define WT_STORE16(ptr, val) __builtin_amdgcn_raw_buffer_store_b128((val), wsr, (int)((const char*)(ptr) - (const char*)ws), 0, 16)
; template <int MODE>
; __device__ __forceinline__ void gemm_epilogue(const Params& p, int l, const f32x4 (&acc)[2][2][4][2], const Unit& u, int wr, int wc, int fr, int fq, const LAS float* rl, int pm0) {
;     ...
;             u16* ob = (u.pn < 8) ? (u16*)(ws + WS_ZVT) + (size_t)((u.pn - 4) * 256) * T : (u16*)(ws + WS_ZVMT) + (size_t)((u.pn - 16) * 256) * T;
; #pragma unroll
;             for (int bj = 0; bj < 2; ++bj) {
;                 const int tok0 = u.pm * 256 + 128 * bj + 32 * wc + 8 * fq;
;                 f32x4 s0, s1;
; #pragma unroll
;                 for (int e = 0; e < 4; ++e) { s0[e] = (u.pm == pm0) ? rl[128 * bj + 32 * wc + 8 * fq + e] : rstd_of(ss[tok0 + e]); s1[e] = (u.pm == pm0) ? rl[128 * bj + 32 * wc + 8 * fq + 4 + e] : rstd_of(ss[tok0 + 4 + e]); }
; #pragma unroll
;                 for (int ai = 0; ai < 2; ++ai)
; #pragma unroll
;                     for (int m = 0; m < 4; ++m) {
;                         const int zr = 128 * ai + 64 * wr + 16 * m + fr;
;                         const f32x4 v0 = acc[ai][bj][m][0] * s0, v1 = acc[ai][bj][m][1] * s1;
;                         u32x4 w; w.x = cvt_pk_bf16(v0[0], v0[1]); w.y = cvt_pk_bf16(v0[2], v0[3]); w.z = cvt_pk_bf16(v1[0], v1[1]); w.w = cvt_pk_bf16(v1[2], v1[3]);
;                         WT_STORE16(ob + (size_t)zr * T + tok0, w);
;                     }
.LBB0_255:
	s_lshl_b32 s2, s96, 8
	s_add_i32 s15, s2, 0xfffff000
	s_ashr_i32 s17, s15, 31
	s_addk_i32 s2, 0xfc00
	s_cmp_lt_u32 s96, 8
	s_cselect_b32 s2, s2, s15
	s_mov_b32 s15, 0x16b00000
	s_cselect_b32 s15, s15, 0x1ce00000
	s_mul_i32 s22, s2, 0x8400
	s_cselect_b32 s17, 0, s17
	s_mul_hi_u32 s20, s2, 0x8400
	s_waitcnt lgkmcnt(0)
	v_pk_mul_f32 v[126:127], v[126:127], v[132:133]
	s_add_u32 s2, s22, s15
	v_pk_mul_f32 v[184:185], v[124:125], v[178:179]
	v_pk_mul_f32 v[124:125], v[122:123], v[174:175]
	v_cvt_pk_bf16_f32 v122, v126, v127
	v_lshl_add_u32 v126, v130, 1, s2
	v_pk_mul_f32 v[128:129], v[128:129], v[176:177]
	v_add_u32_e32 v127, v126, v154
	v_cvt_pk_bf16_f32 v123, v128, v129
	v_pk_mul_f32 v[118:119], v[118:119], v[132:133]
	v_cvt_pk_bf16_f32 v124, v124, v125
	v_cvt_pk_bf16_f32 v125, v184, v185
	buffer_store_dwordx4 v[122:125], v127, s[60:63], 0 offen
	v_pk_mul_f32 v[120:121], v[120:121], v[176:177]
	v_pk_mul_f32 v[110:111], v[110:111], v[132:133]
	v_pk_mul_f32 v[122:123], v[116:117], v[178:179]
	v_pk_mul_f32 v[116:117], v[114:115], v[174:175]
	v_cvt_pk_bf16_f32 v114, v118, v119
	v_cvt_pk_bf16_f32 v115, v120, v121
	v_add_u32_e32 v118, v126, v156
	v_cvt_pk_bf16_f32 v116, v116, v117
	v_cvt_pk_bf16_f32 v117, v122, v123
	buffer_store_dwordx4 v[114:117], v118, s[60:63], 0 offen
	v_pk_mul_f32 v[112:113], v[112:113], v[176:177]
	v_pk_mul_f32 v[102:103], v[102:103], v[132:133]
	v_pk_mul_f32 v[114:115], v[108:109], v[178:179]
	v_pk_mul_f32 v[108:109], v[106:107], v[174:175]
	v_cvt_pk_bf16_f32 v106, v110, v111
	v_cvt_pk_bf16_f32 v107, v112, v113
	v_add_u32_e32 v110, v126, v158
	v_cvt_pk_bf16_f32 v108, v108, v109
	v_cvt_pk_bf16_f32 v109, v114, v115
	buffer_store_dwordx4 v[106:109], v110, s[60:63], 0 offen
	v_pk_mul_f32 v[104:105], v[104:105], v[176:177]
	v_pk_mul_f32 v[94:95], v[94:95], v[132:133]
	v_pk_mul_f32 v[106:107], v[100:101], v[178:179]
	v_pk_mul_f32 v[100:101], v[98:99], v[174:175]
	v_cvt_pk_bf16_f32 v98, v102, v103
	v_cvt_pk_bf16_f32 v99, v104, v105
	v_add_u32_e32 v102, v126, v160
	v_cvt_pk_bf16_f32 v100, v100, v101
	v_cvt_pk_bf16_f32 v101, v106, v107
	buffer_store_dwordx4 v[98:101], v102, s[60:63], 0 offen
	v_pk_mul_f32 v[96:97], v[96:97], v[176:177]
	v_pk_mul_f32 v[86:87], v[86:87], v[132:133]
	v_pk_mul_f32 v[98:99], v[92:93], v[178:179]
	v_pk_mul_f32 v[92:93], v[90:91], v[174:175]
	v_cvt_pk_bf16_f32 v90, v94, v95
	v_cvt_pk_bf16_f32 v91, v96, v97
	v_add_u32_e32 v94, v126, v162
	v_cvt_pk_bf16_f32 v92, v92, v93
	v_cvt_pk_bf16_f32 v93, v98, v99
	buffer_store_dwordx4 v[90:93], v94, s[60:63], 0 offen
	v_pk_mul_f32 v[88:89], v[88:89], v[176:177]
	v_pk_mul_f32 v[78:79], v[78:79], v[132:133]
	v_pk_mul_f32 v[90:91], v[84:85], v[178:179]
	v_pk_mul_f32 v[84:85], v[82:83], v[174:175]
	v_cvt_pk_bf16_f32 v82, v86, v87
	v_cvt_pk_bf16_f32 v83, v88, v89
	v_add_u32_e32 v86, v126, v164
	s_mul_i32 s17, s17, 0x8400
	v_cvt_pk_bf16_f32 v84, v84, v85
	v_cvt_pk_bf16_f32 v85, v90, v91
	buffer_store_dwordx4 v[82:85], v86, s[60:63], 0 offen
	v_pk_mul_f32 v[80:81], v[80:81], v[176:177]
	v_pk_mul_f32 v[70:71], v[70:71], v[132:133]
	v_pk_mul_f32 v[82:83], v[76:77], v[178:179]
	v_pk_mul_f32 v[76:77], v[74:75], v[174:175]
	v_cvt_pk_bf16_f32 v74, v78, v79
	v_cvt_pk_bf16_f32 v75, v80, v81
	v_add_u32_e32 v78, v126, v166
	s_add_i32 s17, s20, s17
	v_cvt_pk_bf16_f32 v76, v76, v77
	v_cvt_pk_bf16_f32 v77, v82, v83
	buffer_store_dwordx4 v[74:77], v78, s[60:63], 0 offen
	s_and_b64 vcc, exec, s[40:41]
	s_mov_b64 s[20:21], -1
	v_pk_mul_f32 v[74:75], v[68:69], v[178:179]
	v_pk_mul_f32 v[68:69], v[66:67], v[174:175]
	v_cvt_pk_bf16_f32 v66, v70, v71
	v_add_u32_e32 v70, v126, v168
	v_pk_mul_f32 v[72:73], v[72:73], v[176:177]
	v_cvt_pk_bf16_f32 v68, v68, v69
	v_cvt_pk_bf16_f32 v69, v74, v75
	s_nop 0
	v_cvt_pk_bf16_f32 v67, v72, v73
	buffer_store_dwordx4 v[66:69], v70, s[60:63], 0 offen
	s_cbranch_vccz .LBB0_285
	s_andn2_b64 vcc, exec, s[20:21]
	s_cbranch_vccz .LBB0_286

; __device__ __forceinline__ unsigned cvt_pk_bf16(float lo, float hi) { unsigned r; asm("v_cvt_pk_bf16_f32 %0, %1, %2" : "=v"(r) : "v"(lo), "v"(hi)); return r; }
; #define WT_STORE16(ptr, val) __builtin_amdgcn_raw_buffer_store_b128((val), wsr, (int)((const char*)(ptr) - (const char*)ws), 0, 16)
; template <int MODE>
; __device__ __forceinline__ void gemm_epilogue(const Params& p, int l, const f32x4 (&acc)[2][2][4][2], const Unit& u, int wr, int wc, int fr, int fq, const LAS float* rl, int pm0) {
;     ...
;                 for (int ai = 0; ai < 2; ++ai)
; #pragma unroll
;                     for (int m = 0; m < 4; ++m) {
;                         const int zr = 128 * ai + 64 * wr + 16 * m + fr;
;                         const f32x4 v0 = acc[ai][bj][m][0] * s0, v1 = acc[ai][bj][m][1] * s1;
;                         u32x4 w; w.x = cvt_pk_bf16(v0[0], v0[1]); w.y = cvt_pk_bf16(v0[2], v0[3]); w.z = cvt_pk_bf16(v1[0], v1[1]); w.w = cvt_pk_bf16(v1[2], v1[3]);
;                         WT_STORE16(ob + (size_t)zr * T + tok0, w);
;                     }
.LBB0_369:
	v_subrev_u32_e32 v2, s58, v174
	s_add_i32 s10, s10, 1
	s_and_b64 vcc, exec, s[40:41]
	s_mov_b32 s96, s14
	s_mov_b32 s2, s16
	s_mov_b64 s[38:39], s[78:79]
	s_mov_b64 s[20:21], s[18:19]
	buffer_store_dwordx4 v[130:133], v2, s[60:63], 0 offen
	s_cbranch_vccnz .LBB0_497

; __device__ __forceinline__ float rstd_of(u64 s) { return rsqrtf((float)s * SS_INV + EPS); }
; __device__ __forceinline__ unsigned cvt_pk_bf16(float lo, float hi) { unsigned r; asm("v_cvt_pk_bf16_f32 %0, %1, %2" : "=v"(r) : "v"(lo), "v"(hi)); return r; }
; #define WT_STORE16(ptr, val) __builtin_amdgcn_raw_buffer_store_b128((val), wsr, (int)((const char*)(ptr) - (const char*)ws), 0, 16)
; template <int MODE>
; __device__ __forceinline__ void gemm_epilogue(const Params& p, int l, const f32x4 (&acc)[2][2][4][2], const Unit& u, int wr, int wc, int fr, int fq, const LAS float* rl, int pm0) {
;     ...
; #pragma unroll
;             for (int ai = 0; ai < 2; ++ai)
; #pragma unroll
;                 for (int m = 0; m < 4; ++m) {
;                     const int tok = u.pm * 256 + 128 * ai + 64 * wr + 16 * m + fr;
;                     const float rs = (u.pm == pm0) ? rl[128 * ai + 64 * wr + 16 * m + fr] : rstd_of(ss[tok]);
; #pragma unroll
;                     for (int bj = 0; bj < 2; ++bj) {
;                         const f32x4 v0 = acc[ai][bj][m][0] * rs, v1 = acc[ai][bj][m][1] * rs;
;                         u32x4 w; w.x = cvt_pk_bf16(v0[0], v0[1]); w.y = cvt_pk_bf16(v0[2], v0[3]); w.z = cvt_pk_bf16(v1[0], v1[1]); w.w = cvt_pk_bf16(v1[2], v1[3]);
;                         WT_STORE16(ob + (size_t)tok * ld + 128 * bj + 32 * wc + 8 * fq, w);
;                     }
;                 }
.LBB0_403:
	s_add_u32 s28, s38, s11
	s_addc_u32 s29, s39, 0
	v_lshl_add_u64 v[132:133], s[28:29], 0, v[0:1]
	v_mul_lo_u32 v142, v130, s20
	v_lshl_add_u32 v155, v142, 1, v132
	s_waitcnt lgkmcnt(0)
	v_pk_mul_f32 v[176:177], v[126:127], v[174:175] op_sel_hi:[1,0]
	v_pk_mul_f32 v[142:143], v[128:129], v[174:175] op_sel_hi:[1,0]
	v_pk_mul_f32 v[178:179], v[122:123], v[174:175] op_sel_hi:[1,0]
	v_cvt_pk_bf16_f32 v176, v176, v177
	v_cvt_pk_bf16_f32 v177, v142, v143
	v_subrev_u32_e32 v155, s58, v155
	v_pk_mul_f32 v[184:185], v[124:125], v[174:175] op_sel_hi:[1,0]
	v_cvt_pk_bf16_f32 v178, v178, v179
	v_pk_mul_f32 v[142:143], v[64:65], v[174:175] op_sel_hi:[1,0]
	v_cvt_pk_bf16_f32 v179, v184, v185
	buffer_store_dwordx4 v[176:179], v155, s[60:63], 0 offen
	v_pk_mul_f32 v[184:185], v[58:59], v[174:175] op_sel_hi:[1,0]
	s_andn2_b64 vcc, exec, s[22:23]
	v_pk_mul_f32 v[176:177], v[62:63], v[174:175] op_sel_hi:[1,0]
	v_pk_mul_f32 v[178:179], v[60:61], v[174:175] op_sel_hi:[1,0]
	v_cvt_pk_bf16_f32 v174, v176, v177
	v_cvt_pk_bf16_f32 v175, v142, v143
	v_cvt_pk_bf16_f32 v176, v184, v185
	v_cndmask_b32_e64 v142, 0, 1, s[22:23]
	v_cvt_pk_bf16_f32 v177, v178, v179
	buffer_store_dwordx4 v[174:177], v155, s[60:63], 0 offen offset:256
	v_cmp_ne_u32_e64 s[38:39], 1, v142
	s_mov_b64 s[22:23], -1
	v_or_b32_e32 v176, 16, v130
	s_cbranch_vccnz .LBB0_405
	v_lshl_add_u64 v[142:143], v[130:131], 3, s[0:1]
	global_load_dwordx2 v[142:143], v[142:143], off offset:128
	s_mov_b64 s[22:23], 0
	s_waitcnt vmcnt(0)
	v_ffbh_u32_e32 v155, v143
	v_min_u32_e32 v155, 32, v155
	v_lshlrev_b64 v[142:143], v155, v[142:143]
	v_min_u32_e32 v142, 1, v142
	v_or_b32_e32 v142, v143, v142
	v_cvt_f32_u32_e32 v142, v142
	v_sub_u32_e32 v143, 32, v155
	v_ldexp_f32 v142, v142, v143
	v_fmamk_f32 v142, v142, 0x30000000, v203
	v_mul_f32_e32 v143, 0x4b800000, v142
	v_cmp_gt_f32_e32 vcc, s89, v142
	s_nop 1
	v_cndmask_b32_e32 v142, v142, v143, vcc
	v_rsq_f32_e32 v142, v142
	s_nop 0
	v_mul_f32_e32 v143, 0x45800000, v142
	v_cndmask_b32_e32 v174, v142, v143, vcc

; __device__ __forceinline__ float rstd_of(u64 s) { return rsqrtf((float)s * SS_INV + EPS); }
; __device__ __forceinline__ unsigned cvt_pk_bf16(float lo, float hi) { unsigned r; asm("v_cvt_pk_bf16_f32 %0, %1, %2" : "=v"(r) : "v"(lo), "v"(hi)); return r; }
; #define WT_STORE16(ptr, val) __builtin_amdgcn_raw_buffer_store_b128((val), wsr, (int)((const char*)(ptr) - (const char*)ws), 0, 16)
; template <int MODE>
; __device__ __forceinline__ void gemm_epilogue(const Params& p, int l, const f32x4 (&acc)[2][2][4][2], const Unit& u, int wr, int wc, int fr, int fq, const LAS float* rl, int pm0) {
;     ...
; #pragma unroll
;             for (int ai = 0; ai < 2; ++ai)
; #pragma unroll
;                 for (int m = 0; m < 4; ++m) {
;                     const int tok = u.pm * 256 + 128 * ai + 64 * wr + 16 * m + fr;
;                     const float rs = (u.pm == pm0) ? rl[128 * ai + 64 * wr + 16 * m + fr] : rstd_of(ss[tok]);
; #pragma unroll
;                     for (int bj = 0; bj < 2; ++bj) {
;                         const f32x4 v0 = acc[ai][bj][m][0] * rs, v1 = acc[ai][bj][m][1] * rs;
;                         u32x4 w; w.x = cvt_pk_bf16(v0[0], v0[1]); w.y = cvt_pk_bf16(v0[2], v0[3]); w.z = cvt_pk_bf16(v1[0], v1[1]); w.w = cvt_pk_bf16(v1[2], v1[3]);
;                         WT_STORE16(ob + (size_t)tok * ld + 128 * bj + 32 * wc + 8 * fq, w);
;                     }
;                 }
.LBB0_407:
	v_mul_lo_u32 v142, v176, s20
	v_lshl_add_u32 v155, v142, 1, v132
	s_waitcnt lgkmcnt(0)
	v_pk_mul_f32 v[176:177], v[118:119], v[174:175] op_sel_hi:[1,0]
	v_pk_mul_f32 v[142:143], v[120:121], v[174:175] op_sel_hi:[1,0]
	v_pk_mul_f32 v[178:179], v[114:115], v[174:175] op_sel_hi:[1,0]
	v_cvt_pk_bf16_f32 v176, v176, v177
	v_cvt_pk_bf16_f32 v177, v142, v143
	v_subrev_u32_e32 v155, s58, v155
	v_pk_mul_f32 v[184:185], v[116:117], v[174:175] op_sel_hi:[1,0]
	v_cvt_pk_bf16_f32 v178, v178, v179
	v_pk_mul_f32 v[142:143], v[56:57], v[174:175] op_sel_hi:[1,0]
	v_cvt_pk_bf16_f32 v179, v184, v185
	buffer_store_dwordx4 v[176:179], v155, s[60:63], 0 offen
	v_pk_mul_f32 v[184:185], v[50:51], v[174:175] op_sel_hi:[1,0]
	s_and_b64 vcc, exec, s[38:39]
	v_pk_mul_f32 v[176:177], v[54:55], v[174:175] op_sel_hi:[1,0]
	v_pk_mul_f32 v[178:179], v[52:53], v[174:175] op_sel_hi:[1,0]
	v_cvt_pk_bf16_f32 v174, v176, v177
	v_cvt_pk_bf16_f32 v176, v184, v185
	v_cvt_pk_bf16_f32 v175, v142, v143
	s_mov_b64 s[22:23], -1
	v_cvt_pk_bf16_f32 v177, v178, v179
	buffer_store_dwordx4 v[174:177], v155, s[60:63], 0 offen offset:256
	s_nop 1
	v_or_b32_e32 v176, 32, v130
	s_cbranch_vccnz .LBB0_409
	v_lshl_add_u64 v[142:143], v[130:131], 3, s[0:1]
	global_load_dwordx2 v[142:143], v[142:143], off offset:256
	s_mov_b64 s[22:23], 0
	s_waitcnt vmcnt(0)
	v_ffbh_u32_e32 v155, v143
	v_min_u32_e32 v155, 32, v155
	v_lshlrev_b64 v[142:143], v155, v[142:143]
	v_min_u32_e32 v142, 1, v142
	v_or_b32_e32 v142, v143, v142
	v_cvt_f32_u32_e32 v142, v142
	v_sub_u32_e32 v143, 32, v155
	v_ldexp_f32 v142, v142, v143
	v_fmamk_f32 v142, v142, 0x30000000, v203
	v_mul_f32_e32 v143, 0x4b800000, v142
	v_cmp_gt_f32_e32 vcc, s89, v142
	s_nop 1
	v_cndmask_b32_e32 v142, v142, v143, vcc
	v_rsq_f32_e32 v142, v142
	s_nop 0
	v_mul_f32_e32 v143, 0x45800000, v142
	v_cndmask_b32_e32 v174, v142, v143, vcc

; __device__ __forceinline__ float rstd_of(u64 s) { return rsqrtf((float)s * SS_INV + EPS); }
; __device__ __forceinline__ unsigned cvt_pk_bf16(float lo, float hi) { unsigned r; asm("v_cvt_pk_bf16_f32 %0, %1, %2" : "=v"(r) : "v"(lo), "v"(hi)); return r; }
; #define WT_STORE16(ptr, val) __builtin_amdgcn_raw_buffer_store_b128((val), wsr, (int)((const char*)(ptr) - (const char*)ws), 0, 16)
; template <int MODE>
; __device__ __forceinline__ void gemm_epilogue(const Params& p, int l, const f32x4 (&acc)[2][2][4][2], const Unit& u, int wr, int wc, int fr, int fq, const LAS float* rl, int pm0) {
;     ...
; #pragma unroll
;             for (int ai = 0; ai < 2; ++ai)
; #pragma unroll
;                 for (int m = 0; m < 4; ++m) {
;                     const int tok = u.pm * 256 + 128 * ai + 64 * wr + 16 * m + fr;
;                     const float rs = (u.pm == pm0) ? rl[128 * ai + 64 * wr + 16 * m + fr] : rstd_of(ss[tok]);
; #pragma unroll
;                     for (int bj = 0; bj < 2; ++bj) {
;                         const f32x4 v0 = acc[ai][bj][m][0] * rs, v1 = acc[ai][bj][m][1] * rs;
;                         u32x4 w; w.x = cvt_pk_bf16(v0[0], v0[1]); w.y = cvt_pk_bf16(v0[2], v0[3]); w.z = cvt_pk_bf16(v1[0], v1[1]); w.w = cvt_pk_bf16(v1[2], v1[3]);
;                         WT_STORE16(ob + (size_t)tok * ld + 128 * bj + 32 * wc + 8 * fq, w);
;                     }
;                 }
.LBB0_411:
	v_mul_lo_u32 v142, v176, s20
	v_lshl_add_u32 v155, v142, 1, v132
	s_waitcnt lgkmcnt(0)
	v_pk_mul_f32 v[176:177], v[110:111], v[174:175] op_sel_hi:[1,0]
	v_pk_mul_f32 v[142:143], v[112:113], v[174:175] op_sel_hi:[1,0]
	v_pk_mul_f32 v[178:179], v[106:107], v[174:175] op_sel_hi:[1,0]
	v_cvt_pk_bf16_f32 v176, v176, v177
	v_cvt_pk_bf16_f32 v177, v142, v143
	v_subrev_u32_e32 v155, s58, v155
	v_pk_mul_f32 v[184:185], v[108:109], v[174:175] op_sel_hi:[1,0]
	v_cvt_pk_bf16_f32 v178, v178, v179
	v_pk_mul_f32 v[142:143], v[48:49], v[174:175] op_sel_hi:[1,0]
	v_cvt_pk_bf16_f32 v179, v184, v185
	buffer_store_dwordx4 v[176:179], v155, s[60:63], 0 offen
	v_pk_mul_f32 v[184:185], v[42:43], v[174:175] op_sel_hi:[1,0]
	s_and_b64 vcc, exec, s[38:39]
	v_pk_mul_f32 v[176:177], v[46:47], v[174:175] op_sel_hi:[1,0]
	v_pk_mul_f32 v[178:179], v[44:45], v[174:175] op_sel_hi:[1,0]
	v_cvt_pk_bf16_f32 v174, v176, v177
	v_cvt_pk_bf16_f32 v176, v184, v185
	v_cvt_pk_bf16_f32 v175, v142, v143
	s_mov_b64 s[22:23], -1
	v_cvt_pk_bf16_f32 v177, v178, v179
	buffer_store_dwordx4 v[174:177], v155, s[60:63], 0 offen offset:256
	s_nop 1
	v_or_b32_e32 v176, 48, v130
	s_cbranch_vccnz .LBB0_413
	v_lshl_add_u64 v[142:143], v[130:131], 3, s[0:1]
	global_load_dwordx2 v[142:143], v[142:143], off offset:384
	s_mov_b64 s[22:23], 0
	s_waitcnt vmcnt(0)
	v_ffbh_u32_e32 v155, v143
	v_min_u32_e32 v155, 32, v155
	v_lshlrev_b64 v[142:143], v155, v[142:143]
	v_min_u32_e32 v142, 1, v142
	v_or_b32_e32 v142, v143, v142
	v_cvt_f32_u32_e32 v142, v142
	v_sub_u32_e32 v143, 32, v155
	v_ldexp_f32 v142, v142, v143
	v_fmamk_f32 v142, v142, 0x30000000, v203
	v_mul_f32_e32 v143, 0x4b800000, v142
	v_cmp_gt_f32_e32 vcc, s89, v142
	s_nop 1
	v_cndmask_b32_e32 v142, v142, v143, vcc
	v_rsq_f32_e32 v142, v142
	s_nop 0
	v_mul_f32_e32 v143, 0x45800000, v142
	v_cndmask_b32_e32 v174, v142, v143, vcc

; __device__ __forceinline__ float rstd_of(u64 s) { return rsqrtf((float)s * SS_INV + EPS); }
; __device__ __forceinline__ unsigned cvt_pk_bf16(float lo, float hi) { unsigned r; asm("v_cvt_pk_bf16_f32 %0, %1, %2" : "=v"(r) : "v"(lo), "v"(hi)); return r; }
; #define WT_STORE16(ptr, val) __builtin_amdgcn_raw_buffer_store_b128((val), wsr, (int)((const char*)(ptr) - (const char*)ws), 0, 16)
; template <int MODE>
; __device__ __forceinline__ void gemm_epilogue(const Params& p, int l, const f32x4 (&acc)[2][2][4][2], const Unit& u, int wr, int wc, int fr, int fq, const LAS float* rl, int pm0) {
;     ...
; #pragma unroll
;             for (int ai = 0; ai < 2; ++ai)
; #pragma unroll
;                 for (int m = 0; m < 4; ++m) {
;                     const int tok = u.pm * 256 + 128 * ai + 64 * wr + 16 * m + fr;
;                     const float rs = (u.pm == pm0) ? rl[128 * ai + 64 * wr + 16 * m + fr] : rstd_of(ss[tok]);
; #pragma unroll
;                     for (int bj = 0; bj < 2; ++bj) {
;                         const f32x4 v0 = acc[ai][bj][m][0] * rs, v1 = acc[ai][bj][m][1] * rs;
;                         u32x4 w; w.x = cvt_pk_bf16(v0[0], v0[1]); w.y = cvt_pk_bf16(v0[2], v0[3]); w.z = cvt_pk_bf16(v1[0], v1[1]); w.w = cvt_pk_bf16(v1[2], v1[3]);
;                         WT_STORE16(ob + (size_t)tok * ld + 128 * bj + 32 * wc + 8 * fq, w);
;                     }
;                 }
.LBB0_415:
	v_mul_lo_u32 v142, v176, s20
	v_lshl_add_u32 v155, v142, 1, v132
	s_waitcnt lgkmcnt(0)
	v_pk_mul_f32 v[176:177], v[102:103], v[174:175] op_sel_hi:[1,0]
	v_pk_mul_f32 v[142:143], v[104:105], v[174:175] op_sel_hi:[1,0]
	v_pk_mul_f32 v[178:179], v[98:99], v[174:175] op_sel_hi:[1,0]
	v_cvt_pk_bf16_f32 v176, v176, v177
	v_cvt_pk_bf16_f32 v177, v142, v143
	v_subrev_u32_e32 v155, s58, v155
	v_pk_mul_f32 v[184:185], v[100:101], v[174:175] op_sel_hi:[1,0]
	v_cvt_pk_bf16_f32 v178, v178, v179
	v_pk_mul_f32 v[142:143], v[40:41], v[174:175] op_sel_hi:[1,0]
	v_cvt_pk_bf16_f32 v179, v184, v185
	buffer_store_dwordx4 v[176:179], v155, s[60:63], 0 offen
	v_pk_mul_f32 v[184:185], v[34:35], v[174:175] op_sel_hi:[1,0]
	s_and_b64 vcc, exec, s[38:39]
	v_pk_mul_f32 v[176:177], v[38:39], v[174:175] op_sel_hi:[1,0]
	v_pk_mul_f32 v[178:179], v[36:37], v[174:175] op_sel_hi:[1,0]
	v_cvt_pk_bf16_f32 v174, v176, v177
	v_cvt_pk_bf16_f32 v176, v184, v185
	v_cvt_pk_bf16_f32 v175, v142, v143
	s_mov_b64 s[22:23], -1
	v_cvt_pk_bf16_f32 v177, v178, v179
	buffer_store_dwordx4 v[174:177], v155, s[60:63], 0 offen offset:256
	s_nop 1
	v_add_u32_e32 v176, 0x80, v130
	s_cbranch_vccnz .LBB0_417
	v_lshl_add_u64 v[142:143], v[130:131], 3, s[0:1]
	global_load_dwordx2 v[142:143], v[142:143], off offset:1024
	s_mov_b64 s[22:23], 0
	s_waitcnt vmcnt(0)
	v_ffbh_u32_e32 v155, v143
	v_min_u32_e32 v155, 32, v155
	v_lshlrev_b64 v[142:143], v155, v[142:143]
	v_min_u32_e32 v142, 1, v142
	v_or_b32_e32 v142, v143, v142
	v_cvt_f32_u32_e32 v142, v142
	v_sub_u32_e32 v143, 32, v155
	v_ldexp_f32 v142, v142, v143
	v_fmamk_f32 v142, v142, 0x30000000, v203
	v_mul_f32_e32 v143, 0x4b800000, v142
	v_cmp_gt_f32_e32 vcc, s89, v142
	s_nop 1
	v_cndmask_b32_e32 v142, v142, v143, vcc
	v_rsq_f32_e32 v142, v142
	s_nop 0
	v_mul_f32_e32 v143, 0x45800000, v142
	v_cndmask_b32_e32 v174, v142, v143, vcc

; __device__ __forceinline__ float rstd_of(u64 s) { return rsqrtf((float)s * SS_INV + EPS); }
; __device__ __forceinline__ unsigned cvt_pk_bf16(float lo, float hi) { unsigned r; asm("v_cvt_pk_bf16_f32 %0, %1, %2" : "=v"(r) : "v"(lo), "v"(hi)); return r; }
; #define WT_STORE16(ptr, val) __builtin_amdgcn_raw_buffer_store_b128((val), wsr, (int)((const char*)(ptr) - (const char*)ws), 0, 16)
; template <int MODE>
; __device__ __forceinline__ void gemm_epilogue(const Params& p, int l, const f32x4 (&acc)[2][2][4][2], const Unit& u, int wr, int wc, int fr, int fq, const LAS float* rl, int pm0) {
;     ...
; #pragma unroll
;             for (int ai = 0; ai < 2; ++ai)
; #pragma unroll
;                 for (int m = 0; m < 4; ++m) {
;                     const int tok = u.pm * 256 + 128 * ai + 64 * wr + 16 * m + fr;
;                     const float rs = (u.pm == pm0) ? rl[128 * ai + 64 * wr + 16 * m + fr] : rstd_of(ss[tok]);
; #pragma unroll
;                     for (int bj = 0; bj < 2; ++bj) {
;                         const f32x4 v0 = acc[ai][bj][m][0] * rs, v1 = acc[ai][bj][m][1] * rs;
;                         u32x4 w; w.x = cvt_pk_bf16(v0[0], v0[1]); w.y = cvt_pk_bf16(v0[2], v0[3]); w.z = cvt_pk_bf16(v1[0], v1[1]); w.w = cvt_pk_bf16(v1[2], v1[3]);
;                         WT_STORE16(ob + (size_t)tok * ld + 128 * bj + 32 * wc + 8 * fq, w);
;                     }
;                 }
.LBB0_419:
	v_mul_lo_u32 v142, v176, s20
	v_lshl_add_u32 v155, v142, 1, v132
	s_waitcnt lgkmcnt(0)
	v_pk_mul_f32 v[176:177], v[94:95], v[174:175] op_sel_hi:[1,0]
	v_pk_mul_f32 v[142:143], v[96:97], v[174:175] op_sel_hi:[1,0]
	v_pk_mul_f32 v[178:179], v[90:91], v[174:175] op_sel_hi:[1,0]
	v_cvt_pk_bf16_f32 v176, v176, v177
	v_cvt_pk_bf16_f32 v177, v142, v143
	v_subrev_u32_e32 v155, s58, v155
	v_pk_mul_f32 v[184:185], v[92:93], v[174:175] op_sel_hi:[1,0]
	v_cvt_pk_bf16_f32 v178, v178, v179
	v_pk_mul_f32 v[142:143], v[32:33], v[174:175] op_sel_hi:[1,0]
	v_cvt_pk_bf16_f32 v179, v184, v185
	buffer_store_dwordx4 v[176:179], v155, s[60:63], 0 offen
	v_pk_mul_f32 v[184:185], v[26:27], v[174:175] op_sel_hi:[1,0]
	s_and_b64 vcc, exec, s[38:39]
	v_pk_mul_f32 v[176:177], v[30:31], v[174:175] op_sel_hi:[1,0]
	v_pk_mul_f32 v[178:179], v[28:29], v[174:175] op_sel_hi:[1,0]
	v_cvt_pk_bf16_f32 v174, v176, v177
	v_cvt_pk_bf16_f32 v176, v184, v185
	v_cvt_pk_bf16_f32 v175, v142, v143
	s_mov_b64 s[22:23], -1
	v_cvt_pk_bf16_f32 v177, v178, v179
	buffer_store_dwordx4 v[174:177], v155, s[60:63], 0 offen offset:256
	s_nop 1
	v_add_u32_e32 v176, 0x90, v130
	s_cbranch_vccnz .LBB0_421
	v_lshl_add_u64 v[142:143], v[130:131], 3, s[0:1]
	global_load_dwordx2 v[142:143], v[142:143], off offset:1152
	s_mov_b64 s[22:23], 0
	s_waitcnt vmcnt(0)
	v_ffbh_u32_e32 v155, v143
	v_min_u32_e32 v155, 32, v155
	v_lshlrev_b64 v[142:143], v155, v[142:143]
	v_min_u32_e32 v142, 1, v142
	v_or_b32_e32 v142, v143, v142
	v_cvt_f32_u32_e32 v142, v142
	v_sub_u32_e32 v143, 32, v155
	v_ldexp_f32 v142, v142, v143
	v_fmamk_f32 v142, v142, 0x30000000, v203
	v_mul_f32_e32 v143, 0x4b800000, v142
	v_cmp_gt_f32_e32 vcc, s89, v142
	s_nop 1
	v_cndmask_b32_e32 v142, v142, v143, vcc
	v_rsq_f32_e32 v142, v142
	s_nop 0
	v_mul_f32_e32 v143, 0x45800000, v142
	v_cndmask_b32_e32 v174, v142, v143, vcc

; __device__ __forceinline__ float rstd_of(u64 s) { return rsqrtf((float)s * SS_INV + EPS); }
; __device__ __forceinline__ unsigned cvt_pk_bf16(float lo, float hi) { unsigned r; asm("v_cvt_pk_bf16_f32 %0, %1, %2" : "=v"(r) : "v"(lo), "v"(hi)); return r; }
; #define WT_STORE16(ptr, val) __builtin_amdgcn_raw_buffer_store_b128((val), wsr, (int)((const char*)(ptr) - (const char*)ws), 0, 16)
; template <int MODE>
; __device__ __forceinline__ void gemm_epilogue(const Params& p, int l, const f32x4 (&acc)[2][2][4][2], const Unit& u, int wr, int wc, int fr, int fq, const LAS float* rl, int pm0) {
;     ...
; #pragma unroll
;             for (int ai = 0; ai < 2; ++ai)
; #pragma unroll
;                 for (int m = 0; m < 4; ++m) {
;                     const int tok = u.pm * 256 + 128 * ai + 64 * wr + 16 * m + fr;
;                     const float rs = (u.pm == pm0) ? rl[128 * ai + 64 * wr + 16 * m + fr] : rstd_of(ss[tok]);
; #pragma unroll
;                     for (int bj = 0; bj < 2; ++bj) {
;                         const f32x4 v0 = acc[ai][bj][m][0] * rs, v1 = acc[ai][bj][m][1] * rs;
;                         u32x4 w; w.x = cvt_pk_bf16(v0[0], v0[1]); w.y = cvt_pk_bf16(v0[2], v0[3]); w.z = cvt_pk_bf16(v1[0], v1[1]); w.w = cvt_pk_bf16(v1[2], v1[3]);
;                         WT_STORE16(ob + (size_t)tok * ld + 128 * bj + 32 * wc + 8 * fq, w);
;                     }
;                 }
.LBB0_423:
	v_mul_lo_u32 v142, v176, s20
	v_lshl_add_u32 v155, v142, 1, v132
	s_waitcnt lgkmcnt(0)
	v_pk_mul_f32 v[176:177], v[86:87], v[174:175] op_sel_hi:[1,0]
	v_pk_mul_f32 v[142:143], v[88:89], v[174:175] op_sel_hi:[1,0]
	v_pk_mul_f32 v[178:179], v[82:83], v[174:175] op_sel_hi:[1,0]
	v_cvt_pk_bf16_f32 v176, v176, v177
	v_cvt_pk_bf16_f32 v177, v142, v143
	v_subrev_u32_e32 v155, s58, v155
	v_pk_mul_f32 v[184:185], v[84:85], v[174:175] op_sel_hi:[1,0]
	v_cvt_pk_bf16_f32 v178, v178, v179
	v_pk_mul_f32 v[142:143], v[24:25], v[174:175] op_sel_hi:[1,0]
	v_cvt_pk_bf16_f32 v179, v184, v185
	buffer_store_dwordx4 v[176:179], v155, s[60:63], 0 offen
	v_pk_mul_f32 v[184:185], v[18:19], v[174:175] op_sel_hi:[1,0]
	s_and_b64 vcc, exec, s[38:39]
	v_pk_mul_f32 v[176:177], v[22:23], v[174:175] op_sel_hi:[1,0]
	v_pk_mul_f32 v[178:179], v[20:21], v[174:175] op_sel_hi:[1,0]
	v_cvt_pk_bf16_f32 v174, v176, v177
	v_cvt_pk_bf16_f32 v176, v184, v185
	v_cvt_pk_bf16_f32 v175, v142, v143
	s_mov_b64 s[22:23], -1
	v_cvt_pk_bf16_f32 v177, v178, v179
	buffer_store_dwordx4 v[174:177], v155, s[60:63], 0 offen offset:256
	s_nop 1
	v_add_u32_e32 v176, 0xa0, v130
	s_cbranch_vccnz .LBB0_425
	v_lshl_add_u64 v[142:143], v[130:131], 3, s[0:1]
	global_load_dwordx2 v[142:143], v[142:143], off offset:1280
	s_mov_b64 s[22:23], 0
	s_waitcnt vmcnt(0)
	v_ffbh_u32_e32 v155, v143
	v_min_u32_e32 v155, 32, v155
	v_lshlrev_b64 v[142:143], v155, v[142:143]
	v_min_u32_e32 v142, 1, v142
	v_or_b32_e32 v142, v143, v142
	v_cvt_f32_u32_e32 v142, v142
	v_sub_u32_e32 v143, 32, v155
	v_ldexp_f32 v142, v142, v143
	v_fmamk_f32 v142, v142, 0x30000000, v203
	v_mul_f32_e32 v143, 0x4b800000, v142
	v_cmp_gt_f32_e32 vcc, s89, v142
	s_nop 1
	v_cndmask_b32_e32 v142, v142, v143, vcc
	v_rsq_f32_e32 v142, v142
	s_nop 0
	v_mul_f32_e32 v143, 0x45800000, v142
	v_cndmask_b32_e32 v174, v142, v143, vcc

; __device__ __forceinline__ float rstd_of(u64 s) { return rsqrtf((float)s * SS_INV + EPS); }
; __device__ __forceinline__ unsigned cvt_pk_bf16(float lo, float hi) { unsigned r; asm("v_cvt_pk_bf16_f32 %0, %1, %2" : "=v"(r) : "v"(lo), "v"(hi)); return r; }
; #define WT_STORE16(ptr, val) __builtin_amdgcn_raw_buffer_store_b128((val), wsr, (int)((const char*)(ptr) - (const char*)ws), 0, 16)
; template <int MODE>
; __device__ __forceinline__ void gemm_epilogue(const Params& p, int l, const f32x4 (&acc)[2][2][4][2], const Unit& u, int wr, int wc, int fr, int fq, const LAS float* rl, int pm0) {
;     ...
; #pragma unroll
;             for (int ai = 0; ai < 2; ++ai)
; #pragma unroll
;                 for (int m = 0; m < 4; ++m) {
;                     const int tok = u.pm * 256 + 128 * ai + 64 * wr + 16 * m + fr;
;                     const float rs = (u.pm == pm0) ? rl[128 * ai + 64 * wr + 16 * m + fr] : rstd_of(ss[tok]);
; #pragma unroll
;                     for (int bj = 0; bj < 2; ++bj) {
;                         const f32x4 v0 = acc[ai][bj][m][0] * rs, v1 = acc[ai][bj][m][1] * rs;
;                         u32x4 w; w.x = cvt_pk_bf16(v0[0], v0[1]); w.y = cvt_pk_bf16(v0[2], v0[3]); w.z = cvt_pk_bf16(v1[0], v1[1]); w.w = cvt_pk_bf16(v1[2], v1[3]);
;                         WT_STORE16(ob + (size_t)tok * ld + 128 * bj + 32 * wc + 8 * fq, w);
;                     }
;                 }
.LBB0_427:
	v_mul_lo_u32 v142, v176, s20
	v_lshl_add_u32 v155, v142, 1, v132
	s_waitcnt lgkmcnt(0)
	v_pk_mul_f32 v[176:177], v[78:79], v[174:175] op_sel_hi:[1,0]
	v_pk_mul_f32 v[142:143], v[80:81], v[174:175] op_sel_hi:[1,0]
	v_pk_mul_f32 v[178:179], v[74:75], v[174:175] op_sel_hi:[1,0]
	v_cvt_pk_bf16_f32 v176, v176, v177
	v_cvt_pk_bf16_f32 v177, v142, v143
	v_subrev_u32_e32 v155, s58, v155
	v_pk_mul_f32 v[184:185], v[76:77], v[174:175] op_sel_hi:[1,0]
	v_cvt_pk_bf16_f32 v178, v178, v179
	v_pk_mul_f32 v[142:143], v[16:17], v[174:175] op_sel_hi:[1,0]
	v_cvt_pk_bf16_f32 v179, v184, v185
	buffer_store_dwordx4 v[176:179], v155, s[60:63], 0 offen
	v_pk_mul_f32 v[184:185], v[10:11], v[174:175] op_sel_hi:[1,0]
	s_mov_b64 s[22:23], -1
	v_pk_mul_f32 v[176:177], v[14:15], v[174:175] op_sel_hi:[1,0]
	v_pk_mul_f32 v[178:179], v[12:13], v[174:175] op_sel_hi:[1,0]
	v_cvt_pk_bf16_f32 v174, v176, v177
	v_cvt_pk_bf16_f32 v176, v184, v185
	v_cvt_pk_bf16_f32 v175, v142, v143
	s_and_b64 vcc, exec, s[38:39]
	v_cvt_pk_bf16_f32 v177, v178, v179
	buffer_store_dwordx4 v[174:177], v155, s[60:63], 0 offen offset:256
	s_nop 1
	v_add_u32_e32 v176, 0xb0, v130
	v_ashrrev_i32_e32 v155, 31, v176
	s_cbranch_vccnz .LBB0_429
	v_lshl_add_u64 v[130:131], v[130:131], 3, s[0:1]
	global_load_dwordx2 v[130:131], v[130:131], off offset:1408
	s_mov_b64 s[22:23], 0
	s_waitcnt vmcnt(0)
	v_ffbh_u32_e32 v142, v131
	v_min_u32_e32 v142, 32, v142
	v_lshlrev_b64 v[130:131], v142, v[130:131]
	v_min_u32_e32 v130, 1, v130
	v_or_b32_e32 v130, v131, v130
	v_cvt_f32_u32_e32 v130, v130
	v_sub_u32_e32 v131, 32, v142
	v_ldexp_f32 v130, v130, v131
	v_fmamk_f32 v130, v130, 0x30000000, v203
	v_mul_f32_e32 v131, 0x4b800000, v130
	v_cmp_gt_f32_e32 vcc, s89, v130
	s_nop 1
	v_cndmask_b32_e32 v130, v130, v131, vcc
	v_rsq_f32_e32 v130, v130
	s_nop 0
	v_mul_f32_e32 v131, 0x45800000, v130
	v_cndmask_b32_e32 v174, v130, v131, vcc

; __device__ __forceinline__ float rstd_of(u64 s) { return rsqrtf((float)s * SS_INV + EPS); }
; __device__ __forceinline__ unsigned cvt_pk_bf16(float lo, float hi) { unsigned r; asm("v_cvt_pk_bf16_f32 %0, %1, %2" : "=v"(r) : "v"(lo), "v"(hi)); return r; }
; #define WT_STORE16(ptr, val) __builtin_amdgcn_raw_buffer_store_b128((val), wsr, (int)((const char*)(ptr) - (const char*)ws), 0, 16)
; template <int MODE>
; __device__ __forceinline__ void gemm_epilogue(const Params& p, int l, const f32x4 (&acc)[2][2][4][2], const Unit& u, int wr, int wc, int fr, int fq, const LAS float* rl, int pm0) {
;     ...
; #pragma unroll
;             for (int ai = 0; ai < 2; ++ai)
; #pragma unroll
;                 for (int m = 0; m < 4; ++m) {
;                     const int tok = u.pm * 256 + 128 * ai + 64 * wr + 16 * m + fr;
;                     const float rs = (u.pm == pm0) ? rl[128 * ai + 64 * wr + 16 * m + fr] : rstd_of(ss[tok]);
; #pragma unroll
;                     for (int bj = 0; bj < 2; ++bj) {
;                         const f32x4 v0 = acc[ai][bj][m][0] * rs, v1 = acc[ai][bj][m][1] * rs;
;                         u32x4 w; w.x = cvt_pk_bf16(v0[0], v0[1]); w.y = cvt_pk_bf16(v0[2], v0[3]); w.z = cvt_pk_bf16(v1[0], v1[1]); w.w = cvt_pk_bf16(v1[2], v1[3]);
;                         WT_STORE16(ob + (size_t)tok * ld + 128 * bj + 32 * wc + 8 * fq, w);
;                     }
;                 }
.LBB0_431:
	v_mul_lo_u32 v142, v155, s20
	v_mul_lo_u32 v143, v176, s21
	v_mad_u64_u32 v[130:131], s[20:21], v176, s20, 0
	v_add3_u32 v131, v131, v143, v142
	v_lshl_add_u64 v[142:143], v[130:131], 1, v[132:133]
	s_waitcnt lgkmcnt(0)
	v_pk_mul_f32 v[132:133], v[72:73], v[174:175] op_sel_hi:[1,0]
	v_pk_mul_f32 v[130:131], v[70:71], v[174:175] op_sel_hi:[1,0]
	v_pk_mul_f32 v[176:177], v[68:69], v[174:175] op_sel_hi:[1,0]
	v_pk_mul_f32 v[178:179], v[66:67], v[174:175] op_sel_hi:[1,0]
	v_cvt_pk_bf16_f32 v130, v130, v131
	v_cvt_pk_bf16_f32 v131, v132, v133
	v_cvt_pk_bf16_f32 v133, v176, v177
	v_subrev_u32_e32 v155, s58, v142
	v_cvt_pk_bf16_f32 v132, v178, v179
	buffer_store_dwordx4 v[130:133], v155, s[60:63], 0 offen
	v_pk_mul_f32 v[176:177], v[4:5], v[174:175] op_sel_hi:[1,0]
	s_nop 0
	v_pk_mul_f32 v[132:133], v[8:9], v[174:175] op_sel_hi:[1,0]
	v_pk_mul_f32 v[130:131], v[6:7], v[174:175] op_sel_hi:[1,0]
	v_pk_mul_f32 v[174:175], v[2:3], v[174:175] op_sel_hi:[1,0]
	v_cvt_pk_bf16_f32 v130, v130, v131
	v_cvt_pk_bf16_f32 v131, v132, v133
	v_cvt_pk_bf16_f32 v133, v176, v177
	s_nop 0
	v_cvt_pk_bf16_f32 v132, v174, v175
	v_lshl_add_u64 v[174:175], v[142:143], 0, s[44:45]
	s_branch .LBB0_369

; __device__ __forceinline__ float rstd_of(u64 s) { return rsqrtf((float)s * SS_INV + EPS); }
; __device__ __forceinline__ unsigned cvt_pk_bf16(float lo, float hi) { unsigned r; asm("v_cvt_pk_bf16_f32 %0, %1, %2" : "=v"(r) : "v"(lo), "v"(hi)); return r; }
; #define WT_STORE16(ptr, val) __builtin_amdgcn_raw_buffer_store_b128((val), wsr, (int)((const char*)(ptr) - (const char*)ws), 0, 16)
; template <int MODE>
; __device__ __forceinline__ void gemm_epilogue(const Params& p, int l, const f32x4 (&acc)[2][2][4][2], const Unit& u, int wr, int wc, int fr, int fq, const LAS float* rl, int pm0) {
;     ...
;             u16* ob = (u.pn < 8) ? (u16*)(ws + WS_ZVT) + (size_t)((u.pn - 4) * 256) * T : (u16*)(ws + WS_ZVMT) + (size_t)((u.pn - 16) * 256) * T;
; #pragma unroll
;             for (int bj = 0; bj < 2; ++bj) {
;                 const int tok0 = u.pm * 256 + 128 * bj + 32 * wc + 8 * fq;
;                 f32x4 s0, s1;
; #pragma unroll
;                 for (int e = 0; e < 4; ++e) { s0[e] = (u.pm == pm0) ? rl[128 * bj + 32 * wc + 8 * fq + e] : rstd_of(ss[tok0 + e]); s1[e] = (u.pm == pm0) ? rl[128 * bj + 32 * wc + 8 * fq + 4 + e] : rstd_of(ss[tok0 + 4 + e]); }
; #pragma unroll
;                 for (int ai = 0; ai < 2; ++ai)
; #pragma unroll
;                     for (int m = 0; m < 4; ++m) {
;                         const int zr = 128 * ai + 64 * wr + 16 * m + fr;
;                         const f32x4 v0 = acc[ai][bj][m][0] * s0, v1 = acc[ai][bj][m][1] * s1;
;                         u32x4 w; w.x = cvt_pk_bf16(v0[0], v0[1]); w.y = cvt_pk_bf16(v0[2], v0[3]); w.z = cvt_pk_bf16(v1[0], v1[1]); w.w = cvt_pk_bf16(v1[2], v1[3]);
;                         WT_STORE16(ob + (size_t)zr * T + tok0, w);
;                     }
.LBB0_450:
	s_lshl_b32 s2, s96, 8
	s_add_i32 s15, s2, 0xfffff000
	s_ashr_i32 s17, s15, 31
	s_addk_i32 s2, 0xfc00
	s_cmp_lt_u32 s96, 8
	s_cselect_b32 s2, s2, s15
	s_mov_b32 s6, 0x16b00000
	s_cselect_b32 s15, s6, 0x1ce00000
	s_mul_i32 s22, s2, 0x8400
	s_cselect_b32 s17, 0, s17
	s_mul_hi_u32 s20, s2, 0x8400
	s_waitcnt lgkmcnt(0)
	v_pk_mul_f32 v[126:127], v[126:127], v[132:133]
	s_add_u32 s2, s22, s15
	v_pk_mul_f32 v[142:143], v[124:125], v[178:179]
	v_pk_mul_f32 v[124:125], v[122:123], v[174:175]
	v_cvt_pk_bf16_f32 v122, v126, v127
	v_lshl_add_u32 v126, v130, 1, s2
	v_pk_mul_f32 v[128:129], v[128:129], v[176:177]
	v_add_u32_e32 v127, v126, v154
	v_cvt_pk_bf16_f32 v123, v128, v129
	v_pk_mul_f32 v[118:119], v[118:119], v[132:133]
	v_cvt_pk_bf16_f32 v124, v124, v125
	v_cvt_pk_bf16_f32 v125, v142, v143
	buffer_store_dwordx4 v[122:125], v127, s[60:63], 0 offen
	v_pk_mul_f32 v[120:121], v[120:121], v[176:177]
	v_pk_mul_f32 v[110:111], v[110:111], v[132:133]
	v_pk_mul_f32 v[122:123], v[116:117], v[178:179]
	v_pk_mul_f32 v[116:117], v[114:115], v[174:175]
	v_cvt_pk_bf16_f32 v114, v118, v119
	v_cvt_pk_bf16_f32 v115, v120, v121
	v_add_u32_e32 v118, v126, v156
	v_cvt_pk_bf16_f32 v116, v116, v117
	v_cvt_pk_bf16_f32 v117, v122, v123
	buffer_store_dwordx4 v[114:117], v118, s[60:63], 0 offen
	v_pk_mul_f32 v[112:113], v[112:113], v[176:177]
	v_pk_mul_f32 v[102:103], v[102:103], v[132:133]
	v_pk_mul_f32 v[114:115], v[108:109], v[178:179]
	v_pk_mul_f32 v[108:109], v[106:107], v[174:175]
	v_cvt_pk_bf16_f32 v106, v110, v111
	v_cvt_pk_bf16_f32 v107, v112, v113
	v_add_u32_e32 v110, v126, v158
	v_cvt_pk_bf16_f32 v108, v108, v109
	v_cvt_pk_bf16_f32 v109, v114, v115
	buffer_store_dwordx4 v[106:109], v110, s[60:63], 0 offen
	v_pk_mul_f32 v[104:105], v[104:105], v[176:177]
	v_pk_mul_f32 v[94:95], v[94:95], v[132:133]
	v_pk_mul_f32 v[106:107], v[100:101], v[178:179]
	v_pk_mul_f32 v[100:101], v[98:99], v[174:175]
	v_cvt_pk_bf16_f32 v98, v102, v103
	v_cvt_pk_bf16_f32 v99, v104, v105
	v_add_u32_e32 v102, v126, v160
	v_cvt_pk_bf16_f32 v100, v100, v101
	v_cvt_pk_bf16_f32 v101, v106, v107
	buffer_store_dwordx4 v[98:101], v102, s[60:63], 0 offen
	v_pk_mul_f32 v[96:97], v[96:97], v[176:177]
	v_pk_mul_f32 v[86:87], v[86:87], v[132:133]
	v_pk_mul_f32 v[98:99], v[92:93], v[178:179]
	v_pk_mul_f32 v[92:93], v[90:91], v[174:175]
	v_cvt_pk_bf16_f32 v90, v94, v95
	v_cvt_pk_bf16_f32 v91, v96, v97
	v_add_u32_e32 v94, v126, v162
	v_cvt_pk_bf16_f32 v92, v92, v93
	v_cvt_pk_bf16_f32 v93, v98, v99
	buffer_store_dwordx4 v[90:93], v94, s[60:63], 0 offen
	v_pk_mul_f32 v[88:89], v[88:89], v[176:177]
	v_pk_mul_f32 v[78:79], v[78:79], v[132:133]
	v_pk_mul_f32 v[90:91], v[84:85], v[178:179]
	v_pk_mul_f32 v[84:85], v[82:83], v[174:175]
	v_cvt_pk_bf16_f32 v82, v86, v87
	v_cvt_pk_bf16_f32 v83, v88, v89
	v_add_u32_e32 v86, v126, v164
	s_mul_i32 s17, s17, 0x8400
	v_cvt_pk_bf16_f32 v84, v84, v85
	v_cvt_pk_bf16_f32 v85, v90, v91
	buffer_store_dwordx4 v[82:85], v86, s[60:63], 0 offen
	v_pk_mul_f32 v[80:81], v[80:81], v[176:177]
	v_pk_mul_f32 v[70:71], v[70:71], v[132:133]
	v_pk_mul_f32 v[82:83], v[76:77], v[178:179]
	v_pk_mul_f32 v[76:77], v[74:75], v[174:175]
	v_cvt_pk_bf16_f32 v74, v78, v79
	v_cvt_pk_bf16_f32 v75, v80, v81
	v_add_u32_e32 v78, v126, v166
	s_add_i32 s17, s20, s17
	v_cvt_pk_bf16_f32 v76, v76, v77
	v_cvt_pk_bf16_f32 v77, v82, v83
	buffer_store_dwordx4 v[74:77], v78, s[60:63], 0 offen
	s_and_b64 vcc, exec, s[38:39]
	s_mov_b64 s[20:21], -1
	v_pk_mul_f32 v[74:75], v[68:69], v[178:179]
	v_pk_mul_f32 v[68:69], v[66:67], v[174:175]
	v_cvt_pk_bf16_f32 v66, v70, v71
	v_add_u32_e32 v70, v126, v168
	v_pk_mul_f32 v[72:73], v[72:73], v[176:177]
	v_cvt_pk_bf16_f32 v68, v68, v69
	v_cvt_pk_bf16_f32 v69, v74, v75
	s_nop 0
	v_cvt_pk_bf16_f32 v67, v72, v73
	buffer_store_dwordx4 v[66:69], v70, s[60:63], 0 offen
	s_cbranch_vccz .LBB0_480
	s_andn2_b64 vcc, exec, s[20:21]
	s_cbranch_vccz .LBB0_481

; #define PG8_STAGE(bufoff, gbase, voff) do { _Pragma("unroll") for (int _i = 0; _i < 2; ++_i) \
;         __builtin_amdgcn_global_load_lds((const unsigned*)((const char*)(gbase) + (voff)[_i]), (LAS unsigned*)(lds + (bufoff) + ldsw + _i * 8192), 16, 0, 0); } while (0)
; #define PG8_LDA(dst, b, h) do { _Pragma("unroll") for (int m = 0; m < 4; ++m) _Pragma("unroll") for (int k = 0; k < 2; ++k) dst[m][k] = *(const LAS bf16x8*)(lds + PG8_SA(b, h) + aoff + m * 2048 + k * 1024); } while (0)
; #define PG8_LDB(dst, b, h) do { _Pragma("unroll") for (int n = 0; n < 2; ++n) _Pragma("unroll") for (int k = 0; k < 2; ++k) dst[n][k] = *(const LAS bf16x8*)(lds + PG8_SB(b, h) + boff + n * 2048 + k * 1024); } while (0)
; #define PG8_MMA(ai, bj, At, Bt) do { __builtin_amdgcn_s_setprio(1); _Pragma("unroll") for (int m = 0; m < 4; ++m) _Pragma("unroll") for (int n = 0; n < 2; ++n) _Pragma("unroll") for (int k = 0; k < 2; ++k) \
;         acc[ai][bj][m][n] = __builtin_amdgcn_mfma_f32_16x16x32_bf16(Bt[n][k], At[m][k], acc[ai][bj][m][n], 0, 0, 0); __builtin_amdgcn_s_setprio(0); } while (0)
; #define PG8_WAIT_V(n) asm volatile("s_waitcnt vmcnt(" #n ")" ::: "memory")
; #define PG8_WAIT_L(n) asm volatile("s_waitcnt lgkmcnt(" #n ")" ::: "memory")
; #define PG8_BAR __builtin_amdgcn_s_barrier()
; #define PG8_SCHED __builtin_amdgcn_sched_barrier(0)
; template <int MODE>
; __device__ __forceinline__ void gemm_phase(LAS unsigned char* lds, const Params& p, int l, int single) {
;     ...
;             PG8_LDB(B0, 0, 0); PG8_SCHED; PG8_LDA(At, 0, 0); PG8_STAGE(PG8_SA(1, 1), a1 + hstep, voffA);
;             PG8_WAIT_L(8); PG8_BAR; PG8_WAIT_L(0); PG8_MMA(0, 0, At, B0); PG8_BAR; PG8_SCHED;
;             PG8_LDB(B1, 0, 1); PG8_STAGE(PG8_SB(0, 0), b2, voffB);
;             PG8_BAR; PG8_WAIT_L(0); PG8_MMA(0, 1, At, B1); PG8_BAR;
;             PG8_LDA(At, 0, 1); PG8_STAGE(PG8_SA(0, 0), a2, voffA);
;             PG8_BAR; PG8_WAIT_L(0); PG8_MMA(1, 0, At, B0); PG8_BAR; PG8_SCHED;
;             PG8_STAGE(PG8_SB(0, 1), b2 + hstep, voffB);
;             PG8_WAIT_V(6); PG8_BAR; PG8_MMA(1, 1, At, B1); PG8_BAR;
.LBB0_643:
	s_add_u32 s20, s33, s38
	s_addc_u32 s21, s78, s39
	s_add_u32 s20, s20, 0x2d58c100
	s_addc_u32 s21, s21, 0
	s_add_u32 s90, s79, s38
	s_addc_u32 s93, s84, s39
	s_add_i32 s96, 0, 0x10000
	v_add_u32_e32 v142, s96, v155
	ds_read_b128 v[158:161], v142
	ds_read_b128 v[162:165], v142 offset:1024
	ds_read_b128 v[166:169], v142 offset:2048
	ds_read_b128 v[170:173], v142 offset:3072
	s_cmpk_eq_i32 s38, 0xf00
	s_cselect_b32 s41, s19, s21
	s_cselect_b32 s40, s18, s20
	s_cselect_b32 s21, s17, s93
	s_cselect_b32 s20, s16, s90
	v_lshl_add_u64 v[142:143], v[150:151], 0, s[38:39]
	s_add_i32 m0, s7, 0xc000
	ds_read_b128 v[174:177], v156
	ds_read_b128 v[178:181], v156 offset:1024
	ds_read_b128 v[182:185], v156 offset:2048
	ds_read_b128 v[186:189], v156 offset:3072
	ds_read_b128 v[190:193], v156 offset:4096
	ds_read_b128 v[194:197], v156 offset:5120
	ds_read_b128 v[208:211], v156 offset:6144
	ds_read_b128 v[212:215], v156 offset:7168
	global_load_lds_dwordx4 v[142:143], off
	v_lshl_add_u64 v[142:143], v[152:153], 0, s[38:39]
	s_add_i32 m0, s7, 0xe000
	s_nop 0
	global_load_lds_dwordx4 v[142:143], off
	s_waitcnt lgkmcnt(8)
	s_barrier
	s_waitcnt lgkmcnt(0)
	s_setprio 1
	s_waitcnt lgkmcnt(0)
	v_mfma_f32_16x16x32_bf16 v[126:129], v[158:161], v[174:177], v[126:129]
	v_mfma_f32_16x16x32_bf16 v[122:125], v[166:169], v[174:177], v[122:125]
	v_mfma_f32_16x16x32_bf16 v[110:113], v[158:161], v[182:185], v[110:113]
	v_mfma_f32_16x16x32_bf16 v[106:109], v[166:169], v[182:185], v[106:109]
	v_mfma_f32_16x16x32_bf16 v[94:97], v[158:161], v[190:193], v[94:97]
	v_mfma_f32_16x16x32_bf16 v[90:93], v[166:169], v[190:193], v[90:93]
	v_mfma_f32_16x16x32_bf16 v[78:81], v[158:161], v[208:211], v[78:81]
	v_mfma_f32_16x16x32_bf16 v[74:77], v[166:169], v[208:211], v[74:77]
	v_mfma_f32_16x16x32_bf16 v[126:129], v[162:165], v[178:181], v[126:129]
	v_mfma_f32_16x16x32_bf16 v[122:125], v[170:173], v[178:181], v[122:125]
	v_mfma_f32_16x16x32_bf16 v[110:113], v[162:165], v[186:189], v[110:113]
	v_mfma_f32_16x16x32_bf16 v[106:109], v[170:173], v[186:189], v[106:109]
	v_mfma_f32_16x16x32_bf16 v[94:97], v[162:165], v[194:197], v[94:97]
	v_mfma_f32_16x16x32_bf16 v[90:93], v[170:173], v[194:197], v[90:93]
	v_mfma_f32_16x16x32_bf16 v[78:81], v[162:165], v[212:215], v[78:81]
	v_mfma_f32_16x16x32_bf16 v[74:77], v[170:173], v[212:215], v[74:77]
	s_setprio 0
	s_barrier
	s_add_i32 s90, 0, 0x14000
	v_add_u32_e32 v142, s90, v155
	s_add_i32 s93, s96, s2
	ds_read_b128 v[216:219], v142
	ds_read_b128 v[220:223], v142 offset:1024
	ds_read_b128 v[224:227], v142 offset:2048
	ds_read_b128 v[228:231], v142 offset:3072
	v_lshl_add_u64 v[142:143], s[20:21], 0, v[0:1]
	s_mov_b32 m0, s93
	v_lshl_add_u64 v[198:199], s[20:21], 0, v[146:147]
	global_load_lds_dwordx4 v[142:143], off
	s_add_i32 m0, s93, 0x2000
	s_nop 0
	global_load_lds_dwordx4 v[198:199], off
	s_barrier
	s_waitcnt lgkmcnt(0)
	s_setprio 1
	s_waitcnt lgkmcnt(0)
	v_mfma_f32_16x16x32_bf16 v[118:121], v[216:219], v[174:177], v[118:121]
	v_mfma_f32_16x16x32_bf16 v[114:117], v[224:227], v[174:177], v[114:117]
	v_mfma_f32_16x16x32_bf16 v[102:105], v[216:219], v[182:185], v[102:105]
	v_mfma_f32_16x16x32_bf16 v[98:101], v[224:227], v[182:185], v[98:101]
	v_mfma_f32_16x16x32_bf16 v[86:89], v[216:219], v[190:193], v[86:89]
	v_mfma_f32_16x16x32_bf16 v[82:85], v[224:227], v[190:193], v[82:85]
	v_mfma_f32_16x16x32_bf16 v[70:73], v[216:219], v[208:211], v[70:73]
	v_mfma_f32_16x16x32_bf16 v[66:69], v[224:227], v[208:211], v[66:69]
	v_mfma_f32_16x16x32_bf16 v[118:121], v[220:223], v[178:181], v[118:121]
	v_mfma_f32_16x16x32_bf16 v[114:117], v[228:231], v[178:181], v[114:117]
	v_mfma_f32_16x16x32_bf16 v[102:105], v[220:223], v[186:189], v[102:105]
	v_mfma_f32_16x16x32_bf16 v[98:101], v[228:231], v[186:189], v[98:101]
	v_mfma_f32_16x16x32_bf16 v[86:89], v[220:223], v[194:197], v[86:89]
	v_mfma_f32_16x16x32_bf16 v[82:85], v[228:231], v[194:197], v[82:85]
	v_mfma_f32_16x16x32_bf16 v[70:73], v[220:223], v[212:215], v[70:73]
	v_mfma_f32_16x16x32_bf16 v[66:69], v[228:231], v[212:215], v[66:69]
	s_setprio 0
	s_mov_b32 m0, s7
	v_lshl_add_u64 v[232:233], s[40:41], 0, v[130:131]
	s_barrier
	ds_read_b128 v[174:177], v156 offset:16384
	ds_read_b128 v[178:181], v156 offset:17408
	ds_read_b128 v[182:185], v156 offset:18432
	ds_read_b128 v[186:189], v156 offset:19456
	ds_read_b128 v[190:193], v156 offset:20480
	ds_read_b128 v[194:197], v156 offset:21504
	ds_read_b128 v[208:211], v156 offset:22528
	ds_read_b128 v[212:215], v156 offset:23552
	global_load_lds_dwordx4 v[232:233], off
	v_lshl_add_u64 v[234:235], s[40:41], 0, v[132:133]
	s_mov_b32 m0, s10
	s_nop 0
	global_load_lds_dwordx4 v[234:235], off
	s_barrier
	s_waitcnt lgkmcnt(0)
	s_setprio 1
	s_waitcnt lgkmcnt(0)
	v_mfma_f32_16x16x32_bf16 v[62:65], v[158:161], v[174:177], v[62:65]
	v_mfma_f32_16x16x32_bf16 v[58:61], v[166:169], v[174:177], v[58:61]
	v_mfma_f32_16x16x32_bf16 v[46:49], v[158:161], v[182:185], v[46:49]
	v_mfma_f32_16x16x32_bf16 v[42:45], v[166:169], v[182:185], v[42:45]
	v_mfma_f32_16x16x32_bf16 v[30:33], v[158:161], v[190:193], v[30:33]
	v_mfma_f32_16x16x32_bf16 v[26:29], v[166:169], v[190:193], v[26:29]
	v_mfma_f32_16x16x32_bf16 v[14:17], v[158:161], v[208:211], v[14:17]
	v_mfma_f32_16x16x32_bf16 v[10:13], v[166:169], v[208:211], v[10:13]
	v_mfma_f32_16x16x32_bf16 v[62:65], v[162:165], v[178:181], v[62:65]
	v_mfma_f32_16x16x32_bf16 v[58:61], v[170:173], v[178:181], v[58:61]
	v_mfma_f32_16x16x32_bf16 v[46:49], v[162:165], v[186:189], v[46:49]
	v_mfma_f32_16x16x32_bf16 v[42:45], v[170:173], v[186:189], v[42:45]
	v_mfma_f32_16x16x32_bf16 v[30:33], v[162:165], v[194:197], v[30:33]
	v_mfma_f32_16x16x32_bf16 v[26:29], v[170:173], v[194:197], v[26:29]
	v_mfma_f32_16x16x32_bf16 v[14:17], v[162:165], v[212:215], v[14:17]
	v_mfma_f32_16x16x32_bf16 v[10:13], v[170:173], v[212:215], v[10:13]
	s_setprio 0
	s_barrier
; #define PG8_STAGE(bufoff, gbase, voff) do { _Pragma("unroll") for (int _i = 0; _i < 2; ++_i) \
;         __builtin_amdgcn_global_load_lds((const unsigned*)((const char*)(gbase) + (voff)[_i]), (LAS unsigned*)(lds + (bufoff) + ldsw + _i * 8192), 16, 0, 0); } while (0)
; #define PG8_LDA(dst, b, h) do { _Pragma("unroll") for (int m = 0; m < 4; ++m) _Pragma("unroll") for (int k = 0; k < 2; ++k) dst[m][k] = *(const LAS bf16x8*)(lds + PG8_SA(b, h) + aoff + m * 2048 + k * 1024); } while (0)
; #define PG8_LDB(dst, b, h) do { _Pragma("unroll") for (int n = 0; n < 2; ++n) _Pragma("unroll") for (int k = 0; k < 2; ++k) dst[n][k] = *(const LAS bf16x8*)(lds + PG8_SB(b, h) + boff + n * 2048 + k * 1024); } while (0)
; #define PG8_MMA(ai, bj, At, Bt) do { __builtin_amdgcn_s_setprio(1); _Pragma("unroll") for (int m = 0; m < 4; ++m) _Pragma("unroll") for (int n = 0; n < 2; ++n) _Pragma("unroll") for (int k = 0; k < 2; ++k) \
;         acc[ai][bj][m][n] = __builtin_amdgcn_mfma_f32_16x16x32_bf16(Bt[n][k], At[m][k], acc[ai][bj][m][n], 0, 0, 0); __builtin_amdgcn_s_setprio(0); } while (0)
; #define PG8_WAIT_V(n) asm volatile("s_waitcnt vmcnt(" #n ")" ::: "memory")
; #define PG8_WAIT_L(n) asm volatile("s_waitcnt lgkmcnt(" #n ")" ::: "memory")
; #define PG8_BAR __builtin_amdgcn_s_barrier()
; #define PG8_SCHED __builtin_amdgcn_sched_barrier(0)
; template <int MODE>
; __device__ __forceinline__ void gemm_phase(LAS unsigned char* lds, const Params& p, int l, int single) {
;     ...
;             PG8_WAIT_V(6); PG8_BAR; PG8_MMA(1, 1, At, B1); PG8_BAR;
;             PG8_LDB(B0, 1, 0); PG8_SCHED; PG8_LDA(At, 1, 0); PG8_STAGE(PG8_SA(0, 1), a2 + hstep, voffA);
;             PG8_WAIT_L(8); PG8_BAR; PG8_WAIT_L(0); PG8_MMA(0, 0, At, B0); PG8_BAR; PG8_SCHED;
;             PG8_LDB(B1, 1, 1); PG8_STAGE(PG8_SB(1, 0), b3, voffB);
;             PG8_BAR; PG8_WAIT_L(0); PG8_MMA(0, 1, At, B1); PG8_BAR;
;             PG8_LDA(At, 1, 1); PG8_STAGE(PG8_SA(1, 0), a3, voffA);
;             PG8_BAR; PG8_WAIT_L(0); PG8_MMA(1, 0, At, B0); PG8_BAR; PG8_SCHED;
;             PG8_STAGE(PG8_SB(1, 1), b3 + hstep, voffB);
;             PG8_WAIT_V(6); PG8_BAR; PG8_MMA(1, 1, At, B1); PG8_BAR;
	s_add_u32 s96, s20, 0x80000
	s_addc_u32 s97, s21, 0
	s_add_i32 s90, s90, s2
	v_lshl_add_u64 v[158:159], s[96:97], 0, v[0:1]
	s_mov_b32 m0, s90
	s_nop 0
	global_load_lds_dwordx4 v[158:159], off
	v_lshl_add_u64 v[158:159], s[96:97], 0, v[146:147]
	s_add_i32 m0, s90, 0x2000
	s_nop 0
	global_load_lds_dwordx4 v[158:159], off
	s_waitcnt vmcnt(6)
	s_barrier
	s_setprio 1
	v_mfma_f32_16x16x32_bf16 v[54:57], v[216:219], v[174:177], v[54:57]
	v_mfma_f32_16x16x32_bf16 v[50:53], v[224:227], v[174:177], v[50:53]
	v_mfma_f32_16x16x32_bf16 v[38:41], v[216:219], v[182:185], v[38:41]
	v_mfma_f32_16x16x32_bf16 v[34:37], v[224:227], v[182:185], v[34:37]
	v_mfma_f32_16x16x32_bf16 v[22:25], v[216:219], v[190:193], v[22:25]
	v_mfma_f32_16x16x32_bf16 v[18:21], v[224:227], v[190:193], v[18:21]
	v_mfma_f32_16x16x32_bf16 v[6:9], v[216:219], v[208:211], v[6:9]
	v_mfma_f32_16x16x32_bf16 v[2:5], v[224:227], v[208:211], v[2:5]
	v_mfma_f32_16x16x32_bf16 v[54:57], v[220:223], v[178:181], v[54:57]
	v_mfma_f32_16x16x32_bf16 v[50:53], v[228:231], v[178:181], v[50:53]
	v_mfma_f32_16x16x32_bf16 v[38:41], v[220:223], v[186:189], v[38:41]
	v_mfma_f32_16x16x32_bf16 v[34:37], v[228:231], v[186:189], v[34:37]
	v_mfma_f32_16x16x32_bf16 v[22:25], v[220:223], v[194:197], v[22:25]
	v_mfma_f32_16x16x32_bf16 v[18:21], v[228:231], v[194:197], v[18:21]
	v_mfma_f32_16x16x32_bf16 v[6:9], v[220:223], v[212:215], v[6:9]
	v_mfma_f32_16x16x32_bf16 v[2:5], v[228:231], v[212:215], v[2:5]
	s_setprio 0
	s_add_i32 s90, 0, 0x18000
	v_add_u32_e32 v157, s90, v155
	s_barrier
	ds_read_b128 v[158:161], v157
	ds_read_b128 v[162:165], v157 offset:1024
	ds_read_b128 v[166:169], v157 offset:2048
	ds_read_b128 v[170:173], v157 offset:3072
	s_add_u32 s40, s40, 0x80000
	s_addc_u32 s41, s41, 0
	s_mov_b32 m0, s24
	v_lshl_add_u64 v[216:217], s[40:41], 0, v[130:131]
	ds_read_b128 v[174:177], v156 offset:32768
	ds_read_b128 v[178:181], v156 offset:33792
	ds_read_b128 v[182:185], v156 offset:34816
	ds_read_b128 v[186:189], v156 offset:35840
	ds_read_b128 v[190:193], v156 offset:36864
	ds_read_b128 v[194:197], v156 offset:37888
	ds_read_b128 v[208:211], v156 offset:38912
	ds_read_b128 v[212:215], v156 offset:39936
	global_load_lds_dwordx4 v[216:217], off
	v_lshl_add_u64 v[216:217], s[40:41], 0, v[132:133]
	s_mov_b32 m0, s25
	s_nop 0
	global_load_lds_dwordx4 v[216:217], off
	s_waitcnt lgkmcnt(8)
	s_barrier
	s_waitcnt lgkmcnt(0)
	s_setprio 1
	s_waitcnt lgkmcnt(0)
	v_mfma_f32_16x16x32_bf16 v[126:129], v[158:161], v[174:177], v[126:129]
	v_mfma_f32_16x16x32_bf16 v[122:125], v[166:169], v[174:177], v[122:125]
	v_mfma_f32_16x16x32_bf16 v[110:113], v[158:161], v[182:185], v[110:113]
	v_mfma_f32_16x16x32_bf16 v[106:109], v[166:169], v[182:185], v[106:109]
	v_mfma_f32_16x16x32_bf16 v[94:97], v[158:161], v[190:193], v[94:97]
	v_mfma_f32_16x16x32_bf16 v[90:93], v[166:169], v[190:193], v[90:93]
	v_mfma_f32_16x16x32_bf16 v[78:81], v[158:161], v[208:211], v[78:81]
	v_mfma_f32_16x16x32_bf16 v[74:77], v[166:169], v[208:211], v[74:77]
	v_mfma_f32_16x16x32_bf16 v[126:129], v[162:165], v[178:181], v[126:129]
	v_mfma_f32_16x16x32_bf16 v[122:125], v[170:173], v[178:181], v[122:125]
	v_mfma_f32_16x16x32_bf16 v[110:113], v[162:165], v[186:189], v[110:113]
	v_mfma_f32_16x16x32_bf16 v[106:109], v[170:173], v[186:189], v[106:109]
	v_mfma_f32_16x16x32_bf16 v[94:97], v[162:165], v[194:197], v[94:97]
	v_mfma_f32_16x16x32_bf16 v[90:93], v[170:173], v[194:197], v[90:93]
	v_mfma_f32_16x16x32_bf16 v[78:81], v[162:165], v[212:215], v[78:81]
	v_mfma_f32_16x16x32_bf16 v[74:77], v[170:173], v[212:215], v[74:77]
	s_setprio 0
	s_barrier
	s_add_i32 s40, 0, 0x1c000
	s_add_i32 s41, s90, s2
	v_add_u32_e32 v157, s40, v155
	v_lshl_add_u64 v[142:143], v[142:143], 0, s[94:95]
	s_mov_b32 m0, s41
	ds_read_b128 v[216:219], v157
	ds_read_b128 v[220:223], v157 offset:1024
	ds_read_b128 v[224:227], v157 offset:2048
	ds_read_b128 v[228:231], v157 offset:3072
	global_load_lds_dwordx4 v[142:143], off
	v_lshl_add_u64 v[142:143], v[198:199], 0, s[94:95]
	s_add_i32 m0, s41, 0x2000
	s_nop 0
	global_load_lds_dwordx4 v[142:143], off
	s_barrier
	s_waitcnt lgkmcnt(0)
	s_setprio 1
	s_waitcnt lgkmcnt(0)
	v_mfma_f32_16x16x32_bf16 v[118:121], v[216:219], v[174:177], v[118:121]
	v_mfma_f32_16x16x32_bf16 v[114:117], v[224:227], v[174:177], v[114:117]
	v_mfma_f32_16x16x32_bf16 v[102:105], v[216:219], v[182:185], v[102:105]
	v_mfma_f32_16x16x32_bf16 v[98:101], v[224:227], v[182:185], v[98:101]
	v_mfma_f32_16x16x32_bf16 v[86:89], v[216:219], v[190:193], v[86:89]
	v_mfma_f32_16x16x32_bf16 v[82:85], v[224:227], v[190:193], v[82:85]
	v_mfma_f32_16x16x32_bf16 v[70:73], v[216:219], v[208:211], v[70:73]
	v_mfma_f32_16x16x32_bf16 v[66:69], v[224:227], v[208:211], v[66:69]
	v_mfma_f32_16x16x32_bf16 v[118:121], v[220:223], v[178:181], v[118:121]
	v_mfma_f32_16x16x32_bf16 v[114:117], v[228:231], v[178:181], v[114:117]
	v_mfma_f32_16x16x32_bf16 v[102:105], v[220:223], v[186:189], v[102:105]
	v_mfma_f32_16x16x32_bf16 v[98:101], v[228:231], v[186:189], v[98:101]
	v_mfma_f32_16x16x32_bf16 v[86:89], v[220:223], v[194:197], v[86:89]
	v_mfma_f32_16x16x32_bf16 v[82:85], v[228:231], v[194:197], v[82:85]
	v_mfma_f32_16x16x32_bf16 v[70:73], v[220:223], v[212:215], v[70:73]
	v_mfma_f32_16x16x32_bf16 v[66:69], v[228:231], v[212:215], v[66:69]
	s_setprio 0
	s_mov_b32 m0, s28
	v_lshl_add_u64 v[142:143], v[232:233], 0, s[94:95]
	s_barrier
	ds_read_b128 v[174:177], v156 offset:49152
	ds_read_b128 v[178:181], v156 offset:50176
	ds_read_b128 v[182:185], v156 offset:51200
	ds_read_b128 v[186:189], v156 offset:52224
	ds_read_b128 v[190:193], v156 offset:53248
	ds_read_b128 v[194:197], v156 offset:54272
	ds_read_b128 v[208:211], v156 offset:55296
	ds_read_b128 v[212:215], v156 offset:56320
	global_load_lds_dwordx4 v[142:143], off
	v_lshl_add_u64 v[142:143], v[234:235], 0, s[94:95]
	s_mov_b32 m0, s29
	s_nop 0
	global_load_lds_dwordx4 v[142:143], off
	s_barrier
; __device__ __forceinline__ float bflo(unsigned w) { return __uint_as_float(w << 16); }
; __device__ __forceinline__ float bfhi(unsigned w) { return __uint_as_float(w & 0xffff0000u); }
; #define PG8_STAGE(bufoff, gbase, voff) do { _Pragma("unroll") for (int _i = 0; _i < 2; ++_i) \
;         __builtin_amdgcn_global_load_lds((const unsigned*)((const char*)(gbase) + (voff)[_i]), (LAS unsigned*)(lds + (bufoff) + ldsw + _i * 8192), 16, 0, 0); } while (0)
; #define PG8_LDA(dst, b, h) do { _Pragma("unroll") for (int m = 0; m < 4; ++m) _Pragma("unroll") for (int k = 0; k < 2; ++k) dst[m][k] = *(const LAS bf16x8*)(lds + PG8_SA(b, h) + aoff + m * 2048 + k * 1024); } while (0)
; #define PG8_WAIT_V(n) asm volatile("s_waitcnt vmcnt(" #n ")" ::: "memory")
; #define PG8_WAIT_L(n) asm volatile("s_waitcnt lgkmcnt(" #n ")" ::: "memory")
; #define PG8_BAR __builtin_amdgcn_s_barrier()
; #define PG8_SCHED __builtin_amdgcn_sched_barrier(0)
; template <int MODE>
; __device__ __forceinline__ void gemm_epilogue(const Params& p, int l, const f32x4 (&acc)[2][2][4][2], const Unit& u, int wr, int wc, int fr, int fq, const LAS float* rl, int pm0) {
;     ...
;         u16* xb = (u16*)(ws + WS_XB);
;         u64* ssn = (u64*)(ws + WS_SUMSQ) + (size_t)(l + 1) * T;
; #pragma unroll
;         for (int ai = 0; ai < 2; ++ai)
; #pragma unroll
;             for (int m = 0; m < 4; ++m) {
;                 const int tok = u.pm * 256 + 128 * ai + 64 * wr + 16 * m + fr;
;                 float part = 0.f;
; #pragma unroll
;                 for (int bj = 0; bj < 2; ++bj) {
;                     const size_t idx = (size_t)tok * 2048 + u.pn * 256 + 128 * bj + 32 * wc + 8 * fq;
;                     const u32x4 xw = *(const u32x4*)(xb + idx);
;                     f32x4 y0 = (f32x4){bflo(xw.x), bfhi(xw.x), bflo(xw.y), bfhi(xw.y)}, y1 = (f32x4){bflo(xw.z), bfhi(xw.z), bflo(xw.w), bfhi(xw.w)};
;                     y0 += acc[ai][bj][m][0]; y1 += acc[ai][bj][m][1];
; template <int MODE>
; __device__ __forceinline__ void gemm_phase(LAS unsigned char* lds, const Params& p, int l, int single) {
;     ...
;             PG8_LDA(At, 1, 1); PG8_STAGE(PG8_SA(1, 0), a3, voffA);
;             PG8_BAR; PG8_WAIT_L(0); PG8_MMA(1, 0, At, B0); PG8_BAR; PG8_SCHED;
;             PG8_STAGE(PG8_SB(1, 1), b3 + hstep, voffB);
;             PG8_WAIT_V(6); PG8_BAR; PG8_MMA(1, 1, At, B1); PG8_BAR;
	s_waitcnt lgkmcnt(0)
	s_setprio 1
	s_waitcnt lgkmcnt(0)
	v_mfma_f32_16x16x32_bf16 v[62:65], v[158:161], v[174:177], v[62:65]
	v_mfma_f32_16x16x32_bf16 v[58:61], v[166:169], v[174:177], v[58:61]
	v_mfma_f32_16x16x32_bf16 v[46:49], v[158:161], v[182:185], v[46:49]
	v_mfma_f32_16x16x32_bf16 v[42:45], v[166:169], v[182:185], v[42:45]
	v_mfma_f32_16x16x32_bf16 v[30:33], v[158:161], v[190:193], v[30:33]
	v_mfma_f32_16x16x32_bf16 v[26:29], v[166:169], v[190:193], v[26:29]
	v_mfma_f32_16x16x32_bf16 v[14:17], v[158:161], v[208:211], v[14:17]
	v_mfma_f32_16x16x32_bf16 v[10:13], v[166:169], v[208:211], v[10:13]
	v_mfma_f32_16x16x32_bf16 v[62:65], v[162:165], v[178:181], v[62:65]
	v_mfma_f32_16x16x32_bf16 v[58:61], v[170:173], v[178:181], v[58:61]
	v_mfma_f32_16x16x32_bf16 v[46:49], v[162:165], v[186:189], v[46:49]
	v_mfma_f32_16x16x32_bf16 v[42:45], v[170:173], v[186:189], v[42:45]
	v_mfma_f32_16x16x32_bf16 v[30:33], v[162:165], v[194:197], v[30:33]
	v_mfma_f32_16x16x32_bf16 v[26:29], v[170:173], v[194:197], v[26:29]
	v_mfma_f32_16x16x32_bf16 v[14:17], v[162:165], v[212:215], v[14:17]
	v_mfma_f32_16x16x32_bf16 v[10:13], v[170:173], v[212:215], v[10:13]
	s_setprio 0
	s_barrier
	s_add_u32 s20, s20, 0x80080
	s_addc_u32 s21, s21, 0
	s_add_i32 s40, s40, s2
	v_lshl_add_u64 v[142:143], s[20:21], 0, v[0:1]
	s_mov_b32 m0, s40
	s_nop 0
	global_load_lds_dwordx4 v[142:143], off
	v_lshl_add_u64 v[142:143], s[20:21], 0, v[146:147]
	s_add_i32 m0, s40, 0x2000
	s_nop 0
	global_load_lds_dwordx4 v[142:143], off
	s_waitcnt vmcnt(6)
	s_barrier
	s_setprio 1
	v_mfma_f32_16x16x32_bf16 v[54:57], v[216:219], v[174:177], v[54:57]
	v_mfma_f32_16x16x32_bf16 v[50:53], v[224:227], v[174:177], v[50:53]
	v_mfma_f32_16x16x32_bf16 v[38:41], v[216:219], v[182:185], v[38:41]
	v_mfma_f32_16x16x32_bf16 v[34:37], v[224:227], v[182:185], v[34:37]
	v_mfma_f32_16x16x32_bf16 v[22:25], v[216:219], v[190:193], v[22:25]
	v_mfma_f32_16x16x32_bf16 v[18:21], v[224:227], v[190:193], v[18:21]
	v_mfma_f32_16x16x32_bf16 v[6:9], v[216:219], v[208:211], v[6:9]
	v_mfma_f32_16x16x32_bf16 v[2:5], v[224:227], v[208:211], v[2:5]
	v_mfma_f32_16x16x32_bf16 v[54:57], v[220:223], v[178:181], v[54:57]
	v_mfma_f32_16x16x32_bf16 v[50:53], v[228:231], v[178:181], v[50:53]
	v_mfma_f32_16x16x32_bf16 v[38:41], v[220:223], v[186:189], v[38:41]
	v_mfma_f32_16x16x32_bf16 v[34:37], v[228:231], v[186:189], v[34:37]
	v_mfma_f32_16x16x32_bf16 v[22:25], v[220:223], v[194:197], v[22:25]
	v_mfma_f32_16x16x32_bf16 v[18:21], v[228:231], v[194:197], v[18:21]
	v_mfma_f32_16x16x32_bf16 v[6:9], v[220:223], v[212:215], v[6:9]
	v_mfma_f32_16x16x32_bf16 v[2:5], v[228:231], v[212:215], v[2:5]
	s_setprio 0
	s_add_i32 s85, s85, 2
	s_add_u32 s38, s38, 0x100
	s_addc_u32 s39, s39, 0
	s_cmp_gt_u32 s85, 29
	s_barrier
	s_cbranch_scc0 .LBB0_643
	s_add_i32 s0, s0, 1
	s_mul_hi_i32 s2, s0, 0x21000
	s_mul_i32 s0, s0, 0x21000
	s_add_u32 s16, s80, s0
	s_addc_u32 s17, s81, s2
	s_lshl_b32 s2, s1, 8
	s_lshl_b32 s0, s1, 9
	s_add_u32 s0, s52, s0
	s_addc_u32 s1, s53, 0
	s_lshl_b32 s7, s11, 1
	v_lshl_add_u32 v130, s76, 8, v149
	s_add_u32 s0, s0, s7
	s_addc_u32 s1, s1, 0
	v_mov_b32_e32 v149, v1
	v_ashrrev_i32_e32 v131, 31, v130
	v_lshl_add_u64 v[132:133], s[0:1], 0, v[148:149]
	v_mov_b32_e32 v162, v130
	v_ashrrev_i32_e32 v163, 31, v162
	v_lshlrev_b64 v[162:163], 12, v[162:163]
	v_lshl_add_u64 v[162:163], v[132:133], 0, v[162:163]
	global_load_dwordx4 v[158:161], v[162:163], off
	global_load_dwordx4 v[162:165], v[162:163], off offset:256
	v_add_u32_e32 v170, 0x10, v130
	v_ashrrev_i32_e32 v171, 31, v170
	v_lshlrev_b64 v[170:171], 12, v[170:171]
	v_lshl_add_u64 v[170:171], v[132:133], 0, v[170:171]
	global_load_dwordx4 v[166:169], v[170:171], off
	global_load_dwordx4 v[170:173], v[170:171], off offset:256
	v_add_u32_e32 v178, 0x20, v130
	v_ashrrev_i32_e32 v179, 31, v178
	v_lshlrev_b64 v[178:179], 12, v[178:179]
	v_lshl_add_u64 v[178:179], v[132:133], 0, v[178:179]
	global_load_dwordx4 v[174:177], v[178:179], off
	global_load_dwordx4 v[178:181], v[178:179], off offset:256
	v_add_u32_e32 v186, 0x30, v130
	v_ashrrev_i32_e32 v187, 31, v186
	v_lshlrev_b64 v[186:187], 12, v[186:187]
	v_lshl_add_u64 v[186:187], v[132:133], 0, v[186:187]
	global_load_dwordx4 v[182:185], v[186:187], off
	global_load_dwordx4 v[186:189], v[186:187], off offset:256
	v_add_u32_e32 v194, 0x80, v130
	v_ashrrev_i32_e32 v195, 31, v194
	v_lshlrev_b64 v[194:195], 12, v[194:195]
	v_lshl_add_u64 v[194:195], v[132:133], 0, v[194:195]
	global_load_dwordx4 v[190:193], v[194:195], off
	global_load_dwordx4 v[194:197], v[194:195], off offset:256
	v_add_u32_e32 v212, 0x90, v130
	v_ashrrev_i32_e32 v213, 31, v212
	v_lshlrev_b64 v[212:213], 12, v[212:213]
	v_lshl_add_u64 v[212:213], v[132:133], 0, v[212:213]
	global_load_dwordx4 v[208:211], v[212:213], off
	global_load_dwordx4 v[212:215], v[212:213], off offset:256
	v_add_u32_e32 v220, 0xa0, v130
	v_ashrrev_i32_e32 v221, 31, v220
	v_lshlrev_b64 v[220:221], 12, v[220:221]
	v_lshl_add_u64 v[220:221], v[132:133], 0, v[220:221]
	global_load_dwordx4 v[216:219], v[220:221], off
	global_load_dwordx4 v[220:223], v[220:221], off offset:256
	v_add_u32_e32 v228, 0xb0, v130
	v_ashrrev_i32_e32 v229, 31, v228
	v_lshlrev_b64 v[228:229], 12, v[228:229]
	v_lshl_add_u64 v[228:229], v[132:133], 0, v[228:229]
	global_load_dwordx4 v[224:227], v[228:229], off
	global_load_dwordx4 v[228:231], v[228:229], off offset:256
	v_lshlrev_b64 v[142:143], 12, v[130:131]
	v_lshl_add_u64 v[152:153], v[132:133], 0, v[142:143]
	v_lshl_or_b32 v0, v154, 3, s2
	v_or_b32_e32 v0, s11, v0
	v_add_u32_e32 v146, 0x10800000, v142
	v_lshlrev_b32_e32 v0, 1, v0
	v_or_b32_e32 v147, v146, v0
	v_cmp_eq_u32_e32 vcc, 0, v154
	s_waitcnt vmcnt(15)
; __device__ __forceinline__ unsigned cvt_pk_bf16(float lo, float hi) { unsigned r; asm("v_cvt_pk_bf16_f32 %0, %1, %2" : "=v"(r) : "v"(lo), "v"(hi)); return r; }
; __device__ __forceinline__ float bflo(unsigned w) { return __uint_as_float(w << 16); }
; __device__ __forceinline__ float bfhi(unsigned w) { return __uint_as_float(w & 0xffff0000u); }
; #define WT_STORE16(ptr, val) __builtin_amdgcn_raw_buffer_store_b128((val), wsr, (int)((const char*)(ptr) - (const char*)ws), 0, 16)
; template <int MODE>
; __device__ __forceinline__ void gemm_epilogue(const Params& p, int l, const f32x4 (&acc)[2][2][4][2], const Unit& u, int wr, int wc, int fr, int fq, const LAS float* rl, int pm0) {
;     ...
; #pragma unroll
;         for (int ai = 0; ai < 2; ++ai)
; #pragma unroll
;             for (int m = 0; m < 4; ++m) {
;                 const int tok = u.pm * 256 + 128 * ai + 64 * wr + 16 * m + fr;
;                 float part = 0.f;
; #pragma unroll
;                 for (int bj = 0; bj < 2; ++bj) {
;                     const size_t idx = (size_t)tok * 2048 + u.pn * 256 + 128 * bj + 32 * wc + 8 * fq;
;                     const u32x4 xw = *(const u32x4*)(xb + idx);
;                     f32x4 y0 = (f32x4){bflo(xw.x), bfhi(xw.x), bflo(xw.y), bfhi(xw.y)}, y1 = (f32x4){bflo(xw.z), bfhi(xw.z), bflo(xw.w), bfhi(xw.w)};
;                     y0 += acc[ai][bj][m][0]; y1 += acc[ai][bj][m][1];
;                     part += y0[0] * y0[0] + y0[1] * y0[1] + y0[2] * y0[2] + y0[3] * y0[3] + y1[0] * y1[0] + y1[1] * y1[1] + y1[2] * y1[2] + y1[3] * y1[3];
;                     u32x4 w; w.x = cvt_pk_bf16(y0[0], y0[1]); w.y = cvt_pk_bf16(y0[2], y0[3]); w.z = cvt_pk_bf16(y1[0], y1[1]); w.w = cvt_pk_bf16(y1[2], y1[3]);
;                     WT_STORE16(xb + idx, w);
;                 }
;                 part += __shfl_xor(part, 16); part += __shfl_xor(part, 32);
;                 if (fq == 0) atomicAdd(ssn + tok, (u64)(part * SS_SCALE));
;             }
	v_mov_b32_e32 v148, v158
	v_mov_b32_e32 v149, v159
	v_mov_b32_e32 v150, v160
	v_mov_b32_e32 v151, v161
	v_lshlrev_b32_e32 v142, 16, v148
	v_and_b32_e32 v143, 0xffff0000, v148
	v_lshlrev_b32_e32 v148, 16, v149
	v_and_b32_e32 v149, 0xffff0000, v149
	v_lshlrev_b32_e32 v156, 16, v150
	v_and_b32_e32 v157, 0xffff0000, v150
	v_lshlrev_b32_e32 v150, 16, v151
	v_and_b32_e32 v151, 0xffff0000, v151
	v_pk_add_f32 v[128:129], v[128:129], v[148:149]
	v_pk_add_f32 v[142:143], v[126:127], v[142:143]
	v_pk_add_f32 v[124:125], v[124:125], v[150:151]
	v_pk_add_f32 v[122:123], v[122:123], v[156:157]
	v_cvt_pk_bf16_f32 v148, v142, v143
	v_cvt_pk_bf16_f32 v149, v128, v129
	v_cvt_pk_bf16_f32 v151, v124, v125
	v_and_b32_e32 v127, 64, v205
	v_cvt_pk_bf16_f32 v150, v122, v123
	buffer_store_dwordx4 v[148:151], v147, s[60:63], 0 offen
	v_xor_b32_e32 v126, 16, v205
	v_add_u32_e32 v127, 64, v127
	v_xor_b32_e32 v147, 32, v205
	v_cmp_lt_i32_e64 s[0:1], v126, v127
	s_nop 1
	v_cndmask_b32_e64 v126, v205, v126, s[0:1]
	v_cmp_lt_i32_e64 s[0:1], v147, v127
	v_lshlrev_b32_e32 v126, 2, v126
	s_nop 0
	v_cndmask_b32_e64 v127, v205, v147, s[0:1]
	v_mul_f32_e32 v147, v143, v143
	v_fmac_f32_e32 v147, v142, v142
	v_fmac_f32_e32 v147, v128, v128
	v_fmac_f32_e32 v147, v129, v129
	v_fmac_f32_e32 v147, v122, v122
	v_fmac_f32_e32 v147, v123, v123
	v_fmac_f32_e32 v147, v124, v124
	v_fmac_f32_e32 v147, v125, v125
	s_waitcnt vmcnt(15)
	v_mov_b32_e32 v148, v162
	v_mov_b32_e32 v149, v163
	v_mov_b32_e32 v150, v164
	v_mov_b32_e32 v151, v165
	v_lshlrev_b32_e32 v122, 16, v148
	v_and_b32_e32 v123, 0xffff0000, v148
	v_lshlrev_b32_e32 v124, 16, v149
	v_and_b32_e32 v125, 0xffff0000, v149
	v_pk_add_f32 v[118:119], v[118:119], v[122:123]
	v_pk_add_f32 v[124:125], v[120:121], v[124:125]
	v_mul_f32_e32 v120, v119, v119
	v_fmac_f32_e32 v120, v118, v118
	v_lshlrev_b32_e32 v128, 16, v150
	v_and_b32_e32 v129, 0xffff0000, v150
	v_fmac_f32_e32 v120, v124, v124
	v_pk_add_f32 v[114:115], v[114:115], v[128:129]
	v_fmac_f32_e32 v120, v125, v125
	v_lshlrev_b32_e32 v142, 16, v151
	v_and_b32_e32 v143, 0xffff0000, v151
	v_fmac_f32_e32 v120, v114, v114
	v_pk_add_f32 v[116:117], v[116:117], v[142:143]
	v_fmac_f32_e32 v120, v115, v115
	v_fmac_f32_e32 v120, v116, v116
	v_fmac_f32_e32 v120, v117, v117
	v_add_f32_e32 v128, v147, v120
	ds_bpermute_b32 v129, v126, v128
	v_cvt_pk_bf16_f32 v120, v118, v119
	v_cvt_pk_bf16_f32 v123, v116, v117
	v_lshlrev_b32_e32 v117, 2, v127
	v_or_b32_e32 v116, 0x100, v0
	s_waitcnt lgkmcnt(0)
	v_add_f32_e32 v118, v128, v129
	ds_bpermute_b32 v119, v117, v118
	v_cvt_pk_bf16_f32 v122, v114, v115
	v_or_b32_e32 v114, v116, v146
	v_cvt_pk_bf16_f32 v121, v124, v125
	buffer_store_dwordx4 v[120:123], v114, s[60:63], 0 offen
	v_lshl_add_u64 v[114:115], v[130:131], 3, s[16:17]
	s_and_saveexec_b64 s[0:1], vcc
	s_cbranch_execz .LBB0_646
	s_waitcnt lgkmcnt(0)
	v_add_f32_e32 v118, v118, v119
	v_mul_f32_e32 v118, 0x49800000, v118
	v_trunc_f32_e32 v118, v118
	v_mul_f32_e32 v119, 0x2f800000, v118
	v_floor_f32_e32 v119, v119
	v_fmac_f32_e32 v118, 0xcf800000, v119
	v_cvt_u32_f32_e32 v118, v118
	v_cvt_u32_f32_e32 v119, v119
	global_atomic_add_x2 v[114:115], v[118:119], off
.LBB0_646:
	s_or_b64 exec, exec, s[0:1]
	v_or_b32_e32 v118, 16, v130
	s_waitcnt lgkmcnt(0)
	v_ashrrev_i32_e32 v119, 31, v118
	v_lshlrev_b64 v[118:119], 12, v[118:119]
	v_lshl_add_u64 v[122:123], v[132:133], 0, v[118:119]
	v_add_u32_e32 v127, 0x10800000, v118
	s_waitcnt vmcnt(15)
	v_mov_b32_e32 v118, v166
	v_mov_b32_e32 v119, v167
	v_mov_b32_e32 v120, v168
	v_mov_b32_e32 v121, v169
	v_lshlrev_b32_e32 v124, 16, v118
	v_and_b32_e32 v125, 0xffff0000, v118
	v_lshlrev_b32_e32 v118, 16, v119
	v_and_b32_e32 v119, 0xffff0000, v119
	v_lshlrev_b32_e32 v128, 16, v120
	v_and_b32_e32 v129, 0xffff0000, v120
	v_lshlrev_b32_e32 v120, 16, v121
	v_and_b32_e32 v121, 0xffff0000, v121
	v_pk_add_f32 v[110:111], v[110:111], v[124:125]
	v_pk_add_f32 v[112:113], v[112:113], v[118:119]
	v_pk_add_f32 v[118:119], v[108:109], v[120:121]
	v_mul_f32_e32 v120, v111, v111
	v_fmac_f32_e32 v120, v110, v110
	v_fmac_f32_e32 v120, v112, v112
	v_pk_add_f32 v[108:109], v[106:107], v[128:129]
	v_fmac_f32_e32 v120, v113, v113
	v_fmac_f32_e32 v120, v108, v108
	v_cvt_pk_bf16_f32 v106, v110, v111
	v_or_b32_e32 v110, v127, v0
	v_fmac_f32_e32 v120, v109, v109
	v_cvt_pk_bf16_f32 v107, v112, v113
	v_cvt_pk_bf16_f32 v108, v108, v109
	v_cvt_pk_bf16_f32 v109, v118, v119
	buffer_store_dwordx4 v[106:109], v110, s[60:63], 0 offen
	v_fmac_f32_e32 v120, v118, v118
	v_fmac_f32_e32 v120, v119, v119
	s_waitcnt vmcnt(15)
	v_mov_b32_e32 v106, v170
	v_mov_b32_e32 v107, v171
	v_mov_b32_e32 v108, v172
	v_mov_b32_e32 v109, v173
	v_lshlrev_b32_e32 v110, 16, v106
	v_and_b32_e32 v111, 0xffff0000, v106
	v_lshlrev_b32_e32 v106, 16, v107
	v_and_b32_e32 v107, 0xffff0000, v107
	v_lshlrev_b32_e32 v112, 16, v108
	v_and_b32_e32 v113, 0xffff0000, v108
	v_lshlrev_b32_e32 v108, 16, v109
	v_and_b32_e32 v109, 0xffff0000, v109
	v_pk_add_f32 v[102:103], v[102:103], v[110:111]
	v_pk_add_f32 v[104:105], v[104:105], v[106:107]
	v_pk_add_f32 v[106:107], v[100:101], v[108:109]
	v_pk_add_f32 v[100:101], v[98:99], v[112:113]
	v_mul_f32_e32 v98, v103, v103
	v_fmac_f32_e32 v98, v102, v102
	v_fmac_f32_e32 v98, v104, v104
	v_fmac_f32_e32 v98, v105, v105
	v_fmac_f32_e32 v98, v100, v100
	v_fmac_f32_e32 v98, v101, v101
	v_fmac_f32_e32 v98, v106, v106
	v_fmac_f32_e32 v98, v107, v107
	v_add_f32_e32 v108, v120, v98
	v_cvt_pk_bf16_f32 v98, v102, v103
	v_add_u32_e32 v102, v127, v116
	v_cvt_pk_bf16_f32 v99, v104, v105
	v_cvt_pk_bf16_f32 v100, v100, v101
	v_cvt_pk_bf16_f32 v101, v106, v107
	buffer_store_dwordx4 v[98:101], v102, s[60:63], 0 offen
	ds_bpermute_b32 v98, v126, v108
	s_waitcnt lgkmcnt(0)
	v_add_f32_e32 v98, v108, v98
	ds_bpermute_b32 v99, v117, v98
	s_and_saveexec_b64 s[0:1], vcc
	s_movk_i32 s33, 0x100
	s_cbranch_execz .LBB0_648
	s_waitcnt lgkmcnt(0)
	v_add_f32_e32 v98, v98, v99
	v_mul_f32_e32 v98, 0x49800000, v98
	v_trunc_f32_e32 v98, v98
	v_mul_f32_e32 v99, 0x2f800000, v98
	v_floor_f32_e32 v99, v99
	v_fmac_f32_e32 v98, 0xcf800000, v99
	v_cvt_u32_f32_e32 v98, v98
	v_cvt_u32_f32_e32 v99, v99
	global_atomic_add_x2 v[114:115], v[98:99], off offset:128
; __device__ __forceinline__ unsigned cvt_pk_bf16(float lo, float hi) { unsigned r; asm("v_cvt_pk_bf16_f32 %0, %1, %2" : "=v"(r) : "v"(lo), "v"(hi)); return r; }
; __device__ __forceinline__ float bflo(unsigned w) { return __uint_as_float(w << 16); }
; __device__ __forceinline__ float bfhi(unsigned w) { return __uint_as_float(w & 0xffff0000u); }
; #define WT_STORE16(ptr, val) __builtin_amdgcn_raw_buffer_store_b128((val), wsr, (int)((const char*)(ptr) - (const char*)ws), 0, 16)
; template <int MODE>
; __device__ __forceinline__ void gemm_epilogue(const Params& p, int l, const f32x4 (&acc)[2][2][4][2], const Unit& u, int wr, int wc, int fr, int fq, const LAS float* rl, int pm0) {
;     ...
; #pragma unroll
;         for (int ai = 0; ai < 2; ++ai)
; #pragma unroll
;             for (int m = 0; m < 4; ++m) {
;                 const int tok = u.pm * 256 + 128 * ai + 64 * wr + 16 * m + fr;
;                 float part = 0.f;
; #pragma unroll
;                 for (int bj = 0; bj < 2; ++bj) {
;                     const size_t idx = (size_t)tok * 2048 + u.pn * 256 + 128 * bj + 32 * wc + 8 * fq;
;                     const u32x4 xw = *(const u32x4*)(xb + idx);
;                     f32x4 y0 = (f32x4){bflo(xw.x), bfhi(xw.x), bflo(xw.y), bfhi(xw.y)}, y1 = (f32x4){bflo(xw.z), bfhi(xw.z), bflo(xw.w), bfhi(xw.w)};
;                     y0 += acc[ai][bj][m][0]; y1 += acc[ai][bj][m][1];
;                     part += y0[0] * y0[0] + y0[1] * y0[1] + y0[2] * y0[2] + y0[3] * y0[3] + y1[0] * y1[0] + y1[1] * y1[1] + y1[2] * y1[2] + y1[3] * y1[3];
;                     u32x4 w; w.x = cvt_pk_bf16(y0[0], y0[1]); w.y = cvt_pk_bf16(y0[2], y0[3]); w.z = cvt_pk_bf16(y1[0], y1[1]); w.w = cvt_pk_bf16(y1[2], y1[3]);
;                     WT_STORE16(xb + idx, w);
;                 }
;                 part += __shfl_xor(part, 16); part += __shfl_xor(part, 32);
;                 if (fq == 0) atomicAdd(ssn + tok, (u64)(part * SS_SCALE));
;             }
.LBB0_648:
	s_or_b64 exec, exec, s[0:1]
	v_or_b32_e32 v98, 32, v130
	s_waitcnt lgkmcnt(0)
	v_ashrrev_i32_e32 v99, 31, v98
	v_lshlrev_b64 v[98:99], 12, v[98:99]
	v_lshl_add_u64 v[102:103], v[132:133], 0, v[98:99]
	v_add_u32_e32 v108, 0x10800000, v98
	s_waitcnt vmcnt(15)
	v_mov_b32_e32 v98, v174
	v_mov_b32_e32 v99, v175
	v_mov_b32_e32 v100, v176
	v_mov_b32_e32 v101, v177
	v_lshlrev_b32_e32 v104, 16, v98
	v_and_b32_e32 v105, 0xffff0000, v98
	v_lshlrev_b32_e32 v98, 16, v99
	v_and_b32_e32 v99, 0xffff0000, v99
	v_lshlrev_b32_e32 v106, 16, v100
	v_and_b32_e32 v107, 0xffff0000, v100
	v_lshlrev_b32_e32 v100, 16, v101
	v_and_b32_e32 v101, 0xffff0000, v101
	v_pk_add_f32 v[94:95], v[94:95], v[104:105]
	v_pk_add_f32 v[96:97], v[96:97], v[98:99]
	v_pk_add_f32 v[98:99], v[92:93], v[100:101]
	v_mul_f32_e32 v100, v95, v95
	v_fmac_f32_e32 v100, v94, v94
	v_fmac_f32_e32 v100, v96, v96
	v_pk_add_f32 v[92:93], v[90:91], v[106:107]
	v_fmac_f32_e32 v100, v97, v97
	v_fmac_f32_e32 v100, v92, v92
	v_cvt_pk_bf16_f32 v90, v94, v95
	v_or_b32_e32 v94, v108, v0
	v_fmac_f32_e32 v100, v93, v93
	v_cvt_pk_bf16_f32 v91, v96, v97
	v_cvt_pk_bf16_f32 v92, v92, v93
	v_cvt_pk_bf16_f32 v93, v98, v99
	buffer_store_dwordx4 v[90:93], v94, s[60:63], 0 offen
	v_fmac_f32_e32 v100, v98, v98
	v_fmac_f32_e32 v100, v99, v99
	s_waitcnt vmcnt(15)
	v_mov_b32_e32 v90, v178
	v_mov_b32_e32 v91, v179
	v_mov_b32_e32 v92, v180
	v_mov_b32_e32 v93, v181
	v_lshlrev_b32_e32 v94, 16, v90
	v_and_b32_e32 v95, 0xffff0000, v90
	v_lshlrev_b32_e32 v90, 16, v91
	v_and_b32_e32 v91, 0xffff0000, v91
	v_lshlrev_b32_e32 v96, 16, v92
	v_and_b32_e32 v97, 0xffff0000, v92
	v_lshlrev_b32_e32 v92, 16, v93
	v_and_b32_e32 v93, 0xffff0000, v93
	v_pk_add_f32 v[86:87], v[86:87], v[94:95]
	v_pk_add_f32 v[88:89], v[88:89], v[90:91]
	v_pk_add_f32 v[90:91], v[84:85], v[92:93]
	v_pk_add_f32 v[84:85], v[82:83], v[96:97]
	v_mul_f32_e32 v82, v87, v87
	v_fmac_f32_e32 v82, v86, v86
	v_fmac_f32_e32 v82, v88, v88
	v_fmac_f32_e32 v82, v89, v89
	v_fmac_f32_e32 v82, v84, v84
	v_fmac_f32_e32 v82, v85, v85
	v_fmac_f32_e32 v82, v90, v90
	v_fmac_f32_e32 v82, v91, v91
	v_add_f32_e32 v92, v100, v82
	v_cvt_pk_bf16_f32 v82, v86, v87
	v_add_u32_e32 v86, v108, v116
	v_cvt_pk_bf16_f32 v83, v88, v89
	v_cvt_pk_bf16_f32 v84, v84, v85
	v_cvt_pk_bf16_f32 v85, v90, v91
	buffer_store_dwordx4 v[82:85], v86, s[60:63], 0 offen
	ds_bpermute_b32 v82, v126, v92
	s_waitcnt lgkmcnt(0)
	v_add_f32_e32 v82, v92, v82
	ds_bpermute_b32 v83, v117, v82
	s_and_saveexec_b64 s[0:1], vcc
	s_cbranch_execz .LBB0_650
	s_waitcnt lgkmcnt(0)
	v_add_f32_e32 v82, v82, v83
	v_mul_f32_e32 v82, 0x49800000, v82
	v_trunc_f32_e32 v82, v82
	v_mul_f32_e32 v83, 0x2f800000, v82
	v_floor_f32_e32 v83, v83
	v_fmac_f32_e32 v82, 0xcf800000, v83
	v_cvt_u32_f32_e32 v82, v82
	v_cvt_u32_f32_e32 v83, v83
	global_atomic_add_x2 v[114:115], v[82:83], off offset:256
.LBB0_650:
	s_or_b64 exec, exec, s[0:1]
	v_or_b32_e32 v82, 48, v130
	s_waitcnt lgkmcnt(0)
	v_ashrrev_i32_e32 v83, 31, v82
	v_lshlrev_b64 v[82:83], 12, v[82:83]
	v_lshl_add_u64 v[86:87], v[132:133], 0, v[82:83]
	v_add_u32_e32 v92, 0x10800000, v82
	s_waitcnt vmcnt(15)
	v_mov_b32_e32 v82, v182
	v_mov_b32_e32 v83, v183
	v_mov_b32_e32 v84, v184
	v_mov_b32_e32 v85, v185
	v_lshlrev_b32_e32 v88, 16, v82
	v_and_b32_e32 v89, 0xffff0000, v82
	v_lshlrev_b32_e32 v82, 16, v83
	v_and_b32_e32 v83, 0xffff0000, v83
	v_lshlrev_b32_e32 v90, 16, v84
	v_and_b32_e32 v91, 0xffff0000, v84
	v_lshlrev_b32_e32 v84, 16, v85
	v_and_b32_e32 v85, 0xffff0000, v85
	v_pk_add_f32 v[78:79], v[78:79], v[88:89]
	v_pk_add_f32 v[80:81], v[80:81], v[82:83]
	v_pk_add_f32 v[82:83], v[76:77], v[84:85]
	v_mul_f32_e32 v84, v79, v79
	v_fmac_f32_e32 v84, v78, v78
	v_fmac_f32_e32 v84, v80, v80
	v_pk_add_f32 v[76:77], v[74:75], v[90:91]
	v_fmac_f32_e32 v84, v81, v81
	v_fmac_f32_e32 v84, v76, v76
	v_cvt_pk_bf16_f32 v74, v78, v79
	v_or_b32_e32 v78, v92, v0
	v_fmac_f32_e32 v84, v77, v77
	v_cvt_pk_bf16_f32 v75, v80, v81
	v_cvt_pk_bf16_f32 v76, v76, v77
	v_cvt_pk_bf16_f32 v77, v82, v83
	buffer_store_dwordx4 v[74:77], v78, s[60:63], 0 offen
	v_fmac_f32_e32 v84, v82, v82
	v_fmac_f32_e32 v84, v83, v83
	s_waitcnt vmcnt(15)
	v_mov_b32_e32 v74, v186
	v_mov_b32_e32 v75, v187
	v_mov_b32_e32 v76, v188
	v_mov_b32_e32 v77, v189
	v_lshlrev_b32_e32 v78, 16, v74
	v_and_b32_e32 v79, 0xffff0000, v74
	v_lshlrev_b32_e32 v74, 16, v75
	v_and_b32_e32 v75, 0xffff0000, v75
	v_lshlrev_b32_e32 v80, 16, v76
	v_and_b32_e32 v81, 0xffff0000, v76
	v_lshlrev_b32_e32 v76, 16, v77
	v_and_b32_e32 v77, 0xffff0000, v77
	v_pk_add_f32 v[70:71], v[70:71], v[78:79]
	v_pk_add_f32 v[72:73], v[72:73], v[74:75]
	v_pk_add_f32 v[74:75], v[68:69], v[76:77]
	v_pk_add_f32 v[68:69], v[66:67], v[80:81]
	v_mul_f32_e32 v66, v71, v71
	v_fmac_f32_e32 v66, v70, v70
	v_fmac_f32_e32 v66, v72, v72
	v_fmac_f32_e32 v66, v73, v73
	v_fmac_f32_e32 v66, v68, v68
	v_fmac_f32_e32 v66, v69, v69
	v_fmac_f32_e32 v66, v74, v74
	v_fmac_f32_e32 v66, v75, v75
	v_add_f32_e32 v76, v84, v66
	v_cvt_pk_bf16_f32 v66, v70, v71
	v_add_u32_e32 v70, v92, v116
	v_cvt_pk_bf16_f32 v67, v72, v73
	v_cvt_pk_bf16_f32 v68, v68, v69
	v_cvt_pk_bf16_f32 v69, v74, v75
	buffer_store_dwordx4 v[66:69], v70, s[60:63], 0 offen
	ds_bpermute_b32 v66, v126, v76
	s_waitcnt lgkmcnt(0)
	v_add_f32_e32 v66, v76, v66
	ds_bpermute_b32 v67, v117, v66
	s_and_saveexec_b64 s[0:1], vcc
	v_readlane_b32 s84, v252, 43
	s_mov_b32 s96, 0x8400
	s_cbranch_execz .LBB0_652
	s_waitcnt lgkmcnt(0)
	v_add_f32_e32 v66, v66, v67
	v_mul_f32_e32 v66, 0x49800000, v66
	v_trunc_f32_e32 v66, v66
	v_mul_f32_e32 v67, 0x2f800000, v66
	v_floor_f32_e32 v67, v67
	v_fmac_f32_e32 v66, 0xcf800000, v67
	v_cvt_u32_f32_e32 v66, v66
	v_cvt_u32_f32_e32 v67, v67
	global_atomic_add_x2 v[114:115], v[66:67], off offset:384
; __device__ __forceinline__ unsigned cvt_pk_bf16(float lo, float hi) { unsigned r; asm("v_cvt_pk_bf16_f32 %0, %1, %2" : "=v"(r) : "v"(lo), "v"(hi)); return r; }
; __device__ __forceinline__ float bflo(unsigned w) { return __uint_as_float(w << 16); }
; __device__ __forceinline__ float bfhi(unsigned w) { return __uint_as_float(w & 0xffff0000u); }
; #define WT_STORE16(ptr, val) __builtin_amdgcn_raw_buffer_store_b128((val), wsr, (int)((const char*)(ptr) - (const char*)ws), 0, 16)
; template <int MODE>
; __device__ __forceinline__ void gemm_epilogue(const Params& p, int l, const f32x4 (&acc)[2][2][4][2], const Unit& u, int wr, int wc, int fr, int fq, const LAS float* rl, int pm0) {
;     ...
; #pragma unroll
;         for (int ai = 0; ai < 2; ++ai)
; #pragma unroll
;             for (int m = 0; m < 4; ++m) {
;                 const int tok = u.pm * 256 + 128 * ai + 64 * wr + 16 * m + fr;
;                 float part = 0.f;
; #pragma unroll
;                 for (int bj = 0; bj < 2; ++bj) {
;                     const size_t idx = (size_t)tok * 2048 + u.pn * 256 + 128 * bj + 32 * wc + 8 * fq;
;                     const u32x4 xw = *(const u32x4*)(xb + idx);
;                     f32x4 y0 = (f32x4){bflo(xw.x), bfhi(xw.x), bflo(xw.y), bfhi(xw.y)}, y1 = (f32x4){bflo(xw.z), bfhi(xw.z), bflo(xw.w), bfhi(xw.w)};
;                     y0 += acc[ai][bj][m][0]; y1 += acc[ai][bj][m][1];
;                     part += y0[0] * y0[0] + y0[1] * y0[1] + y0[2] * y0[2] + y0[3] * y0[3] + y1[0] * y1[0] + y1[1] * y1[1] + y1[2] * y1[2] + y1[3] * y1[3];
;                     u32x4 w; w.x = cvt_pk_bf16(y0[0], y0[1]); w.y = cvt_pk_bf16(y0[2], y0[3]); w.z = cvt_pk_bf16(y1[0], y1[1]); w.w = cvt_pk_bf16(y1[2], y1[3]);
;                     WT_STORE16(xb + idx, w);
;                 }
;                 part += __shfl_xor(part, 16); part += __shfl_xor(part, 32);
;                 if (fq == 0) atomicAdd(ssn + tok, (u64)(part * SS_SCALE));
;             }
.LBB0_652:
	s_or_b64 exec, exec, s[0:1]
	v_add_u32_e32 v66, 0x80, v130
	s_waitcnt lgkmcnt(0)
	v_ashrrev_i32_e32 v67, 31, v66
	v_lshlrev_b64 v[66:67], 12, v[66:67]
	v_lshl_add_u64 v[70:71], v[132:133], 0, v[66:67]
	v_add_u32_e32 v76, 0x10800000, v66
	s_waitcnt vmcnt(15)
	v_mov_b32_e32 v66, v190
	v_mov_b32_e32 v67, v191
	v_mov_b32_e32 v68, v192
	v_mov_b32_e32 v69, v193
	v_lshlrev_b32_e32 v72, 16, v66
	v_and_b32_e32 v73, 0xffff0000, v66
	v_lshlrev_b32_e32 v66, 16, v67
	v_and_b32_e32 v67, 0xffff0000, v67
	v_lshlrev_b32_e32 v74, 16, v68
	v_and_b32_e32 v75, 0xffff0000, v68
	v_lshlrev_b32_e32 v68, 16, v69
	v_and_b32_e32 v69, 0xffff0000, v69
	v_pk_add_f32 v[62:63], v[62:63], v[72:73]
	v_pk_add_f32 v[64:65], v[64:65], v[66:67]
	v_pk_add_f32 v[66:67], v[60:61], v[68:69]
	v_mul_f32_e32 v68, v63, v63
	v_fmac_f32_e32 v68, v62, v62
	v_fmac_f32_e32 v68, v64, v64
	v_pk_add_f32 v[60:61], v[58:59], v[74:75]
	v_fmac_f32_e32 v68, v65, v65
	v_fmac_f32_e32 v68, v60, v60
	v_cvt_pk_bf16_f32 v58, v62, v63
	v_or_b32_e32 v62, v76, v0
	v_fmac_f32_e32 v68, v61, v61
	v_cvt_pk_bf16_f32 v59, v64, v65
	v_cvt_pk_bf16_f32 v60, v60, v61
	v_cvt_pk_bf16_f32 v61, v66, v67
	buffer_store_dwordx4 v[58:61], v62, s[60:63], 0 offen
	v_fmac_f32_e32 v68, v66, v66
	v_fmac_f32_e32 v68, v67, v67
	s_waitcnt vmcnt(15)
	v_mov_b32_e32 v58, v194
	v_mov_b32_e32 v59, v195
	v_mov_b32_e32 v60, v196
	v_mov_b32_e32 v61, v197
	v_lshlrev_b32_e32 v62, 16, v58
	v_and_b32_e32 v63, 0xffff0000, v58
	v_lshlrev_b32_e32 v58, 16, v59
	v_and_b32_e32 v59, 0xffff0000, v59
	v_lshlrev_b32_e32 v64, 16, v60
	v_and_b32_e32 v65, 0xffff0000, v60
	v_lshlrev_b32_e32 v60, 16, v61
	v_and_b32_e32 v61, 0xffff0000, v61
	v_pk_add_f32 v[54:55], v[54:55], v[62:63]
	v_pk_add_f32 v[56:57], v[56:57], v[58:59]
	v_pk_add_f32 v[58:59], v[52:53], v[60:61]
	v_pk_add_f32 v[52:53], v[50:51], v[64:65]
	v_mul_f32_e32 v50, v55, v55
	v_fmac_f32_e32 v50, v54, v54
	v_fmac_f32_e32 v50, v56, v56
	v_fmac_f32_e32 v50, v57, v57
	v_fmac_f32_e32 v50, v52, v52
	v_fmac_f32_e32 v50, v53, v53
	v_fmac_f32_e32 v50, v58, v58
	v_fmac_f32_e32 v50, v59, v59
	v_add_f32_e32 v60, v68, v50
	v_cvt_pk_bf16_f32 v50, v54, v55
	v_add_u32_e32 v54, v76, v116
	v_cvt_pk_bf16_f32 v51, v56, v57
	v_cvt_pk_bf16_f32 v52, v52, v53
	v_cvt_pk_bf16_f32 v53, v58, v59
	buffer_store_dwordx4 v[50:53], v54, s[60:63], 0 offen
	ds_bpermute_b32 v50, v126, v60
	s_waitcnt lgkmcnt(0)
	v_add_f32_e32 v50, v60, v50
	ds_bpermute_b32 v51, v117, v50
	s_and_saveexec_b64 s[0:1], vcc
	s_cbranch_execz .LBB0_654
	s_waitcnt lgkmcnt(0)
	v_add_f32_e32 v50, v50, v51
	v_mul_f32_e32 v50, 0x49800000, v50
	v_trunc_f32_e32 v50, v50
	v_mul_f32_e32 v51, 0x2f800000, v50
	v_floor_f32_e32 v51, v51
	v_fmac_f32_e32 v50, 0xcf800000, v51
	v_cvt_u32_f32_e32 v50, v50
	v_cvt_u32_f32_e32 v51, v51
	global_atomic_add_x2 v[114:115], v[50:51], off offset:1024
.LBB0_654:
	s_or_b64 exec, exec, s[0:1]
	v_add_u32_e32 v50, 0x90, v130
	s_waitcnt lgkmcnt(0)
	v_ashrrev_i32_e32 v51, 31, v50
	v_lshlrev_b64 v[50:51], 12, v[50:51]
	v_lshl_add_u64 v[54:55], v[132:133], 0, v[50:51]
	v_add_u32_e32 v60, 0x10800000, v50
	s_waitcnt vmcnt(15)
	v_mov_b32_e32 v50, v208
	v_mov_b32_e32 v51, v209
	v_mov_b32_e32 v52, v210
	v_mov_b32_e32 v53, v211
	v_lshlrev_b32_e32 v56, 16, v50
	v_and_b32_e32 v57, 0xffff0000, v50
	v_lshlrev_b32_e32 v50, 16, v51
	v_and_b32_e32 v51, 0xffff0000, v51
	v_lshlrev_b32_e32 v58, 16, v52
	v_and_b32_e32 v59, 0xffff0000, v52
	v_lshlrev_b32_e32 v52, 16, v53
	v_and_b32_e32 v53, 0xffff0000, v53
	v_pk_add_f32 v[46:47], v[46:47], v[56:57]
	v_pk_add_f32 v[48:49], v[48:49], v[50:51]
	v_pk_add_f32 v[50:51], v[44:45], v[52:53]
	v_mul_f32_e32 v52, v47, v47
	v_fmac_f32_e32 v52, v46, v46
	v_fmac_f32_e32 v52, v48, v48
	v_pk_add_f32 v[44:45], v[42:43], v[58:59]
	v_fmac_f32_e32 v52, v49, v49
	v_fmac_f32_e32 v52, v44, v44
	v_cvt_pk_bf16_f32 v42, v46, v47
	v_or_b32_e32 v46, v60, v0
	v_fmac_f32_e32 v52, v45, v45
	v_cvt_pk_bf16_f32 v43, v48, v49
	v_cvt_pk_bf16_f32 v44, v44, v45
	v_cvt_pk_bf16_f32 v45, v50, v51
	buffer_store_dwordx4 v[42:45], v46, s[60:63], 0 offen
	v_fmac_f32_e32 v52, v50, v50
	v_fmac_f32_e32 v52, v51, v51
	s_waitcnt vmcnt(15)
	v_mov_b32_e32 v42, v212
	v_mov_b32_e32 v43, v213
	v_mov_b32_e32 v44, v214
	v_mov_b32_e32 v45, v215
	v_lshlrev_b32_e32 v46, 16, v42
	v_and_b32_e32 v47, 0xffff0000, v42
	v_lshlrev_b32_e32 v42, 16, v43
	v_and_b32_e32 v43, 0xffff0000, v43
	v_lshlrev_b32_e32 v48, 16, v44
	v_and_b32_e32 v49, 0xffff0000, v44
	v_lshlrev_b32_e32 v44, 16, v45
	v_and_b32_e32 v45, 0xffff0000, v45
	v_pk_add_f32 v[38:39], v[38:39], v[46:47]
	v_pk_add_f32 v[40:41], v[40:41], v[42:43]
	v_pk_add_f32 v[42:43], v[36:37], v[44:45]
	v_pk_add_f32 v[36:37], v[34:35], v[48:49]
	v_mul_f32_e32 v34, v39, v39
	v_fmac_f32_e32 v34, v38, v38
	v_fmac_f32_e32 v34, v40, v40
	v_fmac_f32_e32 v34, v41, v41
	v_fmac_f32_e32 v34, v36, v36
	v_fmac_f32_e32 v34, v37, v37
	v_fmac_f32_e32 v34, v42, v42
	v_fmac_f32_e32 v34, v43, v43
	v_add_f32_e32 v44, v52, v34
	v_cvt_pk_bf16_f32 v34, v38, v39
	v_add_u32_e32 v38, v60, v116
	v_cvt_pk_bf16_f32 v35, v40, v41
	v_cvt_pk_bf16_f32 v36, v36, v37
	v_cvt_pk_bf16_f32 v37, v42, v43
	buffer_store_dwordx4 v[34:37], v38, s[60:63], 0 offen
	ds_bpermute_b32 v34, v126, v44
	s_waitcnt lgkmcnt(0)
	v_add_f32_e32 v34, v44, v34
	ds_bpermute_b32 v35, v117, v34
	s_and_saveexec_b64 s[0:1], vcc
	s_cbranch_execz .LBB0_656
	s_waitcnt lgkmcnt(0)
	v_add_f32_e32 v34, v34, v35
	v_mul_f32_e32 v34, 0x49800000, v34
	v_trunc_f32_e32 v34, v34
	v_mul_f32_e32 v35, 0x2f800000, v34
	v_floor_f32_e32 v35, v35
	v_fmac_f32_e32 v34, 0xcf800000, v35
	v_cvt_u32_f32_e32 v34, v34
	v_cvt_u32_f32_e32 v35, v35
	global_atomic_add_x2 v[114:115], v[34:35], off offset:1152
; __device__ __forceinline__ unsigned cvt_pk_bf16(float lo, float hi) { unsigned r; asm("v_cvt_pk_bf16_f32 %0, %1, %2" : "=v"(r) : "v"(lo), "v"(hi)); return r; }
; __device__ __forceinline__ float bflo(unsigned w) { return __uint_as_float(w << 16); }
; __device__ __forceinline__ float bfhi(unsigned w) { return __uint_as_float(w & 0xffff0000u); }
; #define WT_STORE16(ptr, val) __builtin_amdgcn_raw_buffer_store_b128((val), wsr, (int)((const char*)(ptr) - (const char*)ws), 0, 16)
; template <int MODE>
; __device__ __forceinline__ void gemm_epilogue(const Params& p, int l, const f32x4 (&acc)[2][2][4][2], const Unit& u, int wr, int wc, int fr, int fq, const LAS float* rl, int pm0) {
;     ...
; #pragma unroll
;         for (int ai = 0; ai < 2; ++ai)
; #pragma unroll
;             for (int m = 0; m < 4; ++m) {
;                 const int tok = u.pm * 256 + 128 * ai + 64 * wr + 16 * m + fr;
;                 float part = 0.f;
; #pragma unroll
;                 for (int bj = 0; bj < 2; ++bj) {
;                     const size_t idx = (size_t)tok * 2048 + u.pn * 256 + 128 * bj + 32 * wc + 8 * fq;
;                     const u32x4 xw = *(const u32x4*)(xb + idx);
;                     f32x4 y0 = (f32x4){bflo(xw.x), bfhi(xw.x), bflo(xw.y), bfhi(xw.y)}, y1 = (f32x4){bflo(xw.z), bfhi(xw.z), bflo(xw.w), bfhi(xw.w)};
;                     y0 += acc[ai][bj][m][0]; y1 += acc[ai][bj][m][1];
;                     part += y0[0] * y0[0] + y0[1] * y0[1] + y0[2] * y0[2] + y0[3] * y0[3] + y1[0] * y1[0] + y1[1] * y1[1] + y1[2] * y1[2] + y1[3] * y1[3];
;                     u32x4 w; w.x = cvt_pk_bf16(y0[0], y0[1]); w.y = cvt_pk_bf16(y0[2], y0[3]); w.z = cvt_pk_bf16(y1[0], y1[1]); w.w = cvt_pk_bf16(y1[2], y1[3]);
;                     WT_STORE16(xb + idx, w);
;                 }
;                 part += __shfl_xor(part, 16); part += __shfl_xor(part, 32);
;                 if (fq == 0) atomicAdd(ssn + tok, (u64)(part * SS_SCALE));
;             }
.LBB0_656:
	s_or_b64 exec, exec, s[0:1]
	v_add_u32_e32 v34, 0xa0, v130
	s_waitcnt lgkmcnt(0)
	v_ashrrev_i32_e32 v35, 31, v34
	v_lshlrev_b64 v[34:35], 12, v[34:35]
	v_lshl_add_u64 v[38:39], v[132:133], 0, v[34:35]
	v_add_u32_e32 v44, 0x10800000, v34
	s_waitcnt vmcnt(15)
	v_mov_b32_e32 v34, v216
	v_mov_b32_e32 v35, v217
	v_mov_b32_e32 v36, v218
	v_mov_b32_e32 v37, v219
	v_lshlrev_b32_e32 v40, 16, v34
	v_and_b32_e32 v41, 0xffff0000, v34
	v_lshlrev_b32_e32 v34, 16, v35
	v_and_b32_e32 v35, 0xffff0000, v35
	v_lshlrev_b32_e32 v42, 16, v36
	v_and_b32_e32 v43, 0xffff0000, v36
	v_lshlrev_b32_e32 v36, 16, v37
	v_and_b32_e32 v37, 0xffff0000, v37
	v_pk_add_f32 v[30:31], v[30:31], v[40:41]
	v_pk_add_f32 v[32:33], v[32:33], v[34:35]
	v_pk_add_f32 v[34:35], v[28:29], v[36:37]
	v_mul_f32_e32 v36, v31, v31
	v_fmac_f32_e32 v36, v30, v30
	v_fmac_f32_e32 v36, v32, v32
	v_pk_add_f32 v[28:29], v[26:27], v[42:43]
	v_fmac_f32_e32 v36, v33, v33
	v_fmac_f32_e32 v36, v28, v28
	v_cvt_pk_bf16_f32 v26, v30, v31
	v_or_b32_e32 v30, v44, v0
	v_fmac_f32_e32 v36, v29, v29
	v_cvt_pk_bf16_f32 v27, v32, v33
	v_cvt_pk_bf16_f32 v28, v28, v29
	v_cvt_pk_bf16_f32 v29, v34, v35
	buffer_store_dwordx4 v[26:29], v30, s[60:63], 0 offen
	v_fmac_f32_e32 v36, v34, v34
	v_fmac_f32_e32 v36, v35, v35
	s_waitcnt vmcnt(15)
	v_mov_b32_e32 v26, v220
	v_mov_b32_e32 v27, v221
	v_mov_b32_e32 v28, v222
	v_mov_b32_e32 v29, v223
	v_lshlrev_b32_e32 v30, 16, v26
	v_and_b32_e32 v31, 0xffff0000, v26
	v_lshlrev_b32_e32 v26, 16, v27
	v_and_b32_e32 v27, 0xffff0000, v27
	v_lshlrev_b32_e32 v32, 16, v28
	v_and_b32_e32 v33, 0xffff0000, v28
	v_lshlrev_b32_e32 v28, 16, v29
	v_and_b32_e32 v29, 0xffff0000, v29
	v_pk_add_f32 v[22:23], v[22:23], v[30:31]
	v_pk_add_f32 v[24:25], v[24:25], v[26:27]
	v_pk_add_f32 v[26:27], v[20:21], v[28:29]
	v_pk_add_f32 v[20:21], v[18:19], v[32:33]
	v_mul_f32_e32 v18, v23, v23
	v_fmac_f32_e32 v18, v22, v22
	v_fmac_f32_e32 v18, v24, v24
	v_fmac_f32_e32 v18, v25, v25
	v_fmac_f32_e32 v18, v20, v20
	v_fmac_f32_e32 v18, v21, v21
	v_fmac_f32_e32 v18, v26, v26
	v_fmac_f32_e32 v18, v27, v27
	v_add_f32_e32 v28, v36, v18
	v_cvt_pk_bf16_f32 v18, v22, v23
	v_add_u32_e32 v22, v44, v116
	v_cvt_pk_bf16_f32 v19, v24, v25
	v_cvt_pk_bf16_f32 v20, v20, v21
	v_cvt_pk_bf16_f32 v21, v26, v27
	buffer_store_dwordx4 v[18:21], v22, s[60:63], 0 offen
	ds_bpermute_b32 v18, v126, v28
	s_waitcnt lgkmcnt(0)
	v_add_f32_e32 v18, v28, v18
	ds_bpermute_b32 v19, v117, v18
	s_and_saveexec_b64 s[0:1], vcc
	s_cbranch_execz .LBB0_658
	s_waitcnt lgkmcnt(0)
	v_add_f32_e32 v18, v18, v19
	v_mul_f32_e32 v18, 0x49800000, v18
	v_trunc_f32_e32 v18, v18
	v_mul_f32_e32 v19, 0x2f800000, v18
	v_floor_f32_e32 v19, v19
	v_fmac_f32_e32 v18, 0xcf800000, v19
	v_cvt_u32_f32_e32 v18, v18
	v_cvt_u32_f32_e32 v19, v19
	global_atomic_add_x2 v[114:115], v[18:19], off offset:1280
.LBB0_658:
	s_or_b64 exec, exec, s[0:1]
	v_add_u32_e32 v18, 0xb0, v130
	s_waitcnt lgkmcnt(0)
	v_ashrrev_i32_e32 v19, 31, v18
	v_lshlrev_b64 v[22:23], 12, v[18:19]
	v_lshl_add_u64 v[24:25], v[132:133], 0, v[22:23]
	v_add_u32_e32 v28, 0x10800000, v22
	v_or_b32_e32 v0, v28, v0
	s_waitcnt vmcnt(15)
	v_mov_b32_e32 v18, v224
	v_mov_b32_e32 v19, v225
	v_mov_b32_e32 v20, v226
	v_mov_b32_e32 v21, v227
	v_lshlrev_b32_e32 v22, 16, v18
	v_and_b32_e32 v23, 0xffff0000, v18
	v_lshlrev_b32_e32 v18, 16, v19
	v_and_b32_e32 v19, 0xffff0000, v19
	v_lshlrev_b32_e32 v26, 16, v20
	v_and_b32_e32 v27, 0xffff0000, v20
	v_lshlrev_b32_e32 v20, 16, v21
	v_and_b32_e32 v21, 0xffff0000, v21
	v_pk_add_f32 v[16:17], v[16:17], v[18:19]
	v_pk_add_f32 v[14:15], v[14:15], v[22:23]
	v_pk_add_f32 v[18:19], v[12:13], v[20:21]
	v_pk_add_f32 v[20:21], v[10:11], v[26:27]
	v_cvt_pk_bf16_f32 v10, v14, v15
	v_cvt_pk_bf16_f32 v11, v16, v17
	v_cvt_pk_bf16_f32 v13, v18, v19
	s_nop 0
	v_cvt_pk_bf16_f32 v12, v20, v21
	buffer_store_dwordx4 v[10:13], v0, s[60:63], 0 offen
	v_mul_f32_e32 v0, v15, v15
	v_fmac_f32_e32 v0, v14, v14
	v_fmac_f32_e32 v0, v16, v16
	v_fmac_f32_e32 v0, v17, v17
	v_fmac_f32_e32 v0, v20, v20
	v_fmac_f32_e32 v0, v21, v21
	v_fmac_f32_e32 v0, v18, v18
	v_fmac_f32_e32 v0, v19, v19
	s_waitcnt vmcnt(15)
	v_mov_b32_e32 v10, v228
	v_mov_b32_e32 v11, v229
	v_mov_b32_e32 v12, v230
	v_mov_b32_e32 v13, v231
	v_lshlrev_b32_e32 v14, 16, v10
	v_and_b32_e32 v15, 0xffff0000, v10
	v_lshlrev_b32_e32 v10, 16, v11
	v_and_b32_e32 v11, 0xffff0000, v11
	v_lshlrev_b32_e32 v16, 16, v12
	v_and_b32_e32 v17, 0xffff0000, v12
	v_lshlrev_b32_e32 v12, 16, v13
	v_and_b32_e32 v13, 0xffff0000, v13
	v_pk_add_f32 v[6:7], v[6:7], v[14:15]
	v_pk_add_f32 v[8:9], v[8:9], v[10:11]
	v_pk_add_f32 v[10:11], v[4:5], v[12:13]
	v_pk_add_f32 v[12:13], v[2:3], v[16:17]
	v_mul_f32_e32 v2, v7, v7
	v_fmac_f32_e32 v2, v6, v6
	v_fmac_f32_e32 v2, v8, v8
	v_fmac_f32_e32 v2, v9, v9
	v_fmac_f32_e32 v2, v12, v12
	v_fmac_f32_e32 v2, v13, v13
	v_fmac_f32_e32 v2, v10, v10
	v_fmac_f32_e32 v2, v11, v11
	v_add_f32_e32 v0, v0, v2
	ds_bpermute_b32 v2, v126, v0
	v_add_u32_e32 v3, v28, v116
	v_cvt_pk_bf16_f32 v4, v6, v7
	v_cvt_pk_bf16_f32 v5, v8, v9
	v_cvt_pk_bf16_f32 v6, v12, v13
	s_waitcnt lgkmcnt(0)
	v_add_f32_e32 v0, v0, v2
	ds_bpermute_b32 v2, v117, v0
	v_cvt_pk_bf16_f32 v7, v10, v11
	buffer_store_dwordx4 v[4:7], v3, s[60:63], 0 offen
	s_and_saveexec_b64 s[0:1], vcc
	s_cbranch_execz .LBB0_660
	s_waitcnt lgkmcnt(0)
	v_add_f32_e32 v0, v0, v2
	v_mul_f32_e32 v0, 0x49800000, v0
	v_trunc_f32_e32 v0, v0
	v_mul_f32_e32 v2, 0x2f800000, v0
	v_floor_f32_e32 v3, v2
	v_fmac_f32_e32 v0, 0xcf800000, v3
	v_cvt_u32_f32_e32 v2, v0
	v_cvt_u32_f32_e32 v3, v3
	global_atomic_add_x2 v[114:115], v[2:3], off offset:1408

; #define PG8_STAGE(bufoff, gbase, voff) do { _Pragma("unroll") for (int _i = 0; _i < 2; ++_i) \
;         __builtin_amdgcn_global_load_lds((const unsigned*)((const char*)(gbase) + (voff)[_i]), (LAS unsigned*)(lds + (bufoff) + ldsw + _i * 8192), 16, 0, 0); } while (0)
; #define PG8_LDA(dst, b, h) do { _Pragma("unroll") for (int m = 0; m < 4; ++m) _Pragma("unroll") for (int k = 0; k < 2; ++k) dst[m][k] = *(const LAS bf16x8*)(lds + PG8_SA(b, h) + aoff + m * 2048 + k * 1024); } while (0)
; #define PG8_LDB(dst, b, h) do { _Pragma("unroll") for (int n = 0; n < 2; ++n) _Pragma("unroll") for (int k = 0; k < 2; ++k) dst[n][k] = *(const LAS bf16x8*)(lds + PG8_SB(b, h) + boff + n * 2048 + k * 1024); } while (0)
; #define PG8_MMA(ai, bj, At, Bt) do { __builtin_amdgcn_s_setprio(1); _Pragma("unroll") for (int m = 0; m < 4; ++m) _Pragma("unroll") for (int n = 0; n < 2; ++n) _Pragma("unroll") for (int k = 0; k < 2; ++k) \
;         acc[ai][bj][m][n] = __builtin_amdgcn_mfma_f32_16x16x32_bf16(Bt[n][k], At[m][k], acc[ai][bj][m][n], 0, 0, 0); __builtin_amdgcn_s_setprio(0); } while (0)
; #define PG8_WAIT_V(n) asm volatile("s_waitcnt vmcnt(" #n ")" ::: "memory")
; #define PG8_WAIT_L(n) asm volatile("s_waitcnt lgkmcnt(" #n ")" ::: "memory")
; #define PG8_BAR __builtin_amdgcn_s_barrier()
; #define PG8_SCHED __builtin_amdgcn_sched_barrier(0)
; template <int MODE>
; __device__ __forceinline__ void gemm_phase(LAS unsigned char* lds, const Params& p, int l, int single) {
;     ...
;             PG8_LDB(B0, 0, 0); PG8_SCHED; PG8_LDA(At, 0, 0); PG8_STAGE(PG8_SA(1, 1), a1 + hstep, voffA);
;             PG8_WAIT_L(8); PG8_BAR; PG8_WAIT_L(0); PG8_MMA(0, 0, At, B0); PG8_BAR; PG8_SCHED;
;             PG8_LDB(B1, 0, 1); PG8_STAGE(PG8_SB(0, 0), b2, voffB);
;             PG8_BAR; PG8_WAIT_L(0); PG8_MMA(0, 1, At, B1); PG8_BAR;
;             PG8_LDA(At, 0, 1); PG8_STAGE(PG8_SA(0, 0), a2, voffA);
;             PG8_BAR; PG8_WAIT_L(0); PG8_MMA(1, 0, At, B0); PG8_BAR; PG8_SCHED;
;             PG8_STAGE(PG8_SB(0, 1), b2 + hstep, voffB);
;             PG8_WAIT_V(6); PG8_BAR; PG8_MMA(1, 1, At, B1); PG8_BAR;
.LBB0_840:
	s_add_u32 s20, s18, 0xfff80080
	s_addc_u32 s21, s19, -1
	s_add_i32 s96, 0, 0x10000
	v_add_u32_e32 v142, s96, v162
	ds_read_b128 v[156:159], v142
	ds_read_b128 v[164:167], v142 offset:1024
	ds_read_b128 v[168:171], v142 offset:2048
	ds_read_b128 v[172:175], v142 offset:3072
	s_cmp_eq_u32 s85, 28
	s_cselect_b32 vcc_hi, s11, s21
	s_cselect_b32 vcc_lo, s13, s20
	s_cselect_b32 s21, s15, s84
	s_cselect_b32 s20, s24, s33
	v_lshl_add_u64 v[142:143], s[18:19], 0, v[152:153]
	s_add_i32 m0, s25, 0xc000
	ds_read_b128 v[176:179], v163
	ds_read_b128 v[180:183], v163 offset:1024
	ds_read_b128 v[184:187], v163 offset:2048
	ds_read_b128 v[188:191], v163 offset:3072
	ds_read_b128 v[192:195], v163 offset:4096
	ds_read_b128 v[196:199], v163 offset:5120
	ds_read_b128 v[208:211], v163 offset:6144
	ds_read_b128 v[212:215], v163 offset:7168
	global_load_lds_dwordx4 v[142:143], off
	v_lshl_add_u64 v[142:143], s[18:19], 0, v[154:155]
	s_add_i32 m0, s25, 0xe000
	s_nop 0
	global_load_lds_dwordx4 v[142:143], off
	s_waitcnt lgkmcnt(8)
	s_barrier
	s_waitcnt lgkmcnt(0)
	s_setprio 1
	s_waitcnt lgkmcnt(0)
	v_mfma_f32_16x16x32_bf16 v[126:129], v[156:159], v[176:179], v[126:129]
	v_mfma_f32_16x16x32_bf16 v[122:125], v[168:171], v[176:179], v[122:125]
	v_mfma_f32_16x16x32_bf16 v[110:113], v[156:159], v[184:187], v[110:113]
	v_mfma_f32_16x16x32_bf16 v[106:109], v[168:171], v[184:187], v[106:109]
	v_mfma_f32_16x16x32_bf16 v[94:97], v[156:159], v[192:195], v[94:97]
	v_mfma_f32_16x16x32_bf16 v[90:93], v[168:171], v[192:195], v[90:93]
	v_mfma_f32_16x16x32_bf16 v[78:81], v[156:159], v[208:211], v[78:81]
	v_mfma_f32_16x16x32_bf16 v[74:77], v[168:171], v[208:211], v[74:77]
	v_mfma_f32_16x16x32_bf16 v[126:129], v[164:167], v[180:183], v[126:129]
	v_mfma_f32_16x16x32_bf16 v[122:125], v[172:175], v[180:183], v[122:125]
	v_mfma_f32_16x16x32_bf16 v[110:113], v[164:167], v[188:191], v[110:113]
	v_mfma_f32_16x16x32_bf16 v[106:109], v[172:175], v[188:191], v[106:109]
	v_mfma_f32_16x16x32_bf16 v[94:97], v[164:167], v[196:199], v[94:97]
	v_mfma_f32_16x16x32_bf16 v[90:93], v[172:175], v[196:199], v[90:93]
	v_mfma_f32_16x16x32_bf16 v[78:81], v[164:167], v[212:215], v[78:81]
	v_mfma_f32_16x16x32_bf16 v[74:77], v[172:175], v[212:215], v[74:77]
	s_setprio 0
	s_barrier
	s_add_i32 s22, 0, 0x14000
	v_add_u32_e32 v142, s22, v162
	s_add_i32 s96, s96, s23
	ds_read_b128 v[216:219], v142
	ds_read_b128 v[220:223], v142 offset:1024
	ds_read_b128 v[224:227], v142 offset:2048
	ds_read_b128 v[228:231], v142 offset:3072
	v_lshl_add_u64 v[142:143], s[20:21], 0, v[0:1]
	s_mov_b32 m0, s96
	v_lshl_add_u64 v[160:161], s[20:21], 0, v[130:131]
	global_load_lds_dwordx4 v[142:143], off
	s_add_i32 m0, s96, 0x2000
	s_nop 0
	global_load_lds_dwordx4 v[160:161], off
	s_barrier
	s_waitcnt lgkmcnt(0)
	s_setprio 1
	s_waitcnt lgkmcnt(0)
	v_mfma_f32_16x16x32_bf16 v[118:121], v[216:219], v[176:179], v[118:121]
	v_mfma_f32_16x16x32_bf16 v[114:117], v[224:227], v[176:179], v[114:117]
	v_mfma_f32_16x16x32_bf16 v[102:105], v[216:219], v[184:187], v[102:105]
	v_mfma_f32_16x16x32_bf16 v[98:101], v[224:227], v[184:187], v[98:101]
	v_mfma_f32_16x16x32_bf16 v[86:89], v[216:219], v[192:195], v[86:89]
	v_mfma_f32_16x16x32_bf16 v[82:85], v[224:227], v[192:195], v[82:85]
	v_mfma_f32_16x16x32_bf16 v[70:73], v[216:219], v[208:211], v[70:73]
	v_mfma_f32_16x16x32_bf16 v[66:69], v[224:227], v[208:211], v[66:69]
	v_mfma_f32_16x16x32_bf16 v[118:121], v[220:223], v[180:183], v[118:121]
	v_mfma_f32_16x16x32_bf16 v[114:117], v[228:231], v[180:183], v[114:117]
	v_mfma_f32_16x16x32_bf16 v[102:105], v[220:223], v[188:191], v[102:105]
	v_mfma_f32_16x16x32_bf16 v[98:101], v[228:231], v[188:191], v[98:101]
	v_mfma_f32_16x16x32_bf16 v[86:89], v[220:223], v[196:199], v[86:89]
	v_mfma_f32_16x16x32_bf16 v[82:85], v[228:231], v[196:199], v[82:85]
	v_mfma_f32_16x16x32_bf16 v[70:73], v[220:223], v[212:215], v[70:73]
	v_mfma_f32_16x16x32_bf16 v[66:69], v[228:231], v[212:215], v[66:69]
	s_setprio 0
	s_mov_b32 m0, s25
	v_lshl_add_u64 v[232:233], vcc, 0, v[146:147]
	s_barrier
	ds_read_b128 v[176:179], v163 offset:16384
	ds_read_b128 v[180:183], v163 offset:17408
	ds_read_b128 v[184:187], v163 offset:18432
	ds_read_b128 v[188:191], v163 offset:19456
	ds_read_b128 v[192:195], v163 offset:20480
	ds_read_b128 v[196:199], v163 offset:21504
	ds_read_b128 v[208:211], v163 offset:22528
	ds_read_b128 v[212:215], v163 offset:23552
	global_load_lds_dwordx4 v[232:233], off
	v_lshl_add_u64 v[234:235], vcc, 0, v[132:133]
	s_mov_b32 m0, s28
	s_nop 0
	global_load_lds_dwordx4 v[234:235], off
	s_barrier
	s_waitcnt lgkmcnt(0)
	s_setprio 1
	s_waitcnt lgkmcnt(0)
	v_mfma_f32_16x16x32_bf16 v[62:65], v[156:159], v[176:179], v[62:65]
	v_mfma_f32_16x16x32_bf16 v[58:61], v[168:171], v[176:179], v[58:61]
	v_mfma_f32_16x16x32_bf16 v[46:49], v[156:159], v[184:187], v[46:49]
	v_mfma_f32_16x16x32_bf16 v[42:45], v[168:171], v[184:187], v[42:45]
	v_mfma_f32_16x16x32_bf16 v[30:33], v[156:159], v[192:195], v[30:33]
	v_mfma_f32_16x16x32_bf16 v[26:29], v[168:171], v[192:195], v[26:29]
	v_mfma_f32_16x16x32_bf16 v[14:17], v[156:159], v[208:211], v[14:17]
	v_mfma_f32_16x16x32_bf16 v[10:13], v[168:171], v[208:211], v[10:13]
	v_mfma_f32_16x16x32_bf16 v[62:65], v[164:167], v[180:183], v[62:65]
	v_mfma_f32_16x16x32_bf16 v[58:61], v[172:175], v[180:183], v[58:61]
	v_mfma_f32_16x16x32_bf16 v[46:49], v[164:167], v[188:191], v[46:49]
	v_mfma_f32_16x16x32_bf16 v[42:45], v[172:175], v[188:191], v[42:45]
	v_mfma_f32_16x16x32_bf16 v[30:33], v[164:167], v[196:199], v[30:33]
	v_mfma_f32_16x16x32_bf16 v[26:29], v[172:175], v[196:199], v[26:29]
	v_mfma_f32_16x16x32_bf16 v[14:17], v[164:167], v[212:215], v[14:17]
	v_mfma_f32_16x16x32_bf16 v[10:13], v[172:175], v[212:215], v[10:13]
	s_setprio 0
	s_barrier
; #define PG8_STAGE(bufoff, gbase, voff) do { _Pragma("unroll") for (int _i = 0; _i < 2; ++_i) \
;         __builtin_amdgcn_global_load_lds((const unsigned*)((const char*)(gbase) + (voff)[_i]), (LAS unsigned*)(lds + (bufoff) + ldsw + _i * 8192), 16, 0, 0); } while (0)
; #define PG8_LDA(dst, b, h) do { _Pragma("unroll") for (int m = 0; m < 4; ++m) _Pragma("unroll") for (int k = 0; k < 2; ++k) dst[m][k] = *(const LAS bf16x8*)(lds + PG8_SA(b, h) + aoff + m * 2048 + k * 1024); } while (0)
; #define PG8_LDB(dst, b, h) do { _Pragma("unroll") for (int n = 0; n < 2; ++n) _Pragma("unroll") for (int k = 0; k < 2; ++k) dst[n][k] = *(const LAS bf16x8*)(lds + PG8_SB(b, h) + boff + n * 2048 + k * 1024); } while (0)
; #define PG8_MMA(ai, bj, At, Bt) do { __builtin_amdgcn_s_setprio(1); _Pragma("unroll") for (int m = 0; m < 4; ++m) _Pragma("unroll") for (int n = 0; n < 2; ++n) _Pragma("unroll") for (int k = 0; k < 2; ++k) \
;         acc[ai][bj][m][n] = __builtin_amdgcn_mfma_f32_16x16x32_bf16(Bt[n][k], At[m][k], acc[ai][bj][m][n], 0, 0, 0); __builtin_amdgcn_s_setprio(0); } while (0)
; #define PG8_WAIT_V(n) asm volatile("s_waitcnt vmcnt(" #n ")" ::: "memory")
; #define PG8_WAIT_L(n) asm volatile("s_waitcnt lgkmcnt(" #n ")" ::: "memory")
; #define PG8_BAR __builtin_amdgcn_s_barrier()
; #define PG8_SCHED __builtin_amdgcn_sched_barrier(0)
; template <int MODE>
; __device__ __forceinline__ void gemm_phase(LAS unsigned char* lds, const Params& p, int l, int single) {
;     ...
;             PG8_WAIT_V(6); PG8_BAR; PG8_MMA(1, 1, At, B1); PG8_BAR;
;             PG8_LDB(B0, 1, 0); PG8_SCHED; PG8_LDA(At, 1, 0); PG8_STAGE(PG8_SA(0, 1), a2 + hstep, voffA);
;             PG8_WAIT_L(8); PG8_BAR; PG8_WAIT_L(0); PG8_MMA(0, 0, At, B0); PG8_BAR; PG8_SCHED;
;             PG8_LDB(B1, 1, 1); PG8_STAGE(PG8_SB(1, 0), b3, voffB);
;             PG8_BAR; PG8_WAIT_L(0); PG8_MMA(0, 1, At, B1); PG8_BAR;
;             PG8_LDA(At, 1, 1); PG8_STAGE(PG8_SA(1, 0), a3, voffA);
;             PG8_BAR; PG8_WAIT_L(0); PG8_MMA(1, 0, At, B0); PG8_BAR; PG8_SCHED;
;             PG8_STAGE(PG8_SB(1, 1), b3 + hstep, voffB);
;             PG8_WAIT_V(6); PG8_BAR; PG8_MMA(1, 1, At, B1); PG8_BAR;
	s_add_u32 s96, s20, 0x80000
	s_addc_u32 s97, s21, 0
	s_add_i32 s22, s22, s23
	v_lshl_add_u64 v[156:157], s[96:97], 0, v[0:1]
	s_mov_b32 m0, s22
	s_nop 0
	global_load_lds_dwordx4 v[156:157], off
	v_lshl_add_u64 v[156:157], s[96:97], 0, v[130:131]
	s_add_i32 m0, s22, 0x2000
	s_nop 0
	global_load_lds_dwordx4 v[156:157], off
	s_waitcnt vmcnt(6)
	s_barrier
	s_setprio 1
	v_mfma_f32_16x16x32_bf16 v[54:57], v[216:219], v[176:179], v[54:57]
	v_mfma_f32_16x16x32_bf16 v[50:53], v[224:227], v[176:179], v[50:53]
	v_mfma_f32_16x16x32_bf16 v[38:41], v[216:219], v[184:187], v[38:41]
	v_mfma_f32_16x16x32_bf16 v[34:37], v[224:227], v[184:187], v[34:37]
	v_mfma_f32_16x16x32_bf16 v[22:25], v[216:219], v[192:195], v[22:25]
	v_mfma_f32_16x16x32_bf16 v[18:21], v[224:227], v[192:195], v[18:21]
	v_mfma_f32_16x16x32_bf16 v[6:9], v[216:219], v[208:211], v[6:9]
	v_mfma_f32_16x16x32_bf16 v[2:5], v[224:227], v[208:211], v[2:5]
	v_mfma_f32_16x16x32_bf16 v[54:57], v[220:223], v[180:183], v[54:57]
	v_mfma_f32_16x16x32_bf16 v[50:53], v[228:231], v[180:183], v[50:53]
	v_mfma_f32_16x16x32_bf16 v[38:41], v[220:223], v[188:191], v[38:41]
	v_mfma_f32_16x16x32_bf16 v[34:37], v[228:231], v[188:191], v[34:37]
	v_mfma_f32_16x16x32_bf16 v[22:25], v[220:223], v[196:199], v[22:25]
	v_mfma_f32_16x16x32_bf16 v[18:21], v[228:231], v[196:199], v[18:21]
	v_mfma_f32_16x16x32_bf16 v[6:9], v[220:223], v[212:215], v[6:9]
	v_mfma_f32_16x16x32_bf16 v[2:5], v[228:231], v[212:215], v[2:5]
	s_setprio 0
	s_add_i32 s22, 0, 0x18000
	v_add_u32_e32 v172, s22, v162
	s_barrier
	ds_read_b128 v[156:159], v172
	ds_read_b128 v[164:167], v172 offset:1024
	ds_read_b128 v[168:171], v172 offset:2048
	ds_read_b128 v[172:175], v172 offset:3072
	s_add_u32 s96, vcc_lo, 0x80000
	s_addc_u32 s97, vcc_hi, 0
	s_mov_b32 m0, s29
	v_lshl_add_u64 v[216:217], s[96:97], 0, v[146:147]
	ds_read_b128 v[176:179], v163 offset:32768
	ds_read_b128 v[180:183], v163 offset:33792
	ds_read_b128 v[184:187], v163 offset:34816
	ds_read_b128 v[188:191], v163 offset:35840
	ds_read_b128 v[192:195], v163 offset:36864
	ds_read_b128 v[196:199], v163 offset:37888
	ds_read_b128 v[208:211], v163 offset:38912
	ds_read_b128 v[212:215], v163 offset:39936
	global_load_lds_dwordx4 v[216:217], off
	v_lshl_add_u64 v[216:217], s[96:97], 0, v[132:133]
	s_mov_b32 m0, s76
	s_nop 0
	global_load_lds_dwordx4 v[216:217], off
	s_waitcnt lgkmcnt(8)
	s_barrier
	s_waitcnt lgkmcnt(0)
	s_setprio 1
	s_waitcnt lgkmcnt(0)
	v_mfma_f32_16x16x32_bf16 v[126:129], v[156:159], v[176:179], v[126:129]
	v_mfma_f32_16x16x32_bf16 v[122:125], v[168:171], v[176:179], v[122:125]
	v_mfma_f32_16x16x32_bf16 v[110:113], v[156:159], v[184:187], v[110:113]
	v_mfma_f32_16x16x32_bf16 v[106:109], v[168:171], v[184:187], v[106:109]
	v_mfma_f32_16x16x32_bf16 v[94:97], v[156:159], v[192:195], v[94:97]
	v_mfma_f32_16x16x32_bf16 v[90:93], v[168:171], v[192:195], v[90:93]
	v_mfma_f32_16x16x32_bf16 v[78:81], v[156:159], v[208:211], v[78:81]
	v_mfma_f32_16x16x32_bf16 v[74:77], v[168:171], v[208:211], v[74:77]
	v_mfma_f32_16x16x32_bf16 v[126:129], v[164:167], v[180:183], v[126:129]
	v_mfma_f32_16x16x32_bf16 v[122:125], v[172:175], v[180:183], v[122:125]
	v_mfma_f32_16x16x32_bf16 v[110:113], v[164:167], v[188:191], v[110:113]
	v_mfma_f32_16x16x32_bf16 v[106:109], v[172:175], v[188:191], v[106:109]
	v_mfma_f32_16x16x32_bf16 v[94:97], v[164:167], v[196:199], v[94:97]
	v_mfma_f32_16x16x32_bf16 v[90:93], v[172:175], v[196:199], v[90:93]
	v_mfma_f32_16x16x32_bf16 v[78:81], v[164:167], v[212:215], v[78:81]
	v_mfma_f32_16x16x32_bf16 v[74:77], v[172:175], v[212:215], v[74:77]
	s_setprio 0
	s_barrier
	s_add_i32 s96, 0, 0x1c000
	s_add_i32 s22, s22, s23
	v_add_u32_e32 v207, s96, v162
	v_lshl_add_u64 v[142:143], v[142:143], 0, s[94:95]
	s_mov_b32 m0, s22
	ds_read_b128 v[216:219], v207
	ds_read_b128 v[220:223], v207 offset:1024
	ds_read_b128 v[224:227], v207 offset:2048
	ds_read_b128 v[228:231], v207 offset:3072
	global_load_lds_dwordx4 v[142:143], off
	v_lshl_add_u64 v[142:143], v[160:161], 0, s[94:95]
	s_add_i32 m0, s22, 0x2000
	s_nop 0
	global_load_lds_dwordx4 v[142:143], off
	s_barrier
	s_waitcnt lgkmcnt(0)
	s_setprio 1
	s_waitcnt lgkmcnt(0)
	v_mfma_f32_16x16x32_bf16 v[118:121], v[216:219], v[176:179], v[118:121]
	v_mfma_f32_16x16x32_bf16 v[114:117], v[224:227], v[176:179], v[114:117]
	v_mfma_f32_16x16x32_bf16 v[102:105], v[216:219], v[184:187], v[102:105]
	v_mfma_f32_16x16x32_bf16 v[98:101], v[224:227], v[184:187], v[98:101]
	v_mfma_f32_16x16x32_bf16 v[86:89], v[216:219], v[192:195], v[86:89]
	v_mfma_f32_16x16x32_bf16 v[82:85], v[224:227], v[192:195], v[82:85]
	v_mfma_f32_16x16x32_bf16 v[70:73], v[216:219], v[208:211], v[70:73]
	v_mfma_f32_16x16x32_bf16 v[66:69], v[224:227], v[208:211], v[66:69]
	v_mfma_f32_16x16x32_bf16 v[118:121], v[220:223], v[180:183], v[118:121]
	v_mfma_f32_16x16x32_bf16 v[114:117], v[228:231], v[180:183], v[114:117]
	v_mfma_f32_16x16x32_bf16 v[102:105], v[220:223], v[188:191], v[102:105]
	v_mfma_f32_16x16x32_bf16 v[98:101], v[228:231], v[188:191], v[98:101]
	v_mfma_f32_16x16x32_bf16 v[86:89], v[220:223], v[196:199], v[86:89]
	v_mfma_f32_16x16x32_bf16 v[82:85], v[228:231], v[196:199], v[82:85]
	v_mfma_f32_16x16x32_bf16 v[70:73], v[220:223], v[212:215], v[70:73]
	v_mfma_f32_16x16x32_bf16 v[66:69], v[228:231], v[212:215], v[66:69]
	s_setprio 0
	s_mov_b32 m0, s90
	v_lshl_add_u64 v[142:143], v[232:233], 0, s[94:95]
	s_barrier
	ds_read_b128 v[176:179], v163 offset:49152
	ds_read_b128 v[180:183], v163 offset:50176
	ds_read_b128 v[184:187], v163 offset:51200
	ds_read_b128 v[188:191], v163 offset:52224
	ds_read_b128 v[192:195], v163 offset:53248
	ds_read_b128 v[196:199], v163 offset:54272
	ds_read_b128 v[208:211], v163 offset:55296
	ds_read_b128 v[212:215], v163 offset:56320
	global_load_lds_dwordx4 v[142:143], off
	v_lshl_add_u64 v[142:143], v[234:235], 0, s[94:95]
	s_mov_b32 m0, s6
	s_nop 0
	global_load_lds_dwordx4 v[142:143], off
	s_barrier
; __device__ __forceinline__ float bflo(unsigned w) { return __uint_as_float(w << 16); }
; __device__ __forceinline__ float bfhi(unsigned w) { return __uint_as_float(w & 0xffff0000u); }
; #define PG8_STAGE(bufoff, gbase, voff) do { _Pragma("unroll") for (int _i = 0; _i < 2; ++_i) \
;         __builtin_amdgcn_global_load_lds((const unsigned*)((const char*)(gbase) + (voff)[_i]), (LAS unsigned*)(lds + (bufoff) + ldsw + _i * 8192), 16, 0, 0); } while (0)
; #define PG8_LDA(dst, b, h) do { _Pragma("unroll") for (int m = 0; m < 4; ++m) _Pragma("unroll") for (int k = 0; k < 2; ++k) dst[m][k] = *(const LAS bf16x8*)(lds + PG8_SA(b, h) + aoff + m * 2048 + k * 1024); } while (0)
; #define PG8_WAIT_V(n) asm volatile("s_waitcnt vmcnt(" #n ")" ::: "memory")
; #define PG8_WAIT_L(n) asm volatile("s_waitcnt lgkmcnt(" #n ")" ::: "memory")
; #define PG8_BAR __builtin_amdgcn_s_barrier()
; #define PG8_SCHED __builtin_amdgcn_sched_barrier(0)
; template <int MODE>
; __device__ __forceinline__ void gemm_epilogue(const Params& p, int l, const f32x4 (&acc)[2][2][4][2], const Unit& u, int wr, int wc, int fr, int fq, const LAS float* rl, int pm0) {
;     ...
;         u16* xb = (u16*)(ws + WS_XB);
;         u64* ssn = (u64*)(ws + WS_SUMSQ) + (size_t)(l + 1) * T;
; #pragma unroll
;         for (int ai = 0; ai < 2; ++ai)
; #pragma unroll
;             for (int m = 0; m < 4; ++m) {
;                 const int tok = u.pm * 256 + 128 * ai + 64 * wr + 16 * m + fr;
;                 float part = 0.f;
; #pragma unroll
;                 for (int bj = 0; bj < 2; ++bj) {
;                     const size_t idx = (size_t)tok * 2048 + u.pn * 256 + 128 * bj + 32 * wc + 8 * fq;
;                     const u32x4 xw = *(const u32x4*)(xb + idx);
;                     f32x4 y0 = (f32x4){bflo(xw.x), bfhi(xw.x), bflo(xw.y), bfhi(xw.y)}, y1 = (f32x4){bflo(xw.z), bfhi(xw.z), bflo(xw.w), bfhi(xw.w)};
;                     y0 += acc[ai][bj][m][0]; y1 += acc[ai][bj][m][1];
; template <int MODE>
; __device__ __forceinline__ void gemm_phase(LAS unsigned char* lds, const Params& p, int l, int single) {
;     ...
;             PG8_LDA(At, 1, 1); PG8_STAGE(PG8_SA(1, 0), a3, voffA);
;             PG8_BAR; PG8_WAIT_L(0); PG8_MMA(1, 0, At, B0); PG8_BAR; PG8_SCHED;
;             PG8_STAGE(PG8_SB(1, 1), b3 + hstep, voffB);
;             PG8_WAIT_V(6); PG8_BAR; PG8_MMA(1, 1, At, B1); PG8_BAR;
	s_waitcnt lgkmcnt(0)
	s_setprio 1
	s_waitcnt lgkmcnt(0)
	v_mfma_f32_16x16x32_bf16 v[62:65], v[156:159], v[176:179], v[62:65]
	v_mfma_f32_16x16x32_bf16 v[58:61], v[168:171], v[176:179], v[58:61]
	v_mfma_f32_16x16x32_bf16 v[46:49], v[156:159], v[184:187], v[46:49]
	v_mfma_f32_16x16x32_bf16 v[42:45], v[168:171], v[184:187], v[42:45]
	v_mfma_f32_16x16x32_bf16 v[30:33], v[156:159], v[192:195], v[30:33]
	v_mfma_f32_16x16x32_bf16 v[26:29], v[168:171], v[192:195], v[26:29]
	v_mfma_f32_16x16x32_bf16 v[14:17], v[156:159], v[208:211], v[14:17]
	v_mfma_f32_16x16x32_bf16 v[10:13], v[168:171], v[208:211], v[10:13]
	v_mfma_f32_16x16x32_bf16 v[62:65], v[164:167], v[180:183], v[62:65]
	v_mfma_f32_16x16x32_bf16 v[58:61], v[172:175], v[180:183], v[58:61]
	v_mfma_f32_16x16x32_bf16 v[46:49], v[164:167], v[188:191], v[46:49]
	v_mfma_f32_16x16x32_bf16 v[42:45], v[172:175], v[188:191], v[42:45]
	v_mfma_f32_16x16x32_bf16 v[30:33], v[164:167], v[196:199], v[30:33]
	v_mfma_f32_16x16x32_bf16 v[26:29], v[172:175], v[196:199], v[26:29]
	v_mfma_f32_16x16x32_bf16 v[14:17], v[164:167], v[212:215], v[14:17]
	v_mfma_f32_16x16x32_bf16 v[10:13], v[172:175], v[212:215], v[10:13]
	s_setprio 0
	s_barrier
	s_add_u32 s20, s20, 0x80080
	s_addc_u32 s21, s21, 0
	s_add_i32 s22, s96, s23
	v_lshl_add_u64 v[142:143], s[20:21], 0, v[0:1]
	s_mov_b32 m0, s22
	s_nop 0
	global_load_lds_dwordx4 v[142:143], off
	v_lshl_add_u64 v[142:143], s[20:21], 0, v[130:131]
	s_add_i32 m0, s22, 0x2000
	s_nop 0
	global_load_lds_dwordx4 v[142:143], off
	s_waitcnt vmcnt(6)
	s_barrier
	s_setprio 1
	v_mfma_f32_16x16x32_bf16 v[54:57], v[216:219], v[176:179], v[54:57]
	v_mfma_f32_16x16x32_bf16 v[50:53], v[224:227], v[176:179], v[50:53]
	v_mfma_f32_16x16x32_bf16 v[38:41], v[216:219], v[184:187], v[38:41]
	v_mfma_f32_16x16x32_bf16 v[34:37], v[224:227], v[184:187], v[34:37]
	v_mfma_f32_16x16x32_bf16 v[22:25], v[216:219], v[192:195], v[22:25]
	v_mfma_f32_16x16x32_bf16 v[18:21], v[224:227], v[192:195], v[18:21]
	v_mfma_f32_16x16x32_bf16 v[6:9], v[216:219], v[208:211], v[6:9]
	v_mfma_f32_16x16x32_bf16 v[2:5], v[224:227], v[208:211], v[2:5]
	v_mfma_f32_16x16x32_bf16 v[54:57], v[220:223], v[180:183], v[54:57]
	v_mfma_f32_16x16x32_bf16 v[50:53], v[228:231], v[180:183], v[50:53]
	v_mfma_f32_16x16x32_bf16 v[38:41], v[220:223], v[188:191], v[38:41]
	v_mfma_f32_16x16x32_bf16 v[34:37], v[228:231], v[188:191], v[34:37]
	v_mfma_f32_16x16x32_bf16 v[22:25], v[220:223], v[196:199], v[22:25]
	v_mfma_f32_16x16x32_bf16 v[18:21], v[228:231], v[196:199], v[18:21]
	v_mfma_f32_16x16x32_bf16 v[6:9], v[220:223], v[212:215], v[6:9]
	v_mfma_f32_16x16x32_bf16 v[2:5], v[228:231], v[212:215], v[2:5]
	s_setprio 0
	s_add_i32 s85, s85, 2
	s_add_u32 s18, s18, 0x100
	s_addc_u32 s19, s19, 0
	s_add_u32 s33, s33, 0x100
	s_addc_u32 s84, s84, 0
	s_cmp_gt_u32 s85, 29
	s_barrier
	s_cbranch_scc0 .LBB0_840
	v_lshl_add_u32 v158, s10, 8, v149
	s_lshl_b32 s10, s2, 8
	s_ashr_i32 s11, s10, 31
	v_ashrrev_i32_e32 v159, 31, v158
	v_lshl_add_u64 v[156:157], s[10:11], 1, v[150:151]
	v_mov_b32_e32 v178, v158
	v_ashrrev_i32_e32 v179, 31, v178
	v_lshlrev_b64 v[178:179], 12, v[178:179]
	v_lshl_add_u64 v[178:179], v[156:157], 0, v[178:179]
	global_load_dwordx4 v[174:177], v[178:179], off
	global_load_dwordx4 v[178:181], v[178:179], off offset:256
	v_add_u32_e32 v186, 0x10, v158
	v_ashrrev_i32_e32 v187, 31, v186
	v_lshlrev_b64 v[186:187], 12, v[186:187]
	v_lshl_add_u64 v[186:187], v[156:157], 0, v[186:187]
	global_load_dwordx4 v[182:185], v[186:187], off
	global_load_dwordx4 v[186:189], v[186:187], off offset:256
	v_add_u32_e32 v194, 0x20, v158
	v_ashrrev_i32_e32 v195, 31, v194
	v_lshlrev_b64 v[194:195], 12, v[194:195]
	v_lshl_add_u64 v[194:195], v[156:157], 0, v[194:195]
	global_load_dwordx4 v[190:193], v[194:195], off
	global_load_dwordx4 v[194:197], v[194:195], off offset:256
	v_add_u32_e32 v212, 0x30, v158
	v_ashrrev_i32_e32 v213, 31, v212
	v_lshlrev_b64 v[212:213], 12, v[212:213]
	v_lshl_add_u64 v[212:213], v[156:157], 0, v[212:213]
	global_load_dwordx4 v[208:211], v[212:213], off
	global_load_dwordx4 v[212:215], v[212:213], off offset:256
	v_add_u32_e32 v220, 0x80, v158
	v_ashrrev_i32_e32 v221, 31, v220
	v_lshlrev_b64 v[220:221], 12, v[220:221]
	v_lshl_add_u64 v[220:221], v[156:157], 0, v[220:221]
	global_load_dwordx4 v[216:219], v[220:221], off
	global_load_dwordx4 v[220:223], v[220:221], off offset:256
	v_add_u32_e32 v228, 0x90, v158
	v_ashrrev_i32_e32 v229, 31, v228
	v_lshlrev_b64 v[228:229], 12, v[228:229]
	v_lshl_add_u64 v[228:229], v[156:157], 0, v[228:229]
	global_load_dwordx4 v[224:227], v[228:229], off
	global_load_dwordx4 v[228:231], v[228:229], off offset:256
	v_lshlrev_b64 v[142:143], 12, v[158:159]
	v_lshl_add_u64 v[168:169], v[156:157], 0, v[142:143]
	v_or_b32_e32 v160, s10, v148
	v_mov_b32_e32 v161, s11
	v_add_u32_e32 v172, 0x10800000, v142
	v_lshlrev_b64 v[160:161], 1, v[160:161]
	v_add_u32_e32 v161, v172, v160
	v_readlane_b32 s10, v252, 45
	v_readlane_b32 s11, v252, 46
	s_waitcnt vmcnt(11)
; __device__ __forceinline__ unsigned cvt_pk_bf16(float lo, float hi) { unsigned r; asm("v_cvt_pk_bf16_f32 %0, %1, %2" : "=v"(r) : "v"(lo), "v"(hi)); return r; }
; __device__ __forceinline__ float bflo(unsigned w) { return __uint_as_float(w << 16); }
; __device__ __forceinline__ float bfhi(unsigned w) { return __uint_as_float(w & 0xffff0000u); }
; #define WT_STORE16(ptr, val) __builtin_amdgcn_raw_buffer_store_b128((val), wsr, (int)((const char*)(ptr) - (const char*)ws), 0, 16)
; template <int MODE>
; __device__ __forceinline__ void gemm_epilogue(const Params& p, int l, const f32x4 (&acc)[2][2][4][2], const Unit& u, int wr, int wc, int fr, int fq, const LAS float* rl, int pm0) {
;     ...
;         u16* xb = (u16*)(ws + WS_XB);
;         u64* ssn = (u64*)(ws + WS_SUMSQ) + (size_t)(l + 1) * T;
; #pragma unroll
;         for (int ai = 0; ai < 2; ++ai)
; #pragma unroll
;             for (int m = 0; m < 4; ++m) {
;                 const int tok = u.pm * 256 + 128 * ai + 64 * wr + 16 * m + fr;
;                 float part = 0.f;
; #pragma unroll
;                 for (int bj = 0; bj < 2; ++bj) {
;                     const size_t idx = (size_t)tok * 2048 + u.pn * 256 + 128 * bj + 32 * wc + 8 * fq;
;                     const u32x4 xw = *(const u32x4*)(xb + idx);
;                     f32x4 y0 = (f32x4){bflo(xw.x), bfhi(xw.x), bflo(xw.y), bfhi(xw.y)}, y1 = (f32x4){bflo(xw.z), bfhi(xw.z), bflo(xw.w), bfhi(xw.w)};
;                     y0 += acc[ai][bj][m][0]; y1 += acc[ai][bj][m][1];
;                     part += y0[0] * y0[0] + y0[1] * y0[1] + y0[2] * y0[2] + y0[3] * y0[3] + y1[0] * y1[0] + y1[1] * y1[1] + y1[2] * y1[2] + y1[3] * y1[3];
;                     u32x4 w; w.x = cvt_pk_bf16(y0[0], y0[1]); w.y = cvt_pk_bf16(y0[2], y0[3]); w.z = cvt_pk_bf16(y1[0], y1[1]); w.w = cvt_pk_bf16(y1[2], y1[3]);
;                     WT_STORE16(xb + idx, w);
;                 }
;                 part += __shfl_xor(part, 16); part += __shfl_xor(part, 32);
;                 if (fq == 0) atomicAdd(ssn + tok, (u64)(part * SS_SCALE));
;             }
	v_mov_b32_e32 v164, v174
	v_mov_b32_e32 v165, v175
	v_mov_b32_e32 v166, v176
	v_mov_b32_e32 v167, v177
	v_lshlrev_b32_e32 v142, 16, v164
	v_and_b32_e32 v143, 0xffff0000, v164
	v_lshlrev_b32_e32 v164, 16, v165
	v_and_b32_e32 v165, 0xffff0000, v165
	v_lshlrev_b32_e32 v170, 16, v166
	v_and_b32_e32 v171, 0xffff0000, v166
	v_lshlrev_b32_e32 v166, 16, v167
	v_and_b32_e32 v167, 0xffff0000, v167
	v_pk_add_f32 v[128:129], v[128:129], v[164:165]
	v_pk_add_f32 v[142:143], v[126:127], v[142:143]
	v_pk_add_f32 v[164:165], v[124:125], v[166:167]
	v_pk_add_f32 v[166:167], v[122:123], v[170:171]
	v_cvt_pk_bf16_f32 v122, v142, v143
	v_cvt_pk_bf16_f32 v123, v128, v129
	v_cvt_pk_bf16_f32 v125, v164, v165
	s_nop 0
	v_cvt_pk_bf16_f32 v124, v166, v167
	buffer_store_dwordx4 v[122:125], v161, s[60:63], 0 offen
	v_xor_b32_e32 v161, 32, v205
	v_and_b32_e32 v123, 64, v205
	v_xor_b32_e32 v122, 16, v205
	v_add_u32_e32 v123, 64, v123
	v_cmp_lt_i32_e32 vcc, v122, v123
	s_nop 1
	v_cndmask_b32_e32 v122, v205, v122, vcc
	v_cmp_lt_i32_e32 vcc, v161, v123
	v_lshlrev_b32_e32 v122, 2, v122
	s_nop 0
	v_cndmask_b32_e32 v123, v205, v161, vcc
	v_mul_f32_e32 v161, v143, v143
	v_fmac_f32_e32 v161, v142, v142
	v_fmac_f32_e32 v161, v128, v128
	v_fmac_f32_e32 v161, v129, v129
	v_fmac_f32_e32 v161, v166, v166
	v_fmac_f32_e32 v161, v167, v167
	v_fmac_f32_e32 v161, v164, v164
	v_fmac_f32_e32 v161, v165, v165
	s_waitcnt vmcnt(11)
	v_mov_b32_e32 v124, v178
	v_mov_b32_e32 v125, v179
	v_mov_b32_e32 v126, v180
	v_mov_b32_e32 v127, v181
	v_add_u32_e32 v178, 0xa0, v158
	v_ashrrev_i32_e32 v179, 31, v178
	v_lshlrev_b64 v[178:179], 12, v[178:179]
	v_lshl_add_u64 v[178:179], v[156:157], 0, v[178:179]
	global_load_dwordx4 v[174:177], v[178:179], off
	global_load_dwordx4 v[178:181], v[178:179], off offset:256
	v_lshlrev_b32_e32 v128, 16, v124
	v_and_b32_e32 v129, 0xffff0000, v124
	v_lshlrev_b32_e32 v124, 16, v125
	v_and_b32_e32 v125, 0xffff0000, v125
	v_pk_add_f32 v[118:119], v[118:119], v[128:129]
	v_pk_add_f32 v[120:121], v[120:121], v[124:125]
	v_mul_f32_e32 v124, v119, v119
	v_fmac_f32_e32 v124, v118, v118
	v_lshlrev_b32_e32 v142, 16, v126
	v_and_b32_e32 v143, 0xffff0000, v126
	v_fmac_f32_e32 v124, v120, v120
	v_pk_add_f32 v[114:115], v[114:115], v[142:143]
	v_fmac_f32_e32 v124, v121, v121
	v_lshlrev_b32_e32 v126, 16, v127
	v_and_b32_e32 v127, 0xffff0000, v127
	v_fmac_f32_e32 v124, v114, v114
	v_pk_add_f32 v[116:117], v[116:117], v[126:127]
	v_fmac_f32_e32 v124, v115, v115
	v_fmac_f32_e32 v124, v116, v116
	v_fmac_f32_e32 v124, v117, v117
	v_add_f32_e32 v128, v161, v124
	ds_bpermute_b32 v129, v122, v128
	v_cvt_pk_bf16_f32 v124, v118, v119
	v_cvt_pk_bf16_f32 v127, v116, v117
	v_lshlrev_b32_e32 v117, 2, v123
	v_or_b32_e32 v116, 0x100, v160
	s_waitcnt lgkmcnt(0)
	v_add_f32_e32 v118, v128, v129
	ds_bpermute_b32 v119, v117, v118
	v_cvt_pk_bf16_f32 v126, v114, v115
	v_add_u32_e32 v114, v172, v116
	v_cvt_pk_bf16_f32 v125, v120, v121
	buffer_store_dwordx4 v[124:127], v114, s[60:63], 0 offen
	v_lshl_add_u64 v[114:115], v[158:159], 3, s[10:11]
	s_and_saveexec_b64 s[18:19], s[38:39]
	s_cbranch_execz .LBB0_843
	s_waitcnt lgkmcnt(0)
	v_add_f32_e32 v118, v118, v119
	v_mul_f32_e32 v118, 0x49800000, v118
	v_trunc_f32_e32 v118, v118
	v_mul_f32_e32 v119, 0x2f800000, v118
	v_floor_f32_e32 v119, v119
	v_fmac_f32_e32 v118, 0xcf800000, v119
	v_cvt_u32_f32_e32 v118, v118
	v_cvt_u32_f32_e32 v119, v119
	global_atomic_add_x2 v[114:115], v[118:119], off
.LBB0_843:
	s_or_b64 exec, exec, s[18:19]
	v_or_b32_e32 v118, 16, v158
	s_waitcnt lgkmcnt(0)
	v_ashrrev_i32_e32 v119, 31, v118
	v_lshlrev_b64 v[118:119], 12, v[118:119]
	v_lshl_add_u64 v[124:125], v[156:157], 0, v[118:119]
	v_add_u32_e32 v123, 0x10800000, v118
	s_waitcnt vmcnt(13)
	v_mov_b32_e32 v118, v182
	v_mov_b32_e32 v119, v183
	v_mov_b32_e32 v120, v184
	v_mov_b32_e32 v121, v185
	v_lshlrev_b32_e32 v126, 16, v118
	v_and_b32_e32 v127, 0xffff0000, v118
	v_lshlrev_b32_e32 v118, 16, v119
	v_and_b32_e32 v119, 0xffff0000, v119
	v_lshlrev_b32_e32 v128, 16, v120
	v_and_b32_e32 v129, 0xffff0000, v120
	v_lshlrev_b32_e32 v120, 16, v121
	v_and_b32_e32 v121, 0xffff0000, v121
	v_pk_add_f32 v[110:111], v[110:111], v[126:127]
	v_pk_add_f32 v[112:113], v[112:113], v[118:119]
	v_pk_add_f32 v[118:119], v[108:109], v[120:121]
	v_mul_f32_e32 v120, v111, v111
	v_fmac_f32_e32 v120, v110, v110
	v_fmac_f32_e32 v120, v112, v112
	v_pk_add_f32 v[108:109], v[106:107], v[128:129]
	v_fmac_f32_e32 v120, v113, v113
	v_fmac_f32_e32 v120, v108, v108
	v_cvt_pk_bf16_f32 v106, v110, v111
	v_add_u32_e32 v110, v123, v160
	v_fmac_f32_e32 v120, v109, v109
	v_cvt_pk_bf16_f32 v107, v112, v113
	v_cvt_pk_bf16_f32 v108, v108, v109
	v_cvt_pk_bf16_f32 v109, v118, v119
	buffer_store_dwordx4 v[106:109], v110, s[60:63], 0 offen
	v_fmac_f32_e32 v120, v118, v118
	v_fmac_f32_e32 v120, v119, v119
	s_waitcnt vmcnt(13)
	v_mov_b32_e32 v106, v186
	v_mov_b32_e32 v107, v187
	v_mov_b32_e32 v108, v188
	v_mov_b32_e32 v109, v189
	v_add_u32_e32 v186, 0xb0, v158
	v_ashrrev_i32_e32 v187, 31, v186
	v_lshlrev_b64 v[186:187], 12, v[186:187]
	v_lshl_add_u64 v[186:187], v[156:157], 0, v[186:187]
	global_load_dwordx4 v[182:185], v[186:187], off
	global_load_dwordx4 v[186:189], v[186:187], off offset:256
	v_lshlrev_b32_e32 v110, 16, v106
	v_and_b32_e32 v111, 0xffff0000, v106
	v_lshlrev_b32_e32 v106, 16, v107
	v_and_b32_e32 v107, 0xffff0000, v107
	v_lshlrev_b32_e32 v112, 16, v108
	v_and_b32_e32 v113, 0xffff0000, v108
	v_lshlrev_b32_e32 v108, 16, v109
	v_and_b32_e32 v109, 0xffff0000, v109
	v_pk_add_f32 v[102:103], v[102:103], v[110:111]
	v_pk_add_f32 v[104:105], v[104:105], v[106:107]
	v_pk_add_f32 v[106:107], v[100:101], v[108:109]
	v_pk_add_f32 v[100:101], v[98:99], v[112:113]
	v_mul_f32_e32 v98, v103, v103
	v_fmac_f32_e32 v98, v102, v102
	v_fmac_f32_e32 v98, v104, v104
	v_fmac_f32_e32 v98, v105, v105
	v_fmac_f32_e32 v98, v100, v100
	v_fmac_f32_e32 v98, v101, v101
	v_fmac_f32_e32 v98, v106, v106
	v_fmac_f32_e32 v98, v107, v107
	v_add_f32_e32 v108, v120, v98
	v_cvt_pk_bf16_f32 v98, v102, v103
	v_add_u32_e32 v102, v123, v116
	v_cvt_pk_bf16_f32 v99, v104, v105
	v_cvt_pk_bf16_f32 v100, v100, v101
	v_cvt_pk_bf16_f32 v101, v106, v107
	buffer_store_dwordx4 v[98:101], v102, s[60:63], 0 offen
	ds_bpermute_b32 v98, v122, v108
	s_waitcnt lgkmcnt(0)
	v_add_f32_e32 v98, v108, v98
	ds_bpermute_b32 v99, v117, v98
	s_and_saveexec_b64 s[18:19], s[38:39]
	s_movk_i32 s33, 0x100
	s_mov_b32 s13, s0
	s_cbranch_execz .LBB0_845
	s_waitcnt lgkmcnt(0)
	v_add_f32_e32 v98, v98, v99
	v_mul_f32_e32 v98, 0x49800000, v98
	v_trunc_f32_e32 v98, v98
	v_mul_f32_e32 v99, 0x2f800000, v98
	v_floor_f32_e32 v99, v99
	v_fmac_f32_e32 v98, 0xcf800000, v99
	v_cvt_u32_f32_e32 v98, v98
	v_cvt_u32_f32_e32 v99, v99
	global_atomic_add_x2 v[114:115], v[98:99], off offset:128
; __device__ __forceinline__ unsigned cvt_pk_bf16(float lo, float hi) { unsigned r; asm("v_cvt_pk_bf16_f32 %0, %1, %2" : "=v"(r) : "v"(lo), "v"(hi)); return r; }
; __device__ __forceinline__ float bflo(unsigned w) { return __uint_as_float(w << 16); }
; __device__ __forceinline__ float bfhi(unsigned w) { return __uint_as_float(w & 0xffff0000u); }
; #define WT_STORE16(ptr, val) __builtin_amdgcn_raw_buffer_store_b128((val), wsr, (int)((const char*)(ptr) - (const char*)ws), 0, 16)
; template <int MODE>
; __device__ __forceinline__ void gemm_epilogue(const Params& p, int l, const f32x4 (&acc)[2][2][4][2], const Unit& u, int wr, int wc, int fr, int fq, const LAS float* rl, int pm0) {
;     ...
;         u16* xb = (u16*)(ws + WS_XB);
;         u64* ssn = (u64*)(ws + WS_SUMSQ) + (size_t)(l + 1) * T;
; #pragma unroll
;         for (int ai = 0; ai < 2; ++ai)
; #pragma unroll
;             for (int m = 0; m < 4; ++m) {
;                 const int tok = u.pm * 256 + 128 * ai + 64 * wr + 16 * m + fr;
;                 float part = 0.f;
; #pragma unroll
;                 for (int bj = 0; bj < 2; ++bj) {
;                     const size_t idx = (size_t)tok * 2048 + u.pn * 256 + 128 * bj + 32 * wc + 8 * fq;
;                     const u32x4 xw = *(const u32x4*)(xb + idx);
;                     f32x4 y0 = (f32x4){bflo(xw.x), bfhi(xw.x), bflo(xw.y), bfhi(xw.y)}, y1 = (f32x4){bflo(xw.z), bfhi(xw.z), bflo(xw.w), bfhi(xw.w)};
;                     y0 += acc[ai][bj][m][0]; y1 += acc[ai][bj][m][1];
;                     part += y0[0] * y0[0] + y0[1] * y0[1] + y0[2] * y0[2] + y0[3] * y0[3] + y1[0] * y1[0] + y1[1] * y1[1] + y1[2] * y1[2] + y1[3] * y1[3];
;                     u32x4 w; w.x = cvt_pk_bf16(y0[0], y0[1]); w.y = cvt_pk_bf16(y0[2], y0[3]); w.z = cvt_pk_bf16(y1[0], y1[1]); w.w = cvt_pk_bf16(y1[2], y1[3]);
;                     WT_STORE16(xb + idx, w);
;                 }
;                 part += __shfl_xor(part, 16); part += __shfl_xor(part, 32);
;                 if (fq == 0) atomicAdd(ssn + tok, (u64)(part * SS_SCALE));
;             }
.LBB0_845:
	s_or_b64 exec, exec, s[18:19]
	v_or_b32_e32 v98, 32, v158
	s_waitcnt lgkmcnt(0)
	v_ashrrev_i32_e32 v99, 31, v98
	v_lshlrev_b64 v[98:99], 12, v[98:99]
	v_lshl_add_u64 v[102:103], v[156:157], 0, v[98:99]
	v_add_u32_e32 v108, 0x10800000, v98
	s_waitcnt vmcnt(15)
	v_mov_b32_e32 v98, v190
	v_mov_b32_e32 v99, v191
	v_mov_b32_e32 v100, v192
	v_mov_b32_e32 v101, v193
	v_lshlrev_b32_e32 v104, 16, v98
	v_and_b32_e32 v105, 0xffff0000, v98
	v_lshlrev_b32_e32 v98, 16, v99
	v_and_b32_e32 v99, 0xffff0000, v99
	v_lshlrev_b32_e32 v106, 16, v100
	v_and_b32_e32 v107, 0xffff0000, v100
	v_lshlrev_b32_e32 v100, 16, v101
	v_and_b32_e32 v101, 0xffff0000, v101
	v_pk_add_f32 v[94:95], v[94:95], v[104:105]
	v_pk_add_f32 v[96:97], v[96:97], v[98:99]
	v_pk_add_f32 v[98:99], v[92:93], v[100:101]
	v_mul_f32_e32 v100, v95, v95
	v_fmac_f32_e32 v100, v94, v94
	v_fmac_f32_e32 v100, v96, v96
	v_pk_add_f32 v[92:93], v[90:91], v[106:107]
	v_fmac_f32_e32 v100, v97, v97
	v_fmac_f32_e32 v100, v92, v92
	v_cvt_pk_bf16_f32 v90, v94, v95
	v_add_u32_e32 v94, v108, v160
	v_fmac_f32_e32 v100, v93, v93
	v_cvt_pk_bf16_f32 v91, v96, v97
	v_cvt_pk_bf16_f32 v92, v92, v93
	v_cvt_pk_bf16_f32 v93, v98, v99
	buffer_store_dwordx4 v[90:93], v94, s[60:63], 0 offen
	v_fmac_f32_e32 v100, v98, v98
	v_fmac_f32_e32 v100, v99, v99
	s_waitcnt vmcnt(15)
	v_mov_b32_e32 v90, v194
	v_mov_b32_e32 v91, v195
	v_mov_b32_e32 v92, v196
	v_mov_b32_e32 v93, v197
	v_lshlrev_b32_e32 v94, 16, v90
	v_and_b32_e32 v95, 0xffff0000, v90
	v_lshlrev_b32_e32 v90, 16, v91
	v_and_b32_e32 v91, 0xffff0000, v91
	v_lshlrev_b32_e32 v96, 16, v92
	v_and_b32_e32 v97, 0xffff0000, v92
	v_lshlrev_b32_e32 v92, 16, v93
	v_and_b32_e32 v93, 0xffff0000, v93
	v_pk_add_f32 v[86:87], v[86:87], v[94:95]
	v_pk_add_f32 v[88:89], v[88:89], v[90:91]
	v_pk_add_f32 v[90:91], v[84:85], v[92:93]
	v_pk_add_f32 v[84:85], v[82:83], v[96:97]
	v_mul_f32_e32 v82, v87, v87
	v_fmac_f32_e32 v82, v86, v86
	v_fmac_f32_e32 v82, v88, v88
	v_fmac_f32_e32 v82, v89, v89
	v_fmac_f32_e32 v82, v84, v84
	v_fmac_f32_e32 v82, v85, v85
	v_fmac_f32_e32 v82, v90, v90
	v_fmac_f32_e32 v82, v91, v91
	v_add_f32_e32 v92, v100, v82
	v_cvt_pk_bf16_f32 v82, v86, v87
	v_add_u32_e32 v86, v108, v116
	v_cvt_pk_bf16_f32 v83, v88, v89
	v_cvt_pk_bf16_f32 v84, v84, v85
	v_cvt_pk_bf16_f32 v85, v90, v91
	buffer_store_dwordx4 v[82:85], v86, s[60:63], 0 offen
	ds_bpermute_b32 v82, v122, v92
	s_waitcnt lgkmcnt(0)
	v_add_f32_e32 v82, v92, v82
	ds_bpermute_b32 v83, v117, v82
	s_and_saveexec_b64 s[18:19], s[38:39]
	s_cbranch_execz .LBB0_847
	s_waitcnt lgkmcnt(0)
	v_add_f32_e32 v82, v82, v83
	v_mul_f32_e32 v82, 0x49800000, v82
	v_trunc_f32_e32 v82, v82
	v_mul_f32_e32 v83, 0x2f800000, v82
	v_floor_f32_e32 v83, v83
	v_fmac_f32_e32 v82, 0xcf800000, v83
	v_cvt_u32_f32_e32 v82, v82
	v_cvt_u32_f32_e32 v83, v83
	global_atomic_add_x2 v[114:115], v[82:83], off offset:256
.LBB0_847:
	s_or_b64 exec, exec, s[18:19]
	v_or_b32_e32 v82, 48, v158
	s_waitcnt lgkmcnt(0)
	v_ashrrev_i32_e32 v83, 31, v82
	v_lshlrev_b64 v[82:83], 12, v[82:83]
	v_lshl_add_u64 v[86:87], v[156:157], 0, v[82:83]
	v_add_u32_e32 v92, 0x10800000, v82
	s_waitcnt vmcnt(15)
	v_mov_b32_e32 v82, v208
	v_mov_b32_e32 v83, v209
	v_mov_b32_e32 v84, v210
	v_mov_b32_e32 v85, v211
	v_lshlrev_b32_e32 v88, 16, v82
	v_and_b32_e32 v89, 0xffff0000, v82
	v_lshlrev_b32_e32 v82, 16, v83
	v_and_b32_e32 v83, 0xffff0000, v83
	v_lshlrev_b32_e32 v90, 16, v84
	v_and_b32_e32 v91, 0xffff0000, v84
	v_lshlrev_b32_e32 v84, 16, v85
	v_and_b32_e32 v85, 0xffff0000, v85
	v_pk_add_f32 v[78:79], v[78:79], v[88:89]
	v_pk_add_f32 v[80:81], v[80:81], v[82:83]
	v_pk_add_f32 v[82:83], v[76:77], v[84:85]
	v_mul_f32_e32 v84, v79, v79
	v_fmac_f32_e32 v84, v78, v78
	v_fmac_f32_e32 v84, v80, v80
	v_pk_add_f32 v[76:77], v[74:75], v[90:91]
	v_fmac_f32_e32 v84, v81, v81
	v_fmac_f32_e32 v84, v76, v76
	v_cvt_pk_bf16_f32 v74, v78, v79
	v_add_u32_e32 v78, v92, v160
	v_fmac_f32_e32 v84, v77, v77
	v_cvt_pk_bf16_f32 v75, v80, v81
	v_cvt_pk_bf16_f32 v76, v76, v77
	v_cvt_pk_bf16_f32 v77, v82, v83
	buffer_store_dwordx4 v[74:77], v78, s[60:63], 0 offen
	v_fmac_f32_e32 v84, v82, v82
	v_fmac_f32_e32 v84, v83, v83
	s_waitcnt vmcnt(15)
	v_mov_b32_e32 v74, v212
	v_mov_b32_e32 v75, v213
	v_mov_b32_e32 v76, v214
	v_mov_b32_e32 v77, v215
	v_lshlrev_b32_e32 v78, 16, v74
	v_and_b32_e32 v79, 0xffff0000, v74
	v_lshlrev_b32_e32 v74, 16, v75
	v_and_b32_e32 v75, 0xffff0000, v75
	v_lshlrev_b32_e32 v80, 16, v76
	v_and_b32_e32 v81, 0xffff0000, v76
	v_lshlrev_b32_e32 v76, 16, v77
	v_and_b32_e32 v77, 0xffff0000, v77
	v_pk_add_f32 v[70:71], v[70:71], v[78:79]
	v_pk_add_f32 v[72:73], v[72:73], v[74:75]
	v_pk_add_f32 v[74:75], v[68:69], v[76:77]
	v_pk_add_f32 v[68:69], v[66:67], v[80:81]
	v_mul_f32_e32 v66, v71, v71
	v_fmac_f32_e32 v66, v70, v70
	v_fmac_f32_e32 v66, v72, v72
	v_fmac_f32_e32 v66, v73, v73
	v_fmac_f32_e32 v66, v68, v68
	v_fmac_f32_e32 v66, v69, v69
	v_fmac_f32_e32 v66, v74, v74
	v_fmac_f32_e32 v66, v75, v75
	v_add_f32_e32 v76, v84, v66
	v_cvt_pk_bf16_f32 v66, v70, v71
	v_add_u32_e32 v70, v92, v116
	v_cvt_pk_bf16_f32 v67, v72, v73
	v_cvt_pk_bf16_f32 v68, v68, v69
	v_cvt_pk_bf16_f32 v69, v74, v75
	buffer_store_dwordx4 v[66:69], v70, s[60:63], 0 offen
	ds_bpermute_b32 v66, v122, v76
	s_waitcnt lgkmcnt(0)
	v_add_f32_e32 v66, v76, v66
	ds_bpermute_b32 v67, v117, v66
	s_and_saveexec_b64 s[18:19], s[38:39]
	v_readlane_b32 s84, v252, 43
	s_mov_b32 s96, 0x8400
	s_cbranch_execz .LBB0_849
	s_waitcnt lgkmcnt(0)
	v_add_f32_e32 v66, v66, v67
	v_mul_f32_e32 v66, 0x49800000, v66
	v_trunc_f32_e32 v66, v66
	v_mul_f32_e32 v67, 0x2f800000, v66
	v_floor_f32_e32 v67, v67
	v_fmac_f32_e32 v66, 0xcf800000, v67
	v_cvt_u32_f32_e32 v66, v66
	v_cvt_u32_f32_e32 v67, v67
	global_atomic_add_x2 v[114:115], v[66:67], off offset:384
; __device__ __forceinline__ unsigned cvt_pk_bf16(float lo, float hi) { unsigned r; asm("v_cvt_pk_bf16_f32 %0, %1, %2" : "=v"(r) : "v"(lo), "v"(hi)); return r; }
; __device__ __forceinline__ float bflo(unsigned w) { return __uint_as_float(w << 16); }
; __device__ __forceinline__ float bfhi(unsigned w) { return __uint_as_float(w & 0xffff0000u); }
; #define WT_STORE16(ptr, val) __builtin_amdgcn_raw_buffer_store_b128((val), wsr, (int)((const char*)(ptr) - (const char*)ws), 0, 16)
; template <int MODE>
; __device__ __forceinline__ void gemm_epilogue(const Params& p, int l, const f32x4 (&acc)[2][2][4][2], const Unit& u, int wr, int wc, int fr, int fq, const LAS float* rl, int pm0) {
;     ...
;         u16* xb = (u16*)(ws + WS_XB);
;         u64* ssn = (u64*)(ws + WS_SUMSQ) + (size_t)(l + 1) * T;
; #pragma unroll
;         for (int ai = 0; ai < 2; ++ai)
; #pragma unroll
;             for (int m = 0; m < 4; ++m) {
;                 const int tok = u.pm * 256 + 128 * ai + 64 * wr + 16 * m + fr;
;                 float part = 0.f;
; #pragma unroll
;                 for (int bj = 0; bj < 2; ++bj) {
;                     const size_t idx = (size_t)tok * 2048 + u.pn * 256 + 128 * bj + 32 * wc + 8 * fq;
;                     const u32x4 xw = *(const u32x4*)(xb + idx);
;                     f32x4 y0 = (f32x4){bflo(xw.x), bfhi(xw.x), bflo(xw.y), bfhi(xw.y)}, y1 = (f32x4){bflo(xw.z), bfhi(xw.z), bflo(xw.w), bfhi(xw.w)};
;                     y0 += acc[ai][bj][m][0]; y1 += acc[ai][bj][m][1];
;                     part += y0[0] * y0[0] + y0[1] * y0[1] + y0[2] * y0[2] + y0[3] * y0[3] + y1[0] * y1[0] + y1[1] * y1[1] + y1[2] * y1[2] + y1[3] * y1[3];
;                     u32x4 w; w.x = cvt_pk_bf16(y0[0], y0[1]); w.y = cvt_pk_bf16(y0[2], y0[3]); w.z = cvt_pk_bf16(y1[0], y1[1]); w.w = cvt_pk_bf16(y1[2], y1[3]);
;                     WT_STORE16(xb + idx, w);
;                 }
;                 part += __shfl_xor(part, 16); part += __shfl_xor(part, 32);
;                 if (fq == 0) atomicAdd(ssn + tok, (u64)(part * SS_SCALE));
;             }
.LBB0_849:
	s_or_b64 exec, exec, s[18:19]
	v_add_u32_e32 v66, 0x80, v158
	s_waitcnt lgkmcnt(0)
	v_ashrrev_i32_e32 v67, 31, v66
	v_lshlrev_b64 v[66:67], 12, v[66:67]
	v_lshl_add_u64 v[70:71], v[156:157], 0, v[66:67]
	v_add_u32_e32 v76, 0x10800000, v66
	s_waitcnt vmcnt(15)
	v_mov_b32_e32 v66, v216
	v_mov_b32_e32 v67, v217
	v_mov_b32_e32 v68, v218
	v_mov_b32_e32 v69, v219
	v_lshlrev_b32_e32 v72, 16, v66
	v_and_b32_e32 v73, 0xffff0000, v66
	v_lshlrev_b32_e32 v66, 16, v67
	v_and_b32_e32 v67, 0xffff0000, v67
	v_lshlrev_b32_e32 v74, 16, v68
	v_and_b32_e32 v75, 0xffff0000, v68
	v_lshlrev_b32_e32 v68, 16, v69
	v_and_b32_e32 v69, 0xffff0000, v69
	v_pk_add_f32 v[62:63], v[62:63], v[72:73]
	v_pk_add_f32 v[64:65], v[64:65], v[66:67]
	v_pk_add_f32 v[66:67], v[60:61], v[68:69]
	v_mul_f32_e32 v68, v63, v63
	v_fmac_f32_e32 v68, v62, v62
	v_fmac_f32_e32 v68, v64, v64
	v_pk_add_f32 v[60:61], v[58:59], v[74:75]
	v_fmac_f32_e32 v68, v65, v65
	v_fmac_f32_e32 v68, v60, v60
	v_cvt_pk_bf16_f32 v58, v62, v63
	v_add_u32_e32 v62, v76, v160
	v_fmac_f32_e32 v68, v61, v61
	v_cvt_pk_bf16_f32 v59, v64, v65
	v_cvt_pk_bf16_f32 v60, v60, v61
	v_cvt_pk_bf16_f32 v61, v66, v67
	buffer_store_dwordx4 v[58:61], v62, s[60:63], 0 offen
	v_fmac_f32_e32 v68, v66, v66
	v_fmac_f32_e32 v68, v67, v67
	s_waitcnt vmcnt(15)
	v_mov_b32_e32 v58, v220
	v_mov_b32_e32 v59, v221
	v_mov_b32_e32 v60, v222
	v_mov_b32_e32 v61, v223
	v_lshlrev_b32_e32 v62, 16, v58
	v_and_b32_e32 v63, 0xffff0000, v58
	v_lshlrev_b32_e32 v58, 16, v59
	v_and_b32_e32 v59, 0xffff0000, v59
	v_lshlrev_b32_e32 v64, 16, v60
	v_and_b32_e32 v65, 0xffff0000, v60
	v_lshlrev_b32_e32 v60, 16, v61
	v_and_b32_e32 v61, 0xffff0000, v61
	v_pk_add_f32 v[54:55], v[54:55], v[62:63]
	v_pk_add_f32 v[56:57], v[56:57], v[58:59]
	v_pk_add_f32 v[58:59], v[52:53], v[60:61]
	v_pk_add_f32 v[52:53], v[50:51], v[64:65]
	v_mul_f32_e32 v50, v55, v55
	v_fmac_f32_e32 v50, v54, v54
	v_fmac_f32_e32 v50, v56, v56
	v_fmac_f32_e32 v50, v57, v57
	v_fmac_f32_e32 v50, v52, v52
	v_fmac_f32_e32 v50, v53, v53
	v_fmac_f32_e32 v50, v58, v58
	v_fmac_f32_e32 v50, v59, v59
	v_add_f32_e32 v60, v68, v50
	v_cvt_pk_bf16_f32 v50, v54, v55
	v_add_u32_e32 v54, v76, v116
	v_cvt_pk_bf16_f32 v51, v56, v57
	v_cvt_pk_bf16_f32 v52, v52, v53
	v_cvt_pk_bf16_f32 v53, v58, v59
	buffer_store_dwordx4 v[50:53], v54, s[60:63], 0 offen
	ds_bpermute_b32 v50, v122, v60
	s_waitcnt lgkmcnt(0)
	v_add_f32_e32 v50, v60, v50
	ds_bpermute_b32 v51, v117, v50
	s_and_saveexec_b64 s[18:19], s[38:39]
	s_cbranch_execz .LBB0_851
	s_waitcnt lgkmcnt(0)
	v_add_f32_e32 v50, v50, v51
	v_mul_f32_e32 v50, 0x49800000, v50
	v_trunc_f32_e32 v50, v50
	v_mul_f32_e32 v51, 0x2f800000, v50
	v_floor_f32_e32 v51, v51
	v_fmac_f32_e32 v50, 0xcf800000, v51
	v_cvt_u32_f32_e32 v50, v50
	v_cvt_u32_f32_e32 v51, v51
	global_atomic_add_x2 v[114:115], v[50:51], off offset:1024
.LBB0_851:
	s_or_b64 exec, exec, s[18:19]
	v_add_u32_e32 v50, 0x90, v158
	s_waitcnt lgkmcnt(0)
	v_ashrrev_i32_e32 v51, 31, v50
	v_lshlrev_b64 v[50:51], 12, v[50:51]
	v_lshl_add_u64 v[54:55], v[156:157], 0, v[50:51]
	v_add_u32_e32 v60, 0x10800000, v50
	s_waitcnt vmcnt(15)
	v_mov_b32_e32 v50, v224
	v_mov_b32_e32 v51, v225
	v_mov_b32_e32 v52, v226
	v_mov_b32_e32 v53, v227
	v_lshlrev_b32_e32 v56, 16, v50
	v_and_b32_e32 v57, 0xffff0000, v50
	v_lshlrev_b32_e32 v50, 16, v51
	v_and_b32_e32 v51, 0xffff0000, v51
	v_lshlrev_b32_e32 v58, 16, v52
	v_and_b32_e32 v59, 0xffff0000, v52
	v_lshlrev_b32_e32 v52, 16, v53
	v_and_b32_e32 v53, 0xffff0000, v53
	v_pk_add_f32 v[46:47], v[46:47], v[56:57]
	v_pk_add_f32 v[48:49], v[48:49], v[50:51]
	v_pk_add_f32 v[50:51], v[44:45], v[52:53]
	v_mul_f32_e32 v52, v47, v47
	v_fmac_f32_e32 v52, v46, v46
	v_fmac_f32_e32 v52, v48, v48
	v_pk_add_f32 v[44:45], v[42:43], v[58:59]
	v_fmac_f32_e32 v52, v49, v49
	v_fmac_f32_e32 v52, v44, v44
	v_cvt_pk_bf16_f32 v42, v46, v47
	v_add_u32_e32 v46, v60, v160
	v_fmac_f32_e32 v52, v45, v45
	v_cvt_pk_bf16_f32 v43, v48, v49
	v_cvt_pk_bf16_f32 v44, v44, v45
	v_cvt_pk_bf16_f32 v45, v50, v51
	buffer_store_dwordx4 v[42:45], v46, s[60:63], 0 offen
	v_fmac_f32_e32 v52, v50, v50
	v_fmac_f32_e32 v52, v51, v51
	s_waitcnt vmcnt(15)
	v_mov_b32_e32 v42, v228
	v_mov_b32_e32 v43, v229
	v_mov_b32_e32 v44, v230
	v_mov_b32_e32 v45, v231
	v_lshlrev_b32_e32 v46, 16, v42
	v_and_b32_e32 v47, 0xffff0000, v42
	v_lshlrev_b32_e32 v42, 16, v43
	v_and_b32_e32 v43, 0xffff0000, v43
	v_lshlrev_b32_e32 v48, 16, v44
	v_and_b32_e32 v49, 0xffff0000, v44
	v_lshlrev_b32_e32 v44, 16, v45
	v_and_b32_e32 v45, 0xffff0000, v45
	v_pk_add_f32 v[38:39], v[38:39], v[46:47]
	v_pk_add_f32 v[40:41], v[40:41], v[42:43]
	v_pk_add_f32 v[42:43], v[36:37], v[44:45]
	v_pk_add_f32 v[36:37], v[34:35], v[48:49]
	v_mul_f32_e32 v34, v39, v39
	v_fmac_f32_e32 v34, v38, v38
	v_fmac_f32_e32 v34, v40, v40
	v_fmac_f32_e32 v34, v41, v41
	v_fmac_f32_e32 v34, v36, v36
	v_fmac_f32_e32 v34, v37, v37
	v_fmac_f32_e32 v34, v42, v42
	v_fmac_f32_e32 v34, v43, v43
	v_add_f32_e32 v44, v52, v34
	v_cvt_pk_bf16_f32 v34, v38, v39
	v_add_u32_e32 v38, v60, v116
	v_cvt_pk_bf16_f32 v35, v40, v41
	v_cvt_pk_bf16_f32 v36, v36, v37
	v_cvt_pk_bf16_f32 v37, v42, v43
	buffer_store_dwordx4 v[34:37], v38, s[60:63], 0 offen
	ds_bpermute_b32 v34, v122, v44
	s_waitcnt lgkmcnt(0)
	v_add_f32_e32 v34, v44, v34
	ds_bpermute_b32 v35, v117, v34
	s_and_saveexec_b64 s[18:19], s[38:39]
	s_cbranch_execz .LBB0_853
	s_waitcnt lgkmcnt(0)
	v_add_f32_e32 v34, v34, v35
	v_mul_f32_e32 v34, 0x49800000, v34
	v_trunc_f32_e32 v34, v34
	v_mul_f32_e32 v35, 0x2f800000, v34
	v_floor_f32_e32 v35, v35
	v_fmac_f32_e32 v34, 0xcf800000, v35
	v_cvt_u32_f32_e32 v34, v34
	v_cvt_u32_f32_e32 v35, v35
	global_atomic_add_x2 v[114:115], v[34:35], off offset:1152
; __device__ __forceinline__ unsigned cvt_pk_bf16(float lo, float hi) { unsigned r; asm("v_cvt_pk_bf16_f32 %0, %1, %2" : "=v"(r) : "v"(lo), "v"(hi)); return r; }
; __device__ __forceinline__ float bflo(unsigned w) { return __uint_as_float(w << 16); }
; __device__ __forceinline__ float bfhi(unsigned w) { return __uint_as_float(w & 0xffff0000u); }
; #define WT_STORE16(ptr, val) __builtin_amdgcn_raw_buffer_store_b128((val), wsr, (int)((const char*)(ptr) - (const char*)ws), 0, 16)
; template <int MODE>
; __device__ __forceinline__ void gemm_epilogue(const Params& p, int l, const f32x4 (&acc)[2][2][4][2], const Unit& u, int wr, int wc, int fr, int fq, const LAS float* rl, int pm0) {
;     ...
;         u16* xb = (u16*)(ws + WS_XB);
;         u64* ssn = (u64*)(ws + WS_SUMSQ) + (size_t)(l + 1) * T;
; #pragma unroll
;         for (int ai = 0; ai < 2; ++ai)
; #pragma unroll
;             for (int m = 0; m < 4; ++m) {
;                 const int tok = u.pm * 256 + 128 * ai + 64 * wr + 16 * m + fr;
;                 float part = 0.f;
; #pragma unroll
;                 for (int bj = 0; bj < 2; ++bj) {
;                     const size_t idx = (size_t)tok * 2048 + u.pn * 256 + 128 * bj + 32 * wc + 8 * fq;
;                     const u32x4 xw = *(const u32x4*)(xb + idx);
;                     f32x4 y0 = (f32x4){bflo(xw.x), bfhi(xw.x), bflo(xw.y), bfhi(xw.y)}, y1 = (f32x4){bflo(xw.z), bfhi(xw.z), bflo(xw.w), bfhi(xw.w)};
;                     y0 += acc[ai][bj][m][0]; y1 += acc[ai][bj][m][1];
;                     part += y0[0] * y0[0] + y0[1] * y0[1] + y0[2] * y0[2] + y0[3] * y0[3] + y1[0] * y1[0] + y1[1] * y1[1] + y1[2] * y1[2] + y1[3] * y1[3];
;                     u32x4 w; w.x = cvt_pk_bf16(y0[0], y0[1]); w.y = cvt_pk_bf16(y0[2], y0[3]); w.z = cvt_pk_bf16(y1[0], y1[1]); w.w = cvt_pk_bf16(y1[2], y1[3]);
;                     WT_STORE16(xb + idx, w);
;                 }
;                 part += __shfl_xor(part, 16); part += __shfl_xor(part, 32);
;                 if (fq == 0) atomicAdd(ssn + tok, (u64)(part * SS_SCALE));
;             }
.LBB0_853:
	s_or_b64 exec, exec, s[18:19]
	v_add_u32_e32 v34, 0xa0, v158
	s_waitcnt lgkmcnt(0)
	v_ashrrev_i32_e32 v35, 31, v34
	v_lshlrev_b64 v[34:35], 12, v[34:35]
	v_lshl_add_u64 v[38:39], v[156:157], 0, v[34:35]
	v_add_u32_e32 v44, 0x10800000, v34
	s_waitcnt vmcnt(14)
	v_mov_b32_e32 v34, v174
	v_mov_b32_e32 v35, v175
	v_mov_b32_e32 v36, v176
	v_mov_b32_e32 v37, v177
	v_lshlrev_b32_e32 v40, 16, v34
	v_and_b32_e32 v41, 0xffff0000, v34
	v_lshlrev_b32_e32 v34, 16, v35
	v_and_b32_e32 v35, 0xffff0000, v35
	v_lshlrev_b32_e32 v42, 16, v36
	v_and_b32_e32 v43, 0xffff0000, v36
	v_lshlrev_b32_e32 v36, 16, v37
	v_and_b32_e32 v37, 0xffff0000, v37
	v_pk_add_f32 v[30:31], v[30:31], v[40:41]
	v_pk_add_f32 v[32:33], v[32:33], v[34:35]
	v_pk_add_f32 v[34:35], v[28:29], v[36:37]
	v_mul_f32_e32 v36, v31, v31
	v_fmac_f32_e32 v36, v30, v30
	v_fmac_f32_e32 v36, v32, v32
	v_pk_add_f32 v[28:29], v[26:27], v[42:43]
	v_fmac_f32_e32 v36, v33, v33
	v_fmac_f32_e32 v36, v28, v28
	v_cvt_pk_bf16_f32 v26, v30, v31
	v_add_u32_e32 v30, v44, v160
	v_fmac_f32_e32 v36, v29, v29
	v_cvt_pk_bf16_f32 v27, v32, v33
	v_cvt_pk_bf16_f32 v28, v28, v29
	v_cvt_pk_bf16_f32 v29, v34, v35
	buffer_store_dwordx4 v[26:29], v30, s[60:63], 0 offen
	v_fmac_f32_e32 v36, v34, v34
	v_fmac_f32_e32 v36, v35, v35
	s_waitcnt vmcnt(14)
	v_mov_b32_e32 v26, v178
	v_mov_b32_e32 v27, v179
	v_mov_b32_e32 v28, v180
	v_mov_b32_e32 v29, v181
	v_lshlrev_b32_e32 v30, 16, v26
	v_and_b32_e32 v31, 0xffff0000, v26
	v_lshlrev_b32_e32 v26, 16, v27
	v_and_b32_e32 v27, 0xffff0000, v27
	v_lshlrev_b32_e32 v32, 16, v28
	v_and_b32_e32 v33, 0xffff0000, v28
	v_lshlrev_b32_e32 v28, 16, v29
	v_and_b32_e32 v29, 0xffff0000, v29
	v_pk_add_f32 v[22:23], v[22:23], v[30:31]
	v_pk_add_f32 v[24:25], v[24:25], v[26:27]
	v_pk_add_f32 v[26:27], v[20:21], v[28:29]
	v_pk_add_f32 v[20:21], v[18:19], v[32:33]
	v_mul_f32_e32 v18, v23, v23
	v_fmac_f32_e32 v18, v22, v22
	v_fmac_f32_e32 v18, v24, v24
	v_fmac_f32_e32 v18, v25, v25
	v_fmac_f32_e32 v18, v20, v20
	v_fmac_f32_e32 v18, v21, v21
	v_fmac_f32_e32 v18, v26, v26
	v_fmac_f32_e32 v18, v27, v27
	v_add_f32_e32 v28, v36, v18
	v_cvt_pk_bf16_f32 v18, v22, v23
	v_add_u32_e32 v22, v44, v116
	v_cvt_pk_bf16_f32 v19, v24, v25
	v_cvt_pk_bf16_f32 v20, v20, v21
	v_cvt_pk_bf16_f32 v21, v26, v27
	buffer_store_dwordx4 v[18:21], v22, s[60:63], 0 offen
	ds_bpermute_b32 v18, v122, v28
	s_waitcnt lgkmcnt(0)
	v_add_f32_e32 v18, v28, v18
	ds_bpermute_b32 v19, v117, v18
	s_and_saveexec_b64 s[18:19], s[38:39]
	s_cbranch_execz .LBB0_855
	s_waitcnt lgkmcnt(0)
	v_add_f32_e32 v18, v18, v19
	v_mul_f32_e32 v18, 0x49800000, v18
	v_trunc_f32_e32 v18, v18
	v_mul_f32_e32 v19, 0x2f800000, v18
	v_floor_f32_e32 v19, v19
	v_fmac_f32_e32 v18, 0xcf800000, v19
	v_cvt_u32_f32_e32 v18, v18
	v_cvt_u32_f32_e32 v19, v19
	global_atomic_add_x2 v[114:115], v[18:19], off offset:1280
.LBB0_855:
	s_or_b64 exec, exec, s[18:19]
	v_add_u32_e32 v18, 0xb0, v158
	s_waitcnt lgkmcnt(0)
	v_ashrrev_i32_e32 v19, 31, v18
	v_lshlrev_b64 v[22:23], 12, v[18:19]
	v_lshl_add_u64 v[24:25], v[156:157], 0, v[22:23]
	v_add_u32_e32 v28, 0x10800000, v22
	v_add_u32_e32 v29, v28, v160
	s_waitcnt vmcnt(12)
	v_mov_b32_e32 v18, v182
	v_mov_b32_e32 v19, v183
	v_mov_b32_e32 v20, v184
	v_mov_b32_e32 v21, v185
	v_lshlrev_b32_e32 v22, 16, v18
	v_and_b32_e32 v23, 0xffff0000, v18
	v_lshlrev_b32_e32 v18, 16, v19
	v_and_b32_e32 v19, 0xffff0000, v19
	v_lshlrev_b32_e32 v26, 16, v20
	v_and_b32_e32 v27, 0xffff0000, v20
	v_lshlrev_b32_e32 v20, 16, v21
	v_and_b32_e32 v21, 0xffff0000, v21
	v_pk_add_f32 v[16:17], v[16:17], v[18:19]
	v_pk_add_f32 v[14:15], v[14:15], v[22:23]
	v_pk_add_f32 v[18:19], v[12:13], v[20:21]
	v_pk_add_f32 v[20:21], v[10:11], v[26:27]
	v_cvt_pk_bf16_f32 v10, v14, v15
	v_cvt_pk_bf16_f32 v11, v16, v17
	v_cvt_pk_bf16_f32 v13, v18, v19
	v_mul_f32_e32 v22, v15, v15
	v_cvt_pk_bf16_f32 v12, v20, v21
	buffer_store_dwordx4 v[10:13], v29, s[60:63], 0 offen
	v_fmac_f32_e32 v22, v14, v14
	v_fmac_f32_e32 v22, v16, v16
	v_fmac_f32_e32 v22, v17, v17
	v_fmac_f32_e32 v22, v20, v20
	v_fmac_f32_e32 v22, v21, v21
	v_fmac_f32_e32 v22, v18, v18
	v_fmac_f32_e32 v22, v19, v19
	s_waitcnt vmcnt(12)
	v_mov_b32_e32 v10, v186
	v_mov_b32_e32 v11, v187
	v_mov_b32_e32 v12, v188
	v_mov_b32_e32 v13, v189
	v_lshlrev_b32_e32 v14, 16, v10
	v_and_b32_e32 v15, 0xffff0000, v10
	v_lshlrev_b32_e32 v10, 16, v11
	v_and_b32_e32 v11, 0xffff0000, v11
	v_lshlrev_b32_e32 v16, 16, v12
	v_and_b32_e32 v17, 0xffff0000, v12
	v_lshlrev_b32_e32 v12, 16, v13
	v_and_b32_e32 v13, 0xffff0000, v13
	v_pk_add_f32 v[6:7], v[6:7], v[14:15]
	v_pk_add_f32 v[8:9], v[8:9], v[10:11]
	v_pk_add_f32 v[10:11], v[4:5], v[12:13]
	v_pk_add_f32 v[12:13], v[2:3], v[16:17]
	v_mul_f32_e32 v2, v7, v7
	v_fmac_f32_e32 v2, v6, v6
	v_fmac_f32_e32 v2, v8, v8
	v_fmac_f32_e32 v2, v9, v9
	v_fmac_f32_e32 v2, v12, v12
	v_fmac_f32_e32 v2, v13, v13
	v_fmac_f32_e32 v2, v10, v10
	v_fmac_f32_e32 v2, v11, v11
	v_add_f32_e32 v2, v22, v2
	ds_bpermute_b32 v3, v122, v2
	v_cvt_pk_bf16_f32 v5, v8, v9
	v_add_u32_e32 v8, v28, v116
	v_cvt_pk_bf16_f32 v4, v6, v7
	v_cvt_pk_bf16_f32 v6, v12, v13
	s_waitcnt lgkmcnt(0)
	v_add_f32_e32 v2, v2, v3
	ds_bpermute_b32 v3, v117, v2
	v_cvt_pk_bf16_f32 v7, v10, v11
	buffer_store_dwordx4 v[4:7], v8, s[60:63], 0 offen
	s_and_saveexec_b64 s[18:19], s[38:39]
	s_cbranch_execz .LBB0_836
	s_waitcnt lgkmcnt(0)
	v_add_f32_e32 v2, v2, v3
	v_mul_f32_e32 v2, 0x49800000, v2
	v_trunc_f32_e32 v2, v2
	v_mul_f32_e32 v3, 0x2f800000, v2
	v_floor_f32_e32 v3, v3
	v_fmac_f32_e32 v2, 0xcf800000, v3
	v_cvt_u32_f32_e32 v2, v2
	v_cvt_u32_f32_e32 v3, v3
	global_atomic_add_x2 v[114:115], v[2:3], off offset:1408
	s_branch .LBB0_836
